# phase-6 row pass rewritten by hand (three 2-row stages in flight, DPP reductions); dt_bias of the softplus tile loaded once per tile
# speedup vs baseline: 1.0179x; 1.0005x over previous
.LBB0_93:
	s_andn2_b64 vcc, exec, s[0:1]
	s_cbranch_vccnz .LBB0_141
	s_cmp_gt_i32 s94, 5
	s_mov_b64 s[0:1], -1
	s_cbranch_scc0 .LBB0_113
	v_readlane_b32 s0, v254, 59
	v_readlane_b32 s1, v254, 60
	s_nop 3
	s_load_dword s2, s[0:1], 0x0
	s_waitcnt lgkmcnt(0)
	s_cmpk_lg_u32 s2, 0x100
	s_cbranch_scc1 .Lrow6_generic
	v_readlane_b32 s0, v254, 58
	v_readfirstlane_b32 s1, v197
	v_readlane_b32 s4, v254, 42
	v_readlane_b32 s5, v254, 43
	v_readlane_b32 s6, v254, 44
	v_readlane_b32 s7, v254, 45
	v_readlane_b32 s8, v253, 4
	v_readlane_b32 s9, v253, 5
	v_readlane_b32 s2, v253, 6
	v_readlane_b32 s3, v253, 7
	v_and_b32_e32 v244, 63, v197
	v_lshlrev_b32_e32 v245, 3, v244
	v_lshlrev_b32_e32 v244, 4, v244
	s_lshr_b32 s1, s1, 6
	s_lshl_b32 s0, s0, 3
	s_add_i32 s1, s0, s1
	s_lshl_b32 s0, s1, 11
	s_add_u32 s10, s92, 0xf000000
	s_addc_u32 s11, s93, 0
	s_add_u32 s10, s10, s0
	s_addc_u32 s11, s11, 0
	s_add_u32 s14, s92, 0x17400000
	s_addc_u32 s15, s93, 0
	s_add_u32 s14, s14, s0
	s_addc_u32 s15, s15, 0
	s_lshl_b32 s0, s1, 12
	s_add_u32 s12, s4, s0
	s_addc_u32 s13, s5, 0
	s_add_u32 s18, s6, s0
	s_addc_u32 s19, s7, 0
	s_add_u32 s16, s10, 0x4000000
	s_addc_u32 s17, s11, 0
	s_add_u32 s20, s14, 0x4000000
	s_addc_u32 s21, s15, 0
	global_load_dwordx4 v[180:183], v244, s[8:9] offset:0
	global_load_dwordx4 v[184:187], v244, s[8:9] offset:1024
	global_load_dwordx4 v[188:191], v244, s[8:9] offset:2048
	global_load_dwordx4 v[192:195], v244, s[8:9] offset:3072
	global_load_dwordx4 v[202:205], v244, s[2:3] offset:0
	global_load_dwordx4 v[206:209], v244, s[2:3] offset:1024
	global_load_dwordx4 v[210:213], v244, s[2:3] offset:2048
	global_load_dwordx4 v[214:217], v244, s[2:3] offset:3072
	s_mov_b64 s[22:23], s[10:11]
	s_mov_b64 s[24:25], s[12:13]
	global_load_dwordx2 v[4:5], v245, s[22:23] offset:0 nt
	global_load_dwordx2 v[6:7], v245, s[22:23] offset:512 nt
	global_load_dwordx2 v[8:9], v245, s[22:23] offset:1024 nt
	global_load_dwordx2 v[10:11], v245, s[22:23] offset:1536 nt
	global_load_dwordx4 v[12:15], v244, s[24:25] offset:0 nt
	global_load_dwordx4 v[16:19], v244, s[24:25] offset:1024 nt
	global_load_dwordx4 v[20:23], v244, s[24:25] offset:2048 nt
	global_load_dwordx4 v[24:27], v244, s[24:25] offset:3072 nt
	s_add_u32 s22, s10, 0x400000
	s_addc_u32 s23, s11, 0
	s_add_u32 s24, s12, 0x800000
	s_addc_u32 s25, s13, 0
	global_load_dwordx2 v[28:29], v245, s[22:23] offset:0 nt
	global_load_dwordx2 v[30:31], v245, s[22:23] offset:512 nt
	global_load_dwordx2 v[32:33], v245, s[22:23] offset:1024 nt
	global_load_dwordx2 v[34:35], v245, s[22:23] offset:1536 nt
	global_load_dwordx4 v[36:39], v244, s[24:25] offset:0 nt
	global_load_dwordx4 v[40:43], v244, s[24:25] offset:1024 nt
	global_load_dwordx4 v[44:47], v244, s[24:25] offset:2048 nt
	global_load_dwordx4 v[48:51], v244, s[24:25] offset:3072 nt
	s_add_u32 s22, s10, 0x800000
	s_addc_u32 s23, s11, 0
	s_add_u32 s24, s12, 0x1000000
	s_addc_u32 s25, s13, 0
	global_load_dwordx2 v[52:53], v245, s[22:23] offset:0 nt
	global_load_dwordx2 v[54:55], v245, s[22:23] offset:512 nt
	global_load_dwordx2 v[56:57], v245, s[22:23] offset:1024 nt
	global_load_dwordx2 v[58:59], v245, s[22:23] offset:1536 nt
	global_load_dwordx4 v[60:63], v244, s[24:25] offset:0 nt
	global_load_dwordx4 v[64:67], v244, s[24:25] offset:1024 nt
	global_load_dwordx4 v[68:71], v244, s[24:25] offset:2048 nt
	global_load_dwordx4 v[72:75], v244, s[24:25] offset:3072 nt
	s_add_u32 s22, s10, 0xc00000
	s_addc_u32 s23, s11, 0
	s_add_u32 s24, s12, 0x1800000
	s_addc_u32 s25, s13, 0
	global_load_dwordx2 v[76:77], v245, s[22:23] offset:0 nt
	global_load_dwordx2 v[78:79], v245, s[22:23] offset:512 nt
	global_load_dwordx2 v[80:81], v245, s[22:23] offset:1024 nt
	global_load_dwordx2 v[82:83], v245, s[22:23] offset:1536 nt
	global_load_dwordx4 v[84:87], v244, s[24:25] offset:0 nt
	global_load_dwordx4 v[88:91], v244, s[24:25] offset:1024 nt
	global_load_dwordx4 v[92:95], v244, s[24:25] offset:2048 nt
	global_load_dwordx4 v[96:99], v244, s[24:25] offset:3072 nt
	s_add_u32 s22, s10, 0x1000000
	s_addc_u32 s23, s11, 0
	s_add_u32 s24, s12, 0x2000000
	s_addc_u32 s25, s13, 0
	global_load_dwordx2 v[100:101], v245, s[22:23] offset:0 nt
	global_load_dwordx2 v[102:103], v245, s[22:23] offset:512 nt
	global_load_dwordx2 v[104:105], v245, s[22:23] offset:1024 nt
	global_load_dwordx2 v[106:107], v245, s[22:23] offset:1536 nt
	global_load_dwordx4 v[108:111], v244, s[24:25] offset:0 nt
	global_load_dwordx4 v[112:115], v244, s[24:25] offset:1024 nt
	global_load_dwordx4 v[116:119], v244, s[24:25] offset:2048 nt
	global_load_dwordx4 v[120:123], v244, s[24:25] offset:3072 nt
	s_add_u32 s22, s10, 0x1400000
	s_addc_u32 s23, s11, 0
	s_add_u32 s24, s12, 0x2800000
	s_addc_u32 s25, s13, 0
	global_load_dwordx2 v[124:125], v245, s[22:23] offset:0 nt
	global_load_dwordx2 v[126:127], v245, s[22:23] offset:512 nt
	global_load_dwordx2 v[128:129], v245, s[22:23] offset:1024 nt
	global_load_dwordx2 v[130:131], v245, s[22:23] offset:1536 nt
	global_load_dwordx4 v[132:135], v244, s[24:25] offset:0 nt
	global_load_dwordx4 v[136:139], v244, s[24:25] offset:1024 nt
	global_load_dwordx4 v[140:143], v244, s[24:25] offset:2048 nt
	global_load_dwordx4 v[144:147], v244, s[24:25] offset:3072 nt
	s_waitcnt vmcnt(40)
	v_lshlrev_b32_e32 v148, 16, v4
	v_and_b32_e32 v149, 0xffff0000, v4
	v_lshlrev_b32_e32 v150, 16, v5
	v_and_b32_e32 v151, 0xffff0000, v5
	v_lshlrev_b32_e32 v152, 16, v6
	v_and_b32_e32 v153, 0xffff0000, v6
	v_lshlrev_b32_e32 v154, 16, v7
	v_and_b32_e32 v155, 0xffff0000, v7
	v_lshlrev_b32_e32 v156, 16, v8
	v_and_b32_e32 v157, 0xffff0000, v8
	v_lshlrev_b32_e32 v158, 16, v9
	v_and_b32_e32 v159, 0xffff0000, v9
	v_lshlrev_b32_e32 v160, 16, v10
	v_and_b32_e32 v161, 0xffff0000, v10
	v_lshlrev_b32_e32 v162, 16, v11
	v_and_b32_e32 v163, 0xffff0000, v11
	s_waitcnt vmcnt(32)
	v_lshlrev_b32_e32 v164, 16, v28
	v_and_b32_e32 v165, 0xffff0000, v28
	v_lshlrev_b32_e32 v166, 16, v29
	v_and_b32_e32 v167, 0xffff0000, v29
	v_lshlrev_b32_e32 v168, 16, v30
	v_and_b32_e32 v169, 0xffff0000, v30
	v_lshlrev_b32_e32 v170, 16, v31
	v_and_b32_e32 v171, 0xffff0000, v31
	v_lshlrev_b32_e32 v172, 16, v32
	v_and_b32_e32 v173, 0xffff0000, v32
	v_lshlrev_b32_e32 v174, 16, v33
	v_and_b32_e32 v175, 0xffff0000, v33
	v_lshlrev_b32_e32 v176, 16, v34
	v_and_b32_e32 v177, 0xffff0000, v34
	v_lshlrev_b32_e32 v178, 16, v35
	v_and_b32_e32 v179, 0xffff0000, v35
	v_pk_mul_f32 v[236:237], v[148:149], v[148:149]
	v_pk_fma_f32 v[236:237], v[150:151], v[150:151], v[236:237]
	v_pk_fma_f32 v[236:237], v[152:153], v[152:153], v[236:237]
	v_pk_fma_f32 v[236:237], v[154:155], v[154:155], v[236:237]
	v_pk_fma_f32 v[236:237], v[156:157], v[156:157], v[236:237]
	v_pk_fma_f32 v[236:237], v[158:159], v[158:159], v[236:237]
	v_pk_fma_f32 v[236:237], v[160:161], v[160:161], v[236:237]
	v_pk_fma_f32 v[236:237], v[162:163], v[162:163], v[236:237]
	v_pk_mul_f32 v[238:239], v[164:165], v[164:165]
	v_pk_fma_f32 v[238:239], v[166:167], v[166:167], v[238:239]
	v_pk_fma_f32 v[238:239], v[168:169], v[168:169], v[238:239]
	v_pk_fma_f32 v[238:239], v[170:171], v[170:171], v[238:239]
	v_pk_fma_f32 v[238:239], v[172:173], v[172:173], v[238:239]
	v_pk_fma_f32 v[238:239], v[174:175], v[174:175], v[238:239]
	v_pk_fma_f32 v[238:239], v[176:177], v[176:177], v[238:239]
	v_pk_fma_f32 v[238:239], v[178:179], v[178:179], v[238:239]
	v_add_f32_e32 v236, v236, v237
	v_add_f32_e32 v238, v238, v239
	s_nop 1
	v_add_f32_dpp v236, v236, v236 quad_perm:[1,0,3,2] row_mask:0xf bank_mask:0xf
	v_add_f32_dpp v238, v238, v238 quad_perm:[1,0,3,2] row_mask:0xf bank_mask:0xf
	s_nop 1
	v_add_f32_dpp v236, v236, v236 quad_perm:[2,3,0,1] row_mask:0xf bank_mask:0xf
	v_add_f32_dpp v238, v238, v238 quad_perm:[2,3,0,1] row_mask:0xf bank_mask:0xf
	s_nop 1
	v_add_f32_dpp v236, v236, v236 row_half_mirror row_mask:0xf bank_mask:0xf
	v_add_f32_dpp v238, v238, v238 row_half_mirror row_mask:0xf bank_mask:0xf
	s_nop 1
	v_add_f32_dpp v236, v236, v236 row_mirror row_mask:0xf bank_mask:0xf
	v_add_f32_dpp v238, v238, v238 row_mirror row_mask:0xf bank_mask:0xf
	s_nop 1
	v_add_f32_dpp v236, v236, v236 row_bcast:15 row_mask:0xa bank_mask:0xf
	v_add_f32_dpp v238, v238, v238 row_bcast:15 row_mask:0xa bank_mask:0xf
	s_nop 1
	v_add_f32_dpp v236, v236, v236 row_bcast:31 row_mask:0xc bank_mask:0xf
	v_add_f32_dpp v238, v238, v238 row_bcast:31 row_mask:0xc bank_mask:0xf
	s_nop 1
	v_readlane_b32 s2, v236, 63
	v_readlane_b32 s3, v238, 63
	s_nop 1
	v_mov_b32_e32 v240, s2
	v_mov_b32_e32 v242, s3
	v_fmamk_f32 v240, v240, 0x3a800000, v196
	v_fmamk_f32 v242, v242, 0x3a800000, v196
	v_rsq_f32_e32 v240, v240
	v_rsq_f32_e32 v242, v242
	s_nop 0
	v_pk_mul_f32 v[148:149], v[148:149], v[240:241] op_sel_hi:[1,0]
	v_pk_mul_f32 v[150:151], v[150:151], v[240:241] op_sel_hi:[1,0]
	v_pk_mul_f32 v[152:153], v[152:153], v[240:241] op_sel_hi:[1,0]
	v_pk_mul_f32 v[154:155], v[154:155], v[240:241] op_sel_hi:[1,0]
	v_pk_mul_f32 v[156:157], v[156:157], v[240:241] op_sel_hi:[1,0]
	v_pk_mul_f32 v[158:159], v[158:159], v[240:241] op_sel_hi:[1,0]
	v_pk_mul_f32 v[160:161], v[160:161], v[240:241] op_sel_hi:[1,0]
	v_pk_mul_f32 v[162:163], v[162:163], v[240:241] op_sel_hi:[1,0]
	v_pk_fma_f32 v[148:149], v[148:149], v[180:181], v[12:13]
	v_pk_fma_f32 v[150:151], v[150:151], v[182:183], v[14:15]
	v_pk_fma_f32 v[152:153], v[152:153], v[184:185], v[16:17]
	v_pk_fma_f32 v[154:155], v[154:155], v[186:187], v[18:19]
	v_pk_fma_f32 v[156:157], v[156:157], v[188:189], v[20:21]
	v_pk_fma_f32 v[158:159], v[158:159], v[190:191], v[22:23]
	v_pk_fma_f32 v[160:161], v[160:161], v[192:193], v[24:25]
	v_pk_fma_f32 v[162:163], v[162:163], v[194:195], v[26:27]
	v_pk_mul_f32 v[164:165], v[164:165], v[242:243] op_sel_hi:[1,0]
	v_pk_mul_f32 v[166:167], v[166:167], v[242:243] op_sel_hi:[1,0]
	v_pk_mul_f32 v[168:169], v[168:169], v[242:243] op_sel_hi:[1,0]
	v_pk_mul_f32 v[170:171], v[170:171], v[242:243] op_sel_hi:[1,0]
	v_pk_mul_f32 v[172:173], v[172:173], v[242:243] op_sel_hi:[1,0]
	v_pk_mul_f32 v[174:175], v[174:175], v[242:243] op_sel_hi:[1,0]
	v_pk_mul_f32 v[176:177], v[176:177], v[242:243] op_sel_hi:[1,0]
	v_pk_mul_f32 v[178:179], v[178:179], v[242:243] op_sel_hi:[1,0]
	v_pk_fma_f32 v[164:165], v[164:165], v[180:181], v[36:37]
	v_pk_fma_f32 v[166:167], v[166:167], v[182:183], v[38:39]
	v_pk_fma_f32 v[168:169], v[168:169], v[184:185], v[40:41]
	v_pk_fma_f32 v[170:171], v[170:171], v[186:187], v[42:43]
	v_pk_fma_f32 v[172:173], v[172:173], v[188:189], v[44:45]
	v_pk_fma_f32 v[174:175], v[174:175], v[190:191], v[46:47]
	v_pk_fma_f32 v[176:177], v[176:177], v[192:193], v[48:49]
	v_pk_fma_f32 v[178:179], v[178:179], v[194:195], v[50:51]
	v_pk_mul_f32 v[236:237], v[148:149], v[148:149]
	v_pk_fma_f32 v[236:237], v[150:151], v[150:151], v[236:237]
	v_pk_fma_f32 v[236:237], v[152:153], v[152:153], v[236:237]
	v_pk_fma_f32 v[236:237], v[154:155], v[154:155], v[236:237]
	v_pk_fma_f32 v[236:237], v[156:157], v[156:157], v[236:237]
	v_pk_fma_f32 v[236:237], v[158:159], v[158:159], v[236:237]
	v_pk_fma_f32 v[236:237], v[160:161], v[160:161], v[236:237]
	v_pk_fma_f32 v[236:237], v[162:163], v[162:163], v[236:237]
	v_pk_mul_f32 v[238:239], v[164:165], v[164:165]
	v_pk_fma_f32 v[238:239], v[166:167], v[166:167], v[238:239]
	v_pk_fma_f32 v[238:239], v[168:169], v[168:169], v[238:239]
	v_pk_fma_f32 v[238:239], v[170:171], v[170:171], v[238:239]
	v_pk_fma_f32 v[238:239], v[172:173], v[172:173], v[238:239]
	v_pk_fma_f32 v[238:239], v[174:175], v[174:175], v[238:239]
	v_pk_fma_f32 v[238:239], v[176:177], v[176:177], v[238:239]
	v_pk_fma_f32 v[238:239], v[178:179], v[178:179], v[238:239]
	v_add_f32_e32 v236, v236, v237
	v_add_f32_e32 v238, v238, v239
	s_nop 1
	v_add_f32_dpp v236, v236, v236 quad_perm:[1,0,3,2] row_mask:0xf bank_mask:0xf
	v_add_f32_dpp v238, v238, v238 quad_perm:[1,0,3,2] row_mask:0xf bank_mask:0xf
	s_nop 1
	v_add_f32_dpp v236, v236, v236 quad_perm:[2,3,0,1] row_mask:0xf bank_mask:0xf
	v_add_f32_dpp v238, v238, v238 quad_perm:[2,3,0,1] row_mask:0xf bank_mask:0xf
	s_nop 1
	v_add_f32_dpp v236, v236, v236 row_half_mirror row_mask:0xf bank_mask:0xf
	v_add_f32_dpp v238, v238, v238 row_half_mirror row_mask:0xf bank_mask:0xf
	s_nop 1
	v_add_f32_dpp v236, v236, v236 row_mirror row_mask:0xf bank_mask:0xf
	v_add_f32_dpp v238, v238, v238 row_mirror row_mask:0xf bank_mask:0xf
	s_nop 1
	v_add_f32_dpp v236, v236, v236 row_bcast:15 row_mask:0xa bank_mask:0xf
	v_add_f32_dpp v238, v238, v238 row_bcast:15 row_mask:0xa bank_mask:0xf
	s_nop 1
	v_add_f32_dpp v236, v236, v236 row_bcast:31 row_mask:0xc bank_mask:0xf
	v_add_f32_dpp v238, v238, v238 row_bcast:31 row_mask:0xc bank_mask:0xf
	s_nop 1
	v_readlane_b32 s2, v236, 63
	v_readlane_b32 s3, v238, 63
	s_nop 1
	v_mov_b32_e32 v240, s2
	v_mov_b32_e32 v242, s3
	v_fmamk_f32 v240, v240, 0x3a800000, v196
	v_fmamk_f32 v242, v242, 0x3a800000, v196
	v_rsq_f32_e32 v240, v240
	v_rsq_f32_e32 v242, v242
	s_nop 0
	v_pk_mul_f32 v[148:149], v[148:149], v[240:241] op_sel_hi:[1,0]
	v_pk_mul_f32 v[150:151], v[150:151], v[240:241] op_sel_hi:[1,0]
	v_pk_mul_f32 v[152:153], v[152:153], v[240:241] op_sel_hi:[1,0]
	v_pk_mul_f32 v[154:155], v[154:155], v[240:241] op_sel_hi:[1,0]
	v_pk_mul_f32 v[156:157], v[156:157], v[240:241] op_sel_hi:[1,0]
	v_pk_mul_f32 v[158:159], v[158:159], v[240:241] op_sel_hi:[1,0]
	v_pk_mul_f32 v[160:161], v[160:161], v[240:241] op_sel_hi:[1,0]
	v_pk_mul_f32 v[162:163], v[162:163], v[240:241] op_sel_hi:[1,0]
	v_pk_mul_f32 v[148:149], v[148:149], v[202:203]
	v_pk_mul_f32 v[150:151], v[150:151], v[204:205]
	v_pk_mul_f32 v[152:153], v[152:153], v[206:207]
	v_pk_mul_f32 v[154:155], v[154:155], v[208:209]
	v_pk_mul_f32 v[156:157], v[156:157], v[210:211]
	v_pk_mul_f32 v[158:159], v[158:159], v[212:213]
	v_pk_mul_f32 v[160:161], v[160:161], v[214:215]
	v_pk_mul_f32 v[162:163], v[162:163], v[216:217]
	v_cvt_pk_bf16_f32 v148, v148, v149
	v_cvt_pk_bf16_f32 v149, v150, v151
	v_cvt_pk_bf16_f32 v150, v152, v153
	v_cvt_pk_bf16_f32 v151, v154, v155
	v_cvt_pk_bf16_f32 v152, v156, v157
	v_cvt_pk_bf16_f32 v153, v158, v159
	v_cvt_pk_bf16_f32 v154, v160, v161
	v_cvt_pk_bf16_f32 v155, v162, v163
	s_mov_b64 s[26:27], s[14:15]
	global_store_dwordx2 v245, v[148:149], s[26:27] offset:0
	global_store_dwordx2 v245, v[150:151], s[26:27] offset:512
	global_store_dwordx2 v245, v[152:153], s[26:27] offset:1024
	global_store_dwordx2 v245, v[154:155], s[26:27] offset:1536
	v_pk_mul_f32 v[164:165], v[164:165], v[242:243] op_sel_hi:[1,0]
	v_pk_mul_f32 v[166:167], v[166:167], v[242:243] op_sel_hi:[1,0]
	v_pk_mul_f32 v[168:169], v[168:169], v[242:243] op_sel_hi:[1,0]
	v_pk_mul_f32 v[170:171], v[170:171], v[242:243] op_sel_hi:[1,0]
	v_pk_mul_f32 v[172:173], v[172:173], v[242:243] op_sel_hi:[1,0]
	v_pk_mul_f32 v[174:175], v[174:175], v[242:243] op_sel_hi:[1,0]
	v_pk_mul_f32 v[176:177], v[176:177], v[242:243] op_sel_hi:[1,0]
	v_pk_mul_f32 v[178:179], v[178:179], v[242:243] op_sel_hi:[1,0]
	v_pk_mul_f32 v[164:165], v[164:165], v[202:203]
	v_pk_mul_f32 v[166:167], v[166:167], v[204:205]
	v_pk_mul_f32 v[168:169], v[168:169], v[206:207]
	v_pk_mul_f32 v[170:171], v[170:171], v[208:209]
	v_pk_mul_f32 v[172:173], v[172:173], v[210:211]
	v_pk_mul_f32 v[174:175], v[174:175], v[212:213]
	v_pk_mul_f32 v[176:177], v[176:177], v[214:215]
	v_pk_mul_f32 v[178:179], v[178:179], v[216:217]
	v_cvt_pk_bf16_f32 v164, v164, v165
	v_cvt_pk_bf16_f32 v165, v166, v167
	v_cvt_pk_bf16_f32 v166, v168, v169
	v_cvt_pk_bf16_f32 v167, v170, v171
	v_cvt_pk_bf16_f32 v168, v172, v173
	v_cvt_pk_bf16_f32 v169, v174, v175
	v_cvt_pk_bf16_f32 v170, v176, v177
	v_cvt_pk_bf16_f32 v171, v178, v179
	s_add_u32 s26, s14, 0x400000
	s_addc_u32 s27, s15, 0
	global_store_dwordx2 v245, v[164:165], s[26:27] offset:0
	global_store_dwordx2 v245, v[166:167], s[26:27] offset:512
	global_store_dwordx2 v245, v[168:169], s[26:27] offset:1024
	global_store_dwordx2 v245, v[170:171], s[26:27] offset:1536
	s_add_u32 s22, s10, 0x1800000
	s_addc_u32 s23, s11, 0
	s_add_u32 s24, s12, 0x3000000
	s_addc_u32 s25, s13, 0
	global_load_dwordx2 v[4:5], v245, s[22:23] offset:0 nt
	global_load_dwordx2 v[6:7], v245, s[22:23] offset:512 nt
	global_load_dwordx2 v[8:9], v245, s[22:23] offset:1024 nt
	global_load_dwordx2 v[10:11], v245, s[22:23] offset:1536 nt
	global_load_dwordx4 v[12:15], v244, s[24:25] offset:0 nt
	global_load_dwordx4 v[16:19], v244, s[24:25] offset:1024 nt
	global_load_dwordx4 v[20:23], v244, s[24:25] offset:2048 nt
	global_load_dwordx4 v[24:27], v244, s[24:25] offset:3072 nt
	s_add_u32 s22, s10, 0x1c00000
	s_addc_u32 s23, s11, 0
	s_add_u32 s24, s12, 0x3800000
	s_addc_u32 s25, s13, 0
	global_load_dwordx2 v[28:29], v245, s[22:23] offset:0 nt
	global_load_dwordx2 v[30:31], v245, s[22:23] offset:512 nt
	global_load_dwordx2 v[32:33], v245, s[22:23] offset:1024 nt
	global_load_dwordx2 v[34:35], v245, s[22:23] offset:1536 nt
	global_load_dwordx4 v[36:39], v244, s[24:25] offset:0 nt
	global_load_dwordx4 v[40:43], v244, s[24:25] offset:1024 nt
	global_load_dwordx4 v[44:47], v244, s[24:25] offset:2048 nt
	global_load_dwordx4 v[48:51], v244, s[24:25] offset:3072 nt
	s_waitcnt vmcnt(48)
	v_lshlrev_b32_e32 v148, 16, v52
	v_and_b32_e32 v149, 0xffff0000, v52
	v_lshlrev_b32_e32 v150, 16, v53
	v_and_b32_e32 v151, 0xffff0000, v53
	v_lshlrev_b32_e32 v152, 16, v54
	v_and_b32_e32 v153, 0xffff0000, v54
	v_lshlrev_b32_e32 v154, 16, v55
	v_and_b32_e32 v155, 0xffff0000, v55
	v_lshlrev_b32_e32 v156, 16, v56
	v_and_b32_e32 v157, 0xffff0000, v56
	v_lshlrev_b32_e32 v158, 16, v57
	v_and_b32_e32 v159, 0xffff0000, v57
	v_lshlrev_b32_e32 v160, 16, v58
	v_and_b32_e32 v161, 0xffff0000, v58
	v_lshlrev_b32_e32 v162, 16, v59
	v_and_b32_e32 v163, 0xffff0000, v59
	s_waitcnt vmcnt(40)
	v_lshlrev_b32_e32 v164, 16, v76
	v_and_b32_e32 v165, 0xffff0000, v76
	v_lshlrev_b32_e32 v166, 16, v77
	v_and_b32_e32 v167, 0xffff0000, v77
	v_lshlrev_b32_e32 v168, 16, v78
	v_and_b32_e32 v169, 0xffff0000, v78
	v_lshlrev_b32_e32 v170, 16, v79
	v_and_b32_e32 v171, 0xffff0000, v79
	v_lshlrev_b32_e32 v172, 16, v80
	v_and_b32_e32 v173, 0xffff0000, v80
	v_lshlrev_b32_e32 v174, 16, v81
	v_and_b32_e32 v175, 0xffff0000, v81
	v_lshlrev_b32_e32 v176, 16, v82
	v_and_b32_e32 v177, 0xffff0000, v82
	v_lshlrev_b32_e32 v178, 16, v83
	v_and_b32_e32 v179, 0xffff0000, v83
	v_pk_mul_f32 v[236:237], v[148:149], v[148:149]
	v_pk_fma_f32 v[236:237], v[150:151], v[150:151], v[236:237]
	v_pk_fma_f32 v[236:237], v[152:153], v[152:153], v[236:237]
	v_pk_fma_f32 v[236:237], v[154:155], v[154:155], v[236:237]
	v_pk_fma_f32 v[236:237], v[156:157], v[156:157], v[236:237]
	v_pk_fma_f32 v[236:237], v[158:159], v[158:159], v[236:237]
	v_pk_fma_f32 v[236:237], v[160:161], v[160:161], v[236:237]
	v_pk_fma_f32 v[236:237], v[162:163], v[162:163], v[236:237]
	v_pk_mul_f32 v[238:239], v[164:165], v[164:165]
	v_pk_fma_f32 v[238:239], v[166:167], v[166:167], v[238:239]
	v_pk_fma_f32 v[238:239], v[168:169], v[168:169], v[238:239]
	v_pk_fma_f32 v[238:239], v[170:171], v[170:171], v[238:239]
	v_pk_fma_f32 v[238:239], v[172:173], v[172:173], v[238:239]
	v_pk_fma_f32 v[238:239], v[174:175], v[174:175], v[238:239]
	v_pk_fma_f32 v[238:239], v[176:177], v[176:177], v[238:239]
	v_pk_fma_f32 v[238:239], v[178:179], v[178:179], v[238:239]
	v_add_f32_e32 v236, v236, v237
	v_add_f32_e32 v238, v238, v239
	s_nop 1
	v_add_f32_dpp v236, v236, v236 quad_perm:[1,0,3,2] row_mask:0xf bank_mask:0xf
	v_add_f32_dpp v238, v238, v238 quad_perm:[1,0,3,2] row_mask:0xf bank_mask:0xf
	s_nop 1
	v_add_f32_dpp v236, v236, v236 quad_perm:[2,3,0,1] row_mask:0xf bank_mask:0xf
	v_add_f32_dpp v238, v238, v238 quad_perm:[2,3,0,1] row_mask:0xf bank_mask:0xf
	s_nop 1
	v_add_f32_dpp v236, v236, v236 row_half_mirror row_mask:0xf bank_mask:0xf
	v_add_f32_dpp v238, v238, v238 row_half_mirror row_mask:0xf bank_mask:0xf
	s_nop 1
	v_add_f32_dpp v236, v236, v236 row_mirror row_mask:0xf bank_mask:0xf
	v_add_f32_dpp v238, v238, v238 row_mirror row_mask:0xf bank_mask:0xf
	s_nop 1
	v_add_f32_dpp v236, v236, v236 row_bcast:15 row_mask:0xa bank_mask:0xf
	v_add_f32_dpp v238, v238, v238 row_bcast:15 row_mask:0xa bank_mask:0xf
	s_nop 1
	v_add_f32_dpp v236, v236, v236 row_bcast:31 row_mask:0xc bank_mask:0xf
	v_add_f32_dpp v238, v238, v238 row_bcast:31 row_mask:0xc bank_mask:0xf
	s_nop 1
	v_readlane_b32 s2, v236, 63
	v_readlane_b32 s3, v238, 63
	s_nop 1
	v_mov_b32_e32 v240, s2
	v_mov_b32_e32 v242, s3
	v_fmamk_f32 v240, v240, 0x3a800000, v196
	v_fmamk_f32 v242, v242, 0x3a800000, v196
	v_rsq_f32_e32 v240, v240
	v_rsq_f32_e32 v242, v242
	s_nop 0
	v_pk_mul_f32 v[148:149], v[148:149], v[240:241] op_sel_hi:[1,0]
	v_pk_mul_f32 v[150:151], v[150:151], v[240:241] op_sel_hi:[1,0]
	v_pk_mul_f32 v[152:153], v[152:153], v[240:241] op_sel_hi:[1,0]
	v_pk_mul_f32 v[154:155], v[154:155], v[240:241] op_sel_hi:[1,0]
	v_pk_mul_f32 v[156:157], v[156:157], v[240:241] op_sel_hi:[1,0]
	v_pk_mul_f32 v[158:159], v[158:159], v[240:241] op_sel_hi:[1,0]
	v_pk_mul_f32 v[160:161], v[160:161], v[240:241] op_sel_hi:[1,0]
	v_pk_mul_f32 v[162:163], v[162:163], v[240:241] op_sel_hi:[1,0]
	v_pk_fma_f32 v[148:149], v[148:149], v[180:181], v[60:61]
	v_pk_fma_f32 v[150:151], v[150:151], v[182:183], v[62:63]
	v_pk_fma_f32 v[152:153], v[152:153], v[184:185], v[64:65]
	v_pk_fma_f32 v[154:155], v[154:155], v[186:187], v[66:67]
	v_pk_fma_f32 v[156:157], v[156:157], v[188:189], v[68:69]
	v_pk_fma_f32 v[158:159], v[158:159], v[190:191], v[70:71]
	v_pk_fma_f32 v[160:161], v[160:161], v[192:193], v[72:73]
	v_pk_fma_f32 v[162:163], v[162:163], v[194:195], v[74:75]
	v_pk_mul_f32 v[164:165], v[164:165], v[242:243] op_sel_hi:[1,0]
	v_pk_mul_f32 v[166:167], v[166:167], v[242:243] op_sel_hi:[1,0]
	v_pk_mul_f32 v[168:169], v[168:169], v[242:243] op_sel_hi:[1,0]
	v_pk_mul_f32 v[170:171], v[170:171], v[242:243] op_sel_hi:[1,0]
	v_pk_mul_f32 v[172:173], v[172:173], v[242:243] op_sel_hi:[1,0]
	v_pk_mul_f32 v[174:175], v[174:175], v[242:243] op_sel_hi:[1,0]
	v_pk_mul_f32 v[176:177], v[176:177], v[242:243] op_sel_hi:[1,0]
	v_pk_mul_f32 v[178:179], v[178:179], v[242:243] op_sel_hi:[1,0]
	v_pk_fma_f32 v[164:165], v[164:165], v[180:181], v[84:85]
	v_pk_fma_f32 v[166:167], v[166:167], v[182:183], v[86:87]
	v_pk_fma_f32 v[168:169], v[168:169], v[184:185], v[88:89]
	v_pk_fma_f32 v[170:171], v[170:171], v[186:187], v[90:91]
	v_pk_fma_f32 v[172:173], v[172:173], v[188:189], v[92:93]
	v_pk_fma_f32 v[174:175], v[174:175], v[190:191], v[94:95]
	v_pk_fma_f32 v[176:177], v[176:177], v[192:193], v[96:97]
	v_pk_fma_f32 v[178:179], v[178:179], v[194:195], v[98:99]
	v_pk_mul_f32 v[236:237], v[148:149], v[148:149]
	v_pk_fma_f32 v[236:237], v[150:151], v[150:151], v[236:237]
	v_pk_fma_f32 v[236:237], v[152:153], v[152:153], v[236:237]
	v_pk_fma_f32 v[236:237], v[154:155], v[154:155], v[236:237]
	v_pk_fma_f32 v[236:237], v[156:157], v[156:157], v[236:237]
	v_pk_fma_f32 v[236:237], v[158:159], v[158:159], v[236:237]
	v_pk_fma_f32 v[236:237], v[160:161], v[160:161], v[236:237]
	v_pk_fma_f32 v[236:237], v[162:163], v[162:163], v[236:237]
	v_pk_mul_f32 v[238:239], v[164:165], v[164:165]
	v_pk_fma_f32 v[238:239], v[166:167], v[166:167], v[238:239]
	v_pk_fma_f32 v[238:239], v[168:169], v[168:169], v[238:239]
	v_pk_fma_f32 v[238:239], v[170:171], v[170:171], v[238:239]
	v_pk_fma_f32 v[238:239], v[172:173], v[172:173], v[238:239]
	v_pk_fma_f32 v[238:239], v[174:175], v[174:175], v[238:239]
	v_pk_fma_f32 v[238:239], v[176:177], v[176:177], v[238:239]
	v_pk_fma_f32 v[238:239], v[178:179], v[178:179], v[238:239]
	v_add_f32_e32 v236, v236, v237
	v_add_f32_e32 v238, v238, v239
	s_nop 1
	v_add_f32_dpp v236, v236, v236 quad_perm:[1,0,3,2] row_mask:0xf bank_mask:0xf
	v_add_f32_dpp v238, v238, v238 quad_perm:[1,0,3,2] row_mask:0xf bank_mask:0xf
	s_nop 1
	v_add_f32_dpp v236, v236, v236 quad_perm:[2,3,0,1] row_mask:0xf bank_mask:0xf
	v_add_f32_dpp v238, v238, v238 quad_perm:[2,3,0,1] row_mask:0xf bank_mask:0xf
	s_nop 1
	v_add_f32_dpp v236, v236, v236 row_half_mirror row_mask:0xf bank_mask:0xf
	v_add_f32_dpp v238, v238, v238 row_half_mirror row_mask:0xf bank_mask:0xf
	s_nop 1
	v_add_f32_dpp v236, v236, v236 row_mirror row_mask:0xf bank_mask:0xf
	v_add_f32_dpp v238, v238, v238 row_mirror row_mask:0xf bank_mask:0xf
	s_nop 1
	v_add_f32_dpp v236, v236, v236 row_bcast:15 row_mask:0xa bank_mask:0xf
	v_add_f32_dpp v238, v238, v238 row_bcast:15 row_mask:0xa bank_mask:0xf
	s_nop 1
	v_add_f32_dpp v236, v236, v236 row_bcast:31 row_mask:0xc bank_mask:0xf
	v_add_f32_dpp v238, v238, v238 row_bcast:31 row_mask:0xc bank_mask:0xf
	s_nop 1
	v_readlane_b32 s2, v236, 63
	v_readlane_b32 s3, v238, 63
	s_nop 1
	v_mov_b32_e32 v240, s2
	v_mov_b32_e32 v242, s3
	v_fmamk_f32 v240, v240, 0x3a800000, v196
	v_fmamk_f32 v242, v242, 0x3a800000, v196
	v_rsq_f32_e32 v240, v240
	v_rsq_f32_e32 v242, v242
	s_nop 0
	v_pk_mul_f32 v[148:149], v[148:149], v[240:241] op_sel_hi:[1,0]
	v_pk_mul_f32 v[150:151], v[150:151], v[240:241] op_sel_hi:[1,0]
	v_pk_mul_f32 v[152:153], v[152:153], v[240:241] op_sel_hi:[1,0]
	v_pk_mul_f32 v[154:155], v[154:155], v[240:241] op_sel_hi:[1,0]
	v_pk_mul_f32 v[156:157], v[156:157], v[240:241] op_sel_hi:[1,0]
	v_pk_mul_f32 v[158:159], v[158:159], v[240:241] op_sel_hi:[1,0]
	v_pk_mul_f32 v[160:161], v[160:161], v[240:241] op_sel_hi:[1,0]
	v_pk_mul_f32 v[162:163], v[162:163], v[240:241] op_sel_hi:[1,0]
	v_pk_mul_f32 v[148:149], v[148:149], v[202:203]
	v_pk_mul_f32 v[150:151], v[150:151], v[204:205]
	v_pk_mul_f32 v[152:153], v[152:153], v[206:207]
	v_pk_mul_f32 v[154:155], v[154:155], v[208:209]
	v_pk_mul_f32 v[156:157], v[156:157], v[210:211]
	v_pk_mul_f32 v[158:159], v[158:159], v[212:213]
	v_pk_mul_f32 v[160:161], v[160:161], v[214:215]
	v_pk_mul_f32 v[162:163], v[162:163], v[216:217]
	v_cvt_pk_bf16_f32 v148, v148, v149
	v_cvt_pk_bf16_f32 v149, v150, v151
	v_cvt_pk_bf16_f32 v150, v152, v153
	v_cvt_pk_bf16_f32 v151, v154, v155
	v_cvt_pk_bf16_f32 v152, v156, v157
	v_cvt_pk_bf16_f32 v153, v158, v159
	v_cvt_pk_bf16_f32 v154, v160, v161
	v_cvt_pk_bf16_f32 v155, v162, v163
	s_add_u32 s26, s14, 0x800000
	s_addc_u32 s27, s15, 0
	global_store_dwordx2 v245, v[148:149], s[26:27] offset:0
	global_store_dwordx2 v245, v[150:151], s[26:27] offset:512
	global_store_dwordx2 v245, v[152:153], s[26:27] offset:1024
	global_store_dwordx2 v245, v[154:155], s[26:27] offset:1536
	v_pk_mul_f32 v[164:165], v[164:165], v[242:243] op_sel_hi:[1,0]
	v_pk_mul_f32 v[166:167], v[166:167], v[242:243] op_sel_hi:[1,0]
	v_pk_mul_f32 v[168:169], v[168:169], v[242:243] op_sel_hi:[1,0]
	v_pk_mul_f32 v[170:171], v[170:171], v[242:243] op_sel_hi:[1,0]
	v_pk_mul_f32 v[172:173], v[172:173], v[242:243] op_sel_hi:[1,0]
	v_pk_mul_f32 v[174:175], v[174:175], v[242:243] op_sel_hi:[1,0]
	v_pk_mul_f32 v[176:177], v[176:177], v[242:243] op_sel_hi:[1,0]
	v_pk_mul_f32 v[178:179], v[178:179], v[242:243] op_sel_hi:[1,0]
	v_pk_mul_f32 v[164:165], v[164:165], v[202:203]
	v_pk_mul_f32 v[166:167], v[166:167], v[204:205]
	v_pk_mul_f32 v[168:169], v[168:169], v[206:207]
	v_pk_mul_f32 v[170:171], v[170:171], v[208:209]
	v_pk_mul_f32 v[172:173], v[172:173], v[210:211]
	v_pk_mul_f32 v[174:175], v[174:175], v[212:213]
	v_pk_mul_f32 v[176:177], v[176:177], v[214:215]
	v_pk_mul_f32 v[178:179], v[178:179], v[216:217]
	v_cvt_pk_bf16_f32 v164, v164, v165
	v_cvt_pk_bf16_f32 v165, v166, v167
	v_cvt_pk_bf16_f32 v166, v168, v169
	v_cvt_pk_bf16_f32 v167, v170, v171
	v_cvt_pk_bf16_f32 v168, v172, v173
	v_cvt_pk_bf16_f32 v169, v174, v175
	v_cvt_pk_bf16_f32 v170, v176, v177
	v_cvt_pk_bf16_f32 v171, v178, v179
	s_add_u32 s26, s14, 0xc00000
	s_addc_u32 s27, s15, 0
	global_store_dwordx2 v245, v[164:165], s[26:27] offset:0
	global_store_dwordx2 v245, v[166:167], s[26:27] offset:512
	global_store_dwordx2 v245, v[168:169], s[26:27] offset:1024
	global_store_dwordx2 v245, v[170:171], s[26:27] offset:1536
	s_add_u32 s22, s10, 0x2000000
	s_addc_u32 s23, s11, 0
	s_add_u32 s24, s12, 0x4000000
	s_addc_u32 s25, s13, 0
	global_load_dwordx2 v[52:53], v245, s[22:23] offset:0 nt
	global_load_dwordx2 v[54:55], v245, s[22:23] offset:512 nt
	global_load_dwordx2 v[56:57], v245, s[22:23] offset:1024 nt
	global_load_dwordx2 v[58:59], v245, s[22:23] offset:1536 nt
	global_load_dwordx4 v[60:63], v244, s[24:25] offset:0 nt
	global_load_dwordx4 v[64:67], v244, s[24:25] offset:1024 nt
	global_load_dwordx4 v[68:71], v244, s[24:25] offset:2048 nt
	global_load_dwordx4 v[72:75], v244, s[24:25] offset:3072 nt
	s_add_u32 s22, s10, 0x2400000
	s_addc_u32 s23, s11, 0
	s_add_u32 s24, s12, 0x4800000
	s_addc_u32 s25, s13, 0
	global_load_dwordx2 v[76:77], v245, s[22:23] offset:0 nt
	global_load_dwordx2 v[78:79], v245, s[22:23] offset:512 nt
	global_load_dwordx2 v[80:81], v245, s[22:23] offset:1024 nt
	global_load_dwordx2 v[82:83], v245, s[22:23] offset:1536 nt
	global_load_dwordx4 v[84:87], v244, s[24:25] offset:0 nt
	global_load_dwordx4 v[88:91], v244, s[24:25] offset:1024 nt
	global_load_dwordx4 v[92:95], v244, s[24:25] offset:2048 nt
	global_load_dwordx4 v[96:99], v244, s[24:25] offset:3072 nt
	s_waitcnt vmcnt(56)
	v_lshlrev_b32_e32 v148, 16, v100
	v_and_b32_e32 v149, 0xffff0000, v100
	v_lshlrev_b32_e32 v150, 16, v101
	v_and_b32_e32 v151, 0xffff0000, v101
	v_lshlrev_b32_e32 v152, 16, v102
	v_and_b32_e32 v153, 0xffff0000, v102
	v_lshlrev_b32_e32 v154, 16, v103
	v_and_b32_e32 v155, 0xffff0000, v103
	v_lshlrev_b32_e32 v156, 16, v104
	v_and_b32_e32 v157, 0xffff0000, v104
	v_lshlrev_b32_e32 v158, 16, v105
	v_and_b32_e32 v159, 0xffff0000, v105
	v_lshlrev_b32_e32 v160, 16, v106
	v_and_b32_e32 v161, 0xffff0000, v106
	v_lshlrev_b32_e32 v162, 16, v107
	v_and_b32_e32 v163, 0xffff0000, v107
	s_waitcnt vmcnt(48)
	v_lshlrev_b32_e32 v164, 16, v124
	v_and_b32_e32 v165, 0xffff0000, v124
	v_lshlrev_b32_e32 v166, 16, v125
	v_and_b32_e32 v167, 0xffff0000, v125
	v_lshlrev_b32_e32 v168, 16, v126
	v_and_b32_e32 v169, 0xffff0000, v126
	v_lshlrev_b32_e32 v170, 16, v127
	v_and_b32_e32 v171, 0xffff0000, v127
	v_lshlrev_b32_e32 v172, 16, v128
	v_and_b32_e32 v173, 0xffff0000, v128
	v_lshlrev_b32_e32 v174, 16, v129
	v_and_b32_e32 v175, 0xffff0000, v129
	v_lshlrev_b32_e32 v176, 16, v130
	v_and_b32_e32 v177, 0xffff0000, v130
	v_lshlrev_b32_e32 v178, 16, v131
	v_and_b32_e32 v179, 0xffff0000, v131
	v_pk_mul_f32 v[236:237], v[148:149], v[148:149]
	v_pk_fma_f32 v[236:237], v[150:151], v[150:151], v[236:237]
	v_pk_fma_f32 v[236:237], v[152:153], v[152:153], v[236:237]
	v_pk_fma_f32 v[236:237], v[154:155], v[154:155], v[236:237]
	v_pk_fma_f32 v[236:237], v[156:157], v[156:157], v[236:237]
	v_pk_fma_f32 v[236:237], v[158:159], v[158:159], v[236:237]
	v_pk_fma_f32 v[236:237], v[160:161], v[160:161], v[236:237]
	v_pk_fma_f32 v[236:237], v[162:163], v[162:163], v[236:237]
	v_pk_mul_f32 v[238:239], v[164:165], v[164:165]
	v_pk_fma_f32 v[238:239], v[166:167], v[166:167], v[238:239]
	v_pk_fma_f32 v[238:239], v[168:169], v[168:169], v[238:239]
	v_pk_fma_f32 v[238:239], v[170:171], v[170:171], v[238:239]
	v_pk_fma_f32 v[238:239], v[172:173], v[172:173], v[238:239]
	v_pk_fma_f32 v[238:239], v[174:175], v[174:175], v[238:239]
	v_pk_fma_f32 v[238:239], v[176:177], v[176:177], v[238:239]
	v_pk_fma_f32 v[238:239], v[178:179], v[178:179], v[238:239]
	v_add_f32_e32 v236, v236, v237
	v_add_f32_e32 v238, v238, v239
	s_nop 1
	v_add_f32_dpp v236, v236, v236 quad_perm:[1,0,3,2] row_mask:0xf bank_mask:0xf
	v_add_f32_dpp v238, v238, v238 quad_perm:[1,0,3,2] row_mask:0xf bank_mask:0xf
	s_nop 1
	v_add_f32_dpp v236, v236, v236 quad_perm:[2,3,0,1] row_mask:0xf bank_mask:0xf
	v_add_f32_dpp v238, v238, v238 quad_perm:[2,3,0,1] row_mask:0xf bank_mask:0xf
	s_nop 1
	v_add_f32_dpp v236, v236, v236 row_half_mirror row_mask:0xf bank_mask:0xf
	v_add_f32_dpp v238, v238, v238 row_half_mirror row_mask:0xf bank_mask:0xf
	s_nop 1
	v_add_f32_dpp v236, v236, v236 row_mirror row_mask:0xf bank_mask:0xf
	v_add_f32_dpp v238, v238, v238 row_mirror row_mask:0xf bank_mask:0xf
	s_nop 1
	v_add_f32_dpp v236, v236, v236 row_bcast:15 row_mask:0xa bank_mask:0xf
	v_add_f32_dpp v238, v238, v238 row_bcast:15 row_mask:0xa bank_mask:0xf
	s_nop 1
	v_add_f32_dpp v236, v236, v236 row_bcast:31 row_mask:0xc bank_mask:0xf
	v_add_f32_dpp v238, v238, v238 row_bcast:31 row_mask:0xc bank_mask:0xf
	s_nop 1
	v_readlane_b32 s2, v236, 63
	v_readlane_b32 s3, v238, 63
	s_nop 1
	v_mov_b32_e32 v240, s2
	v_mov_b32_e32 v242, s3
	v_fmamk_f32 v240, v240, 0x3a800000, v196
	v_fmamk_f32 v242, v242, 0x3a800000, v196
	v_rsq_f32_e32 v240, v240
	v_rsq_f32_e32 v242, v242
	s_nop 0
	v_pk_mul_f32 v[148:149], v[148:149], v[240:241] op_sel_hi:[1,0]
	v_pk_mul_f32 v[150:151], v[150:151], v[240:241] op_sel_hi:[1,0]
	v_pk_mul_f32 v[152:153], v[152:153], v[240:241] op_sel_hi:[1,0]
	v_pk_mul_f32 v[154:155], v[154:155], v[240:241] op_sel_hi:[1,0]
	v_pk_mul_f32 v[156:157], v[156:157], v[240:241] op_sel_hi:[1,0]
	v_pk_mul_f32 v[158:159], v[158:159], v[240:241] op_sel_hi:[1,0]
	v_pk_mul_f32 v[160:161], v[160:161], v[240:241] op_sel_hi:[1,0]
	v_pk_mul_f32 v[162:163], v[162:163], v[240:241] op_sel_hi:[1,0]
	v_pk_fma_f32 v[148:149], v[148:149], v[180:181], v[108:109]
	v_pk_fma_f32 v[150:151], v[150:151], v[182:183], v[110:111]
	v_pk_fma_f32 v[152:153], v[152:153], v[184:185], v[112:113]
	v_pk_fma_f32 v[154:155], v[154:155], v[186:187], v[114:115]
	v_pk_fma_f32 v[156:157], v[156:157], v[188:189], v[116:117]
	v_pk_fma_f32 v[158:159], v[158:159], v[190:191], v[118:119]
	v_pk_fma_f32 v[160:161], v[160:161], v[192:193], v[120:121]
	v_pk_fma_f32 v[162:163], v[162:163], v[194:195], v[122:123]
	v_pk_mul_f32 v[164:165], v[164:165], v[242:243] op_sel_hi:[1,0]
	v_pk_mul_f32 v[166:167], v[166:167], v[242:243] op_sel_hi:[1,0]
	v_pk_mul_f32 v[168:169], v[168:169], v[242:243] op_sel_hi:[1,0]
	v_pk_mul_f32 v[170:171], v[170:171], v[242:243] op_sel_hi:[1,0]
	v_pk_mul_f32 v[172:173], v[172:173], v[242:243] op_sel_hi:[1,0]
	v_pk_mul_f32 v[174:175], v[174:175], v[242:243] op_sel_hi:[1,0]
	v_pk_mul_f32 v[176:177], v[176:177], v[242:243] op_sel_hi:[1,0]
	v_pk_mul_f32 v[178:179], v[178:179], v[242:243] op_sel_hi:[1,0]
	v_pk_fma_f32 v[164:165], v[164:165], v[180:181], v[132:133]
	v_pk_fma_f32 v[166:167], v[166:167], v[182:183], v[134:135]
	v_pk_fma_f32 v[168:169], v[168:169], v[184:185], v[136:137]
	v_pk_fma_f32 v[170:171], v[170:171], v[186:187], v[138:139]
	v_pk_fma_f32 v[172:173], v[172:173], v[188:189], v[140:141]
	v_pk_fma_f32 v[174:175], v[174:175], v[190:191], v[142:143]
	v_pk_fma_f32 v[176:177], v[176:177], v[192:193], v[144:145]
	v_pk_fma_f32 v[178:179], v[178:179], v[194:195], v[146:147]
	v_pk_mul_f32 v[236:237], v[148:149], v[148:149]
	v_pk_fma_f32 v[236:237], v[150:151], v[150:151], v[236:237]
	v_pk_fma_f32 v[236:237], v[152:153], v[152:153], v[236:237]
	v_pk_fma_f32 v[236:237], v[154:155], v[154:155], v[236:237]
	v_pk_fma_f32 v[236:237], v[156:157], v[156:157], v[236:237]
	v_pk_fma_f32 v[236:237], v[158:159], v[158:159], v[236:237]
	v_pk_fma_f32 v[236:237], v[160:161], v[160:161], v[236:237]
	v_pk_fma_f32 v[236:237], v[162:163], v[162:163], v[236:237]
	v_pk_mul_f32 v[238:239], v[164:165], v[164:165]
	v_pk_fma_f32 v[238:239], v[166:167], v[166:167], v[238:239]
	v_pk_fma_f32 v[238:239], v[168:169], v[168:169], v[238:239]
	v_pk_fma_f32 v[238:239], v[170:171], v[170:171], v[238:239]
	v_pk_fma_f32 v[238:239], v[172:173], v[172:173], v[238:239]
	v_pk_fma_f32 v[238:239], v[174:175], v[174:175], v[238:239]
	v_pk_fma_f32 v[238:239], v[176:177], v[176:177], v[238:239]
	v_pk_fma_f32 v[238:239], v[178:179], v[178:179], v[238:239]
	v_add_f32_e32 v236, v236, v237
	v_add_f32_e32 v238, v238, v239
	s_nop 1
	v_add_f32_dpp v236, v236, v236 quad_perm:[1,0,3,2] row_mask:0xf bank_mask:0xf
	v_add_f32_dpp v238, v238, v238 quad_perm:[1,0,3,2] row_mask:0xf bank_mask:0xf
	s_nop 1
	v_add_f32_dpp v236, v236, v236 quad_perm:[2,3,0,1] row_mask:0xf bank_mask:0xf
	v_add_f32_dpp v238, v238, v238 quad_perm:[2,3,0,1] row_mask:0xf bank_mask:0xf
	s_nop 1
	v_add_f32_dpp v236, v236, v236 row_half_mirror row_mask:0xf bank_mask:0xf
	v_add_f32_dpp v238, v238, v238 row_half_mirror row_mask:0xf bank_mask:0xf
	s_nop 1
	v_add_f32_dpp v236, v236, v236 row_mirror row_mask:0xf bank_mask:0xf
	v_add_f32_dpp v238, v238, v238 row_mirror row_mask:0xf bank_mask:0xf
	s_nop 1
	v_add_f32_dpp v236, v236, v236 row_bcast:15 row_mask:0xa bank_mask:0xf
	v_add_f32_dpp v238, v238, v238 row_bcast:15 row_mask:0xa bank_mask:0xf
	s_nop 1
	v_add_f32_dpp v236, v236, v236 row_bcast:31 row_mask:0xc bank_mask:0xf
	v_add_f32_dpp v238, v238, v238 row_bcast:31 row_mask:0xc bank_mask:0xf
	s_nop 1
	v_readlane_b32 s2, v236, 63
	v_readlane_b32 s3, v238, 63
	s_nop 1
	v_mov_b32_e32 v240, s2
	v_mov_b32_e32 v242, s3
	v_fmamk_f32 v240, v240, 0x3a800000, v196
	v_fmamk_f32 v242, v242, 0x3a800000, v196
	v_rsq_f32_e32 v240, v240
	v_rsq_f32_e32 v242, v242
	s_nop 0
	v_pk_mul_f32 v[148:149], v[148:149], v[240:241] op_sel_hi:[1,0]
	v_pk_mul_f32 v[150:151], v[150:151], v[240:241] op_sel_hi:[1,0]
	v_pk_mul_f32 v[152:153], v[152:153], v[240:241] op_sel_hi:[1,0]
	v_pk_mul_f32 v[154:155], v[154:155], v[240:241] op_sel_hi:[1,0]
	v_pk_mul_f32 v[156:157], v[156:157], v[240:241] op_sel_hi:[1,0]
	v_pk_mul_f32 v[158:159], v[158:159], v[240:241] op_sel_hi:[1,0]
	v_pk_mul_f32 v[160:161], v[160:161], v[240:241] op_sel_hi:[1,0]
	v_pk_mul_f32 v[162:163], v[162:163], v[240:241] op_sel_hi:[1,0]
	v_pk_mul_f32 v[148:149], v[148:149], v[202:203]
	v_pk_mul_f32 v[150:151], v[150:151], v[204:205]
	v_pk_mul_f32 v[152:153], v[152:153], v[206:207]
	v_pk_mul_f32 v[154:155], v[154:155], v[208:209]
	v_pk_mul_f32 v[156:157], v[156:157], v[210:211]
	v_pk_mul_f32 v[158:159], v[158:159], v[212:213]
	v_pk_mul_f32 v[160:161], v[160:161], v[214:215]
	v_pk_mul_f32 v[162:163], v[162:163], v[216:217]
	v_cvt_pk_bf16_f32 v148, v148, v149
	v_cvt_pk_bf16_f32 v149, v150, v151
	v_cvt_pk_bf16_f32 v150, v152, v153
	v_cvt_pk_bf16_f32 v151, v154, v155
	v_cvt_pk_bf16_f32 v152, v156, v157
	v_cvt_pk_bf16_f32 v153, v158, v159
	v_cvt_pk_bf16_f32 v154, v160, v161
	v_cvt_pk_bf16_f32 v155, v162, v163
	s_add_u32 s26, s14, 0x1000000
	s_addc_u32 s27, s15, 0
	global_store_dwordx2 v245, v[148:149], s[26:27] offset:0
	global_store_dwordx2 v245, v[150:151], s[26:27] offset:512
	global_store_dwordx2 v245, v[152:153], s[26:27] offset:1024
	global_store_dwordx2 v245, v[154:155], s[26:27] offset:1536
	v_pk_mul_f32 v[164:165], v[164:165], v[242:243] op_sel_hi:[1,0]
	v_pk_mul_f32 v[166:167], v[166:167], v[242:243] op_sel_hi:[1,0]
	v_pk_mul_f32 v[168:169], v[168:169], v[242:243] op_sel_hi:[1,0]
	v_pk_mul_f32 v[170:171], v[170:171], v[242:243] op_sel_hi:[1,0]
	v_pk_mul_f32 v[172:173], v[172:173], v[242:243] op_sel_hi:[1,0]
	v_pk_mul_f32 v[174:175], v[174:175], v[242:243] op_sel_hi:[1,0]
	v_pk_mul_f32 v[176:177], v[176:177], v[242:243] op_sel_hi:[1,0]
	v_pk_mul_f32 v[178:179], v[178:179], v[242:243] op_sel_hi:[1,0]
	v_pk_mul_f32 v[164:165], v[164:165], v[202:203]
	v_pk_mul_f32 v[166:167], v[166:167], v[204:205]
	v_pk_mul_f32 v[168:169], v[168:169], v[206:207]
	v_pk_mul_f32 v[170:171], v[170:171], v[208:209]
	v_pk_mul_f32 v[172:173], v[172:173], v[210:211]
	v_pk_mul_f32 v[174:175], v[174:175], v[212:213]
	v_pk_mul_f32 v[176:177], v[176:177], v[214:215]
	v_pk_mul_f32 v[178:179], v[178:179], v[216:217]
	v_cvt_pk_bf16_f32 v164, v164, v165
	v_cvt_pk_bf16_f32 v165, v166, v167
	v_cvt_pk_bf16_f32 v166, v168, v169
	v_cvt_pk_bf16_f32 v167, v170, v171
	v_cvt_pk_bf16_f32 v168, v172, v173
	v_cvt_pk_bf16_f32 v169, v174, v175
	v_cvt_pk_bf16_f32 v170, v176, v177
	v_cvt_pk_bf16_f32 v171, v178, v179
	s_add_u32 s26, s14, 0x1400000
	s_addc_u32 s27, s15, 0
	global_store_dwordx2 v245, v[164:165], s[26:27] offset:0
	global_store_dwordx2 v245, v[166:167], s[26:27] offset:512
	global_store_dwordx2 v245, v[168:169], s[26:27] offset:1024
	global_store_dwordx2 v245, v[170:171], s[26:27] offset:1536
	s_add_u32 s22, s10, 0x2800000
	s_addc_u32 s23, s11, 0
	s_add_u32 s24, s12, 0x5000000
	s_addc_u32 s25, s13, 0
	global_load_dwordx2 v[100:101], v245, s[22:23] offset:0 nt
	global_load_dwordx2 v[102:103], v245, s[22:23] offset:512 nt
	global_load_dwordx2 v[104:105], v245, s[22:23] offset:1024 nt
	global_load_dwordx2 v[106:107], v245, s[22:23] offset:1536 nt
	global_load_dwordx4 v[108:111], v244, s[24:25] offset:0 nt
	global_load_dwordx4 v[112:115], v244, s[24:25] offset:1024 nt
	global_load_dwordx4 v[116:119], v244, s[24:25] offset:2048 nt
	global_load_dwordx4 v[120:123], v244, s[24:25] offset:3072 nt
	s_add_u32 s22, s10, 0x2c00000
	s_addc_u32 s23, s11, 0
	s_add_u32 s24, s12, 0x5800000
	s_addc_u32 s25, s13, 0
	global_load_dwordx2 v[124:125], v245, s[22:23] offset:0 nt
	global_load_dwordx2 v[126:127], v245, s[22:23] offset:512 nt
	global_load_dwordx2 v[128:129], v245, s[22:23] offset:1024 nt
	global_load_dwordx2 v[130:131], v245, s[22:23] offset:1536 nt
	global_load_dwordx4 v[132:135], v244, s[24:25] offset:0 nt
	global_load_dwordx4 v[136:139], v244, s[24:25] offset:1024 nt
	global_load_dwordx4 v[140:143], v244, s[24:25] offset:2048 nt
	global_load_dwordx4 v[144:147], v244, s[24:25] offset:3072 nt
	s_waitcnt vmcnt(56)
	v_lshlrev_b32_e32 v148, 16, v4
	v_and_b32_e32 v149, 0xffff0000, v4
	v_lshlrev_b32_e32 v150, 16, v5
	v_and_b32_e32 v151, 0xffff0000, v5
	v_lshlrev_b32_e32 v152, 16, v6
	v_and_b32_e32 v153, 0xffff0000, v6
	v_lshlrev_b32_e32 v154, 16, v7
	v_and_b32_e32 v155, 0xffff0000, v7
	v_lshlrev_b32_e32 v156, 16, v8
	v_and_b32_e32 v157, 0xffff0000, v8
	v_lshlrev_b32_e32 v158, 16, v9
	v_and_b32_e32 v159, 0xffff0000, v9
	v_lshlrev_b32_e32 v160, 16, v10
	v_and_b32_e32 v161, 0xffff0000, v10
	v_lshlrev_b32_e32 v162, 16, v11
	v_and_b32_e32 v163, 0xffff0000, v11
	s_waitcnt vmcnt(48)
	v_lshlrev_b32_e32 v164, 16, v28
	v_and_b32_e32 v165, 0xffff0000, v28
	v_lshlrev_b32_e32 v166, 16, v29
	v_and_b32_e32 v167, 0xffff0000, v29
	v_lshlrev_b32_e32 v168, 16, v30
	v_and_b32_e32 v169, 0xffff0000, v30
	v_lshlrev_b32_e32 v170, 16, v31
	v_and_b32_e32 v171, 0xffff0000, v31
	v_lshlrev_b32_e32 v172, 16, v32
	v_and_b32_e32 v173, 0xffff0000, v32
	v_lshlrev_b32_e32 v174, 16, v33
	v_and_b32_e32 v175, 0xffff0000, v33
	v_lshlrev_b32_e32 v176, 16, v34
	v_and_b32_e32 v177, 0xffff0000, v34
	v_lshlrev_b32_e32 v178, 16, v35
	v_and_b32_e32 v179, 0xffff0000, v35
	v_pk_mul_f32 v[236:237], v[148:149], v[148:149]
	v_pk_fma_f32 v[236:237], v[150:151], v[150:151], v[236:237]
	v_pk_fma_f32 v[236:237], v[152:153], v[152:153], v[236:237]
	v_pk_fma_f32 v[236:237], v[154:155], v[154:155], v[236:237]
	v_pk_fma_f32 v[236:237], v[156:157], v[156:157], v[236:237]
	v_pk_fma_f32 v[236:237], v[158:159], v[158:159], v[236:237]
	v_pk_fma_f32 v[236:237], v[160:161], v[160:161], v[236:237]
	v_pk_fma_f32 v[236:237], v[162:163], v[162:163], v[236:237]
	v_pk_mul_f32 v[238:239], v[164:165], v[164:165]
	v_pk_fma_f32 v[238:239], v[166:167], v[166:167], v[238:239]
	v_pk_fma_f32 v[238:239], v[168:169], v[168:169], v[238:239]
	v_pk_fma_f32 v[238:239], v[170:171], v[170:171], v[238:239]
	v_pk_fma_f32 v[238:239], v[172:173], v[172:173], v[238:239]
	v_pk_fma_f32 v[238:239], v[174:175], v[174:175], v[238:239]
	v_pk_fma_f32 v[238:239], v[176:177], v[176:177], v[238:239]
	v_pk_fma_f32 v[238:239], v[178:179], v[178:179], v[238:239]
	v_add_f32_e32 v236, v236, v237
	v_add_f32_e32 v238, v238, v239
	s_nop 1
	v_add_f32_dpp v236, v236, v236 quad_perm:[1,0,3,2] row_mask:0xf bank_mask:0xf
	v_add_f32_dpp v238, v238, v238 quad_perm:[1,0,3,2] row_mask:0xf bank_mask:0xf
	s_nop 1
	v_add_f32_dpp v236, v236, v236 quad_perm:[2,3,0,1] row_mask:0xf bank_mask:0xf
	v_add_f32_dpp v238, v238, v238 quad_perm:[2,3,0,1] row_mask:0xf bank_mask:0xf
	s_nop 1
	v_add_f32_dpp v236, v236, v236 row_half_mirror row_mask:0xf bank_mask:0xf
	v_add_f32_dpp v238, v238, v238 row_half_mirror row_mask:0xf bank_mask:0xf
	s_nop 1
	v_add_f32_dpp v236, v236, v236 row_mirror row_mask:0xf bank_mask:0xf
	v_add_f32_dpp v238, v238, v238 row_mirror row_mask:0xf bank_mask:0xf
	s_nop 1
	v_add_f32_dpp v236, v236, v236 row_bcast:15 row_mask:0xa bank_mask:0xf
	v_add_f32_dpp v238, v238, v238 row_bcast:15 row_mask:0xa bank_mask:0xf
	s_nop 1
	v_add_f32_dpp v236, v236, v236 row_bcast:31 row_mask:0xc bank_mask:0xf
	v_add_f32_dpp v238, v238, v238 row_bcast:31 row_mask:0xc bank_mask:0xf
	s_nop 1
	v_readlane_b32 s2, v236, 63
	v_readlane_b32 s3, v238, 63
	s_nop 1
	v_mov_b32_e32 v240, s2
	v_mov_b32_e32 v242, s3
	v_fmamk_f32 v240, v240, 0x3a800000, v196
	v_fmamk_f32 v242, v242, 0x3a800000, v196
	v_rsq_f32_e32 v240, v240
	v_rsq_f32_e32 v242, v242
	s_nop 0
	v_pk_mul_f32 v[148:149], v[148:149], v[240:241] op_sel_hi:[1,0]
	v_pk_mul_f32 v[150:151], v[150:151], v[240:241] op_sel_hi:[1,0]
	v_pk_mul_f32 v[152:153], v[152:153], v[240:241] op_sel_hi:[1,0]
	v_pk_mul_f32 v[154:155], v[154:155], v[240:241] op_sel_hi:[1,0]
	v_pk_mul_f32 v[156:157], v[156:157], v[240:241] op_sel_hi:[1,0]
	v_pk_mul_f32 v[158:159], v[158:159], v[240:241] op_sel_hi:[1,0]
	v_pk_mul_f32 v[160:161], v[160:161], v[240:241] op_sel_hi:[1,0]
	v_pk_mul_f32 v[162:163], v[162:163], v[240:241] op_sel_hi:[1,0]
	v_pk_fma_f32 v[148:149], v[148:149], v[180:181], v[12:13]
	v_pk_fma_f32 v[150:151], v[150:151], v[182:183], v[14:15]
	v_pk_fma_f32 v[152:153], v[152:153], v[184:185], v[16:17]
	v_pk_fma_f32 v[154:155], v[154:155], v[186:187], v[18:19]
	v_pk_fma_f32 v[156:157], v[156:157], v[188:189], v[20:21]
	v_pk_fma_f32 v[158:159], v[158:159], v[190:191], v[22:23]
	v_pk_fma_f32 v[160:161], v[160:161], v[192:193], v[24:25]
	v_pk_fma_f32 v[162:163], v[162:163], v[194:195], v[26:27]
	v_pk_mul_f32 v[164:165], v[164:165], v[242:243] op_sel_hi:[1,0]
	v_pk_mul_f32 v[166:167], v[166:167], v[242:243] op_sel_hi:[1,0]
	v_pk_mul_f32 v[168:169], v[168:169], v[242:243] op_sel_hi:[1,0]
	v_pk_mul_f32 v[170:171], v[170:171], v[242:243] op_sel_hi:[1,0]
	v_pk_mul_f32 v[172:173], v[172:173], v[242:243] op_sel_hi:[1,0]
	v_pk_mul_f32 v[174:175], v[174:175], v[242:243] op_sel_hi:[1,0]
	v_pk_mul_f32 v[176:177], v[176:177], v[242:243] op_sel_hi:[1,0]
	v_pk_mul_f32 v[178:179], v[178:179], v[242:243] op_sel_hi:[1,0]
	v_pk_fma_f32 v[164:165], v[164:165], v[180:181], v[36:37]
	v_pk_fma_f32 v[166:167], v[166:167], v[182:183], v[38:39]
	v_pk_fma_f32 v[168:169], v[168:169], v[184:185], v[40:41]
	v_pk_fma_f32 v[170:171], v[170:171], v[186:187], v[42:43]
	v_pk_fma_f32 v[172:173], v[172:173], v[188:189], v[44:45]
	v_pk_fma_f32 v[174:175], v[174:175], v[190:191], v[46:47]
	v_pk_fma_f32 v[176:177], v[176:177], v[192:193], v[48:49]
	v_pk_fma_f32 v[178:179], v[178:179], v[194:195], v[50:51]
	v_pk_mul_f32 v[236:237], v[148:149], v[148:149]
	v_pk_fma_f32 v[236:237], v[150:151], v[150:151], v[236:237]
	v_pk_fma_f32 v[236:237], v[152:153], v[152:153], v[236:237]
	v_pk_fma_f32 v[236:237], v[154:155], v[154:155], v[236:237]
	v_pk_fma_f32 v[236:237], v[156:157], v[156:157], v[236:237]
	v_pk_fma_f32 v[236:237], v[158:159], v[158:159], v[236:237]
	v_pk_fma_f32 v[236:237], v[160:161], v[160:161], v[236:237]
	v_pk_fma_f32 v[236:237], v[162:163], v[162:163], v[236:237]
	v_pk_mul_f32 v[238:239], v[164:165], v[164:165]
	v_pk_fma_f32 v[238:239], v[166:167], v[166:167], v[238:239]
	v_pk_fma_f32 v[238:239], v[168:169], v[168:169], v[238:239]
	v_pk_fma_f32 v[238:239], v[170:171], v[170:171], v[238:239]
	v_pk_fma_f32 v[238:239], v[172:173], v[172:173], v[238:239]
	v_pk_fma_f32 v[238:239], v[174:175], v[174:175], v[238:239]
	v_pk_fma_f32 v[238:239], v[176:177], v[176:177], v[238:239]
	v_pk_fma_f32 v[238:239], v[178:179], v[178:179], v[238:239]
	v_add_f32_e32 v236, v236, v237
	v_add_f32_e32 v238, v238, v239
	s_nop 1
	v_add_f32_dpp v236, v236, v236 quad_perm:[1,0,3,2] row_mask:0xf bank_mask:0xf
	v_add_f32_dpp v238, v238, v238 quad_perm:[1,0,3,2] row_mask:0xf bank_mask:0xf
	s_nop 1
	v_add_f32_dpp v236, v236, v236 quad_perm:[2,3,0,1] row_mask:0xf bank_mask:0xf
	v_add_f32_dpp v238, v238, v238 quad_perm:[2,3,0,1] row_mask:0xf bank_mask:0xf
	s_nop 1
	v_add_f32_dpp v236, v236, v236 row_half_mirror row_mask:0xf bank_mask:0xf
	v_add_f32_dpp v238, v238, v238 row_half_mirror row_mask:0xf bank_mask:0xf
	s_nop 1
	v_add_f32_dpp v236, v236, v236 row_mirror row_mask:0xf bank_mask:0xf
	v_add_f32_dpp v238, v238, v238 row_mirror row_mask:0xf bank_mask:0xf
	s_nop 1
	v_add_f32_dpp v236, v236, v236 row_bcast:15 row_mask:0xa bank_mask:0xf
	v_add_f32_dpp v238, v238, v238 row_bcast:15 row_mask:0xa bank_mask:0xf
	s_nop 1
	v_add_f32_dpp v236, v236, v236 row_bcast:31 row_mask:0xc bank_mask:0xf
	v_add_f32_dpp v238, v238, v238 row_bcast:31 row_mask:0xc bank_mask:0xf
	s_nop 1
	v_readlane_b32 s2, v236, 63
	v_readlane_b32 s3, v238, 63
	s_nop 1
	v_mov_b32_e32 v240, s2
	v_mov_b32_e32 v242, s3
	v_fmamk_f32 v240, v240, 0x3a800000, v196
	v_fmamk_f32 v242, v242, 0x3a800000, v196
	v_rsq_f32_e32 v240, v240
	v_rsq_f32_e32 v242, v242
	s_nop 0
	v_pk_mul_f32 v[148:149], v[148:149], v[240:241] op_sel_hi:[1,0]
	v_pk_mul_f32 v[150:151], v[150:151], v[240:241] op_sel_hi:[1,0]
	v_pk_mul_f32 v[152:153], v[152:153], v[240:241] op_sel_hi:[1,0]
	v_pk_mul_f32 v[154:155], v[154:155], v[240:241] op_sel_hi:[1,0]
	v_pk_mul_f32 v[156:157], v[156:157], v[240:241] op_sel_hi:[1,0]
	v_pk_mul_f32 v[158:159], v[158:159], v[240:241] op_sel_hi:[1,0]
	v_pk_mul_f32 v[160:161], v[160:161], v[240:241] op_sel_hi:[1,0]
	v_pk_mul_f32 v[162:163], v[162:163], v[240:241] op_sel_hi:[1,0]
	v_pk_mul_f32 v[148:149], v[148:149], v[202:203]
	v_pk_mul_f32 v[150:151], v[150:151], v[204:205]
	v_pk_mul_f32 v[152:153], v[152:153], v[206:207]
	v_pk_mul_f32 v[154:155], v[154:155], v[208:209]
	v_pk_mul_f32 v[156:157], v[156:157], v[210:211]
	v_pk_mul_f32 v[158:159], v[158:159], v[212:213]
	v_pk_mul_f32 v[160:161], v[160:161], v[214:215]
	v_pk_mul_f32 v[162:163], v[162:163], v[216:217]
	v_cvt_pk_bf16_f32 v148, v148, v149
	v_cvt_pk_bf16_f32 v149, v150, v151
	v_cvt_pk_bf16_f32 v150, v152, v153
	v_cvt_pk_bf16_f32 v151, v154, v155
	v_cvt_pk_bf16_f32 v152, v156, v157
	v_cvt_pk_bf16_f32 v153, v158, v159
	v_cvt_pk_bf16_f32 v154, v160, v161
	v_cvt_pk_bf16_f32 v155, v162, v163
	s_add_u32 s26, s14, 0x1800000
	s_addc_u32 s27, s15, 0
	global_store_dwordx2 v245, v[148:149], s[26:27] offset:0
	global_store_dwordx2 v245, v[150:151], s[26:27] offset:512
	global_store_dwordx2 v245, v[152:153], s[26:27] offset:1024
	global_store_dwordx2 v245, v[154:155], s[26:27] offset:1536
	v_pk_mul_f32 v[164:165], v[164:165], v[242:243] op_sel_hi:[1,0]
	v_pk_mul_f32 v[166:167], v[166:167], v[242:243] op_sel_hi:[1,0]
	v_pk_mul_f32 v[168:169], v[168:169], v[242:243] op_sel_hi:[1,0]
	v_pk_mul_f32 v[170:171], v[170:171], v[242:243] op_sel_hi:[1,0]
	v_pk_mul_f32 v[172:173], v[172:173], v[242:243] op_sel_hi:[1,0]
	v_pk_mul_f32 v[174:175], v[174:175], v[242:243] op_sel_hi:[1,0]
	v_pk_mul_f32 v[176:177], v[176:177], v[242:243] op_sel_hi:[1,0]
	v_pk_mul_f32 v[178:179], v[178:179], v[242:243] op_sel_hi:[1,0]
	v_pk_mul_f32 v[164:165], v[164:165], v[202:203]
	v_pk_mul_f32 v[166:167], v[166:167], v[204:205]
	v_pk_mul_f32 v[168:169], v[168:169], v[206:207]
	v_pk_mul_f32 v[170:171], v[170:171], v[208:209]
	v_pk_mul_f32 v[172:173], v[172:173], v[210:211]
	v_pk_mul_f32 v[174:175], v[174:175], v[212:213]
	v_pk_mul_f32 v[176:177], v[176:177], v[214:215]
	v_pk_mul_f32 v[178:179], v[178:179], v[216:217]
	v_cvt_pk_bf16_f32 v164, v164, v165
	v_cvt_pk_bf16_f32 v165, v166, v167
	v_cvt_pk_bf16_f32 v166, v168, v169
	v_cvt_pk_bf16_f32 v167, v170, v171
	v_cvt_pk_bf16_f32 v168, v172, v173
	v_cvt_pk_bf16_f32 v169, v174, v175
	v_cvt_pk_bf16_f32 v170, v176, v177
	v_cvt_pk_bf16_f32 v171, v178, v179
	s_add_u32 s26, s14, 0x1c00000
	s_addc_u32 s27, s15, 0
	global_store_dwordx2 v245, v[164:165], s[26:27] offset:0
	global_store_dwordx2 v245, v[166:167], s[26:27] offset:512
	global_store_dwordx2 v245, v[168:169], s[26:27] offset:1024
	global_store_dwordx2 v245, v[170:171], s[26:27] offset:1536
	s_add_u32 s22, s10, 0x3000000
	s_addc_u32 s23, s11, 0
	s_add_u32 s24, s12, 0x6000000
	s_addc_u32 s25, s13, 0
	global_load_dwordx2 v[4:5], v245, s[22:23] offset:0 nt
	global_load_dwordx2 v[6:7], v245, s[22:23] offset:512 nt
	global_load_dwordx2 v[8:9], v245, s[22:23] offset:1024 nt
	global_load_dwordx2 v[10:11], v245, s[22:23] offset:1536 nt
	global_load_dwordx4 v[12:15], v244, s[24:25] offset:0 nt
	global_load_dwordx4 v[16:19], v244, s[24:25] offset:1024 nt
	global_load_dwordx4 v[20:23], v244, s[24:25] offset:2048 nt
	global_load_dwordx4 v[24:27], v244, s[24:25] offset:3072 nt
	s_add_u32 s22, s10, 0x3400000
	s_addc_u32 s23, s11, 0
	s_add_u32 s24, s12, 0x6800000
	s_addc_u32 s25, s13, 0
	global_load_dwordx2 v[28:29], v245, s[22:23] offset:0 nt
	global_load_dwordx2 v[30:31], v245, s[22:23] offset:512 nt
	global_load_dwordx2 v[32:33], v245, s[22:23] offset:1024 nt
	global_load_dwordx2 v[34:35], v245, s[22:23] offset:1536 nt
	global_load_dwordx4 v[36:39], v244, s[24:25] offset:0 nt
	global_load_dwordx4 v[40:43], v244, s[24:25] offset:1024 nt
	global_load_dwordx4 v[44:47], v244, s[24:25] offset:2048 nt
	global_load_dwordx4 v[48:51], v244, s[24:25] offset:3072 nt
	s_waitcnt vmcnt(56)
	v_lshlrev_b32_e32 v148, 16, v52
	v_and_b32_e32 v149, 0xffff0000, v52
	v_lshlrev_b32_e32 v150, 16, v53
	v_and_b32_e32 v151, 0xffff0000, v53
	v_lshlrev_b32_e32 v152, 16, v54
	v_and_b32_e32 v153, 0xffff0000, v54
	v_lshlrev_b32_e32 v154, 16, v55
	v_and_b32_e32 v155, 0xffff0000, v55
	v_lshlrev_b32_e32 v156, 16, v56
	v_and_b32_e32 v157, 0xffff0000, v56
	v_lshlrev_b32_e32 v158, 16, v57
	v_and_b32_e32 v159, 0xffff0000, v57
	v_lshlrev_b32_e32 v160, 16, v58
	v_and_b32_e32 v161, 0xffff0000, v58
	v_lshlrev_b32_e32 v162, 16, v59
	v_and_b32_e32 v163, 0xffff0000, v59
	s_waitcnt vmcnt(48)
	v_lshlrev_b32_e32 v164, 16, v76
	v_and_b32_e32 v165, 0xffff0000, v76
	v_lshlrev_b32_e32 v166, 16, v77
	v_and_b32_e32 v167, 0xffff0000, v77
	v_lshlrev_b32_e32 v168, 16, v78
	v_and_b32_e32 v169, 0xffff0000, v78
	v_lshlrev_b32_e32 v170, 16, v79
	v_and_b32_e32 v171, 0xffff0000, v79
	v_lshlrev_b32_e32 v172, 16, v80
	v_and_b32_e32 v173, 0xffff0000, v80
	v_lshlrev_b32_e32 v174, 16, v81
	v_and_b32_e32 v175, 0xffff0000, v81
	v_lshlrev_b32_e32 v176, 16, v82
	v_and_b32_e32 v177, 0xffff0000, v82
	v_lshlrev_b32_e32 v178, 16, v83
	v_and_b32_e32 v179, 0xffff0000, v83
	v_pk_mul_f32 v[236:237], v[148:149], v[148:149]
	v_pk_fma_f32 v[236:237], v[150:151], v[150:151], v[236:237]
	v_pk_fma_f32 v[236:237], v[152:153], v[152:153], v[236:237]
	v_pk_fma_f32 v[236:237], v[154:155], v[154:155], v[236:237]
	v_pk_fma_f32 v[236:237], v[156:157], v[156:157], v[236:237]
	v_pk_fma_f32 v[236:237], v[158:159], v[158:159], v[236:237]
	v_pk_fma_f32 v[236:237], v[160:161], v[160:161], v[236:237]
	v_pk_fma_f32 v[236:237], v[162:163], v[162:163], v[236:237]
	v_pk_mul_f32 v[238:239], v[164:165], v[164:165]
	v_pk_fma_f32 v[238:239], v[166:167], v[166:167], v[238:239]
	v_pk_fma_f32 v[238:239], v[168:169], v[168:169], v[238:239]
	v_pk_fma_f32 v[238:239], v[170:171], v[170:171], v[238:239]
	v_pk_fma_f32 v[238:239], v[172:173], v[172:173], v[238:239]
	v_pk_fma_f32 v[238:239], v[174:175], v[174:175], v[238:239]
	v_pk_fma_f32 v[238:239], v[176:177], v[176:177], v[238:239]
	v_pk_fma_f32 v[238:239], v[178:179], v[178:179], v[238:239]
	v_add_f32_e32 v236, v236, v237
	v_add_f32_e32 v238, v238, v239
	s_nop 1
	v_add_f32_dpp v236, v236, v236 quad_perm:[1,0,3,2] row_mask:0xf bank_mask:0xf
	v_add_f32_dpp v238, v238, v238 quad_perm:[1,0,3,2] row_mask:0xf bank_mask:0xf
	s_nop 1
	v_add_f32_dpp v236, v236, v236 quad_perm:[2,3,0,1] row_mask:0xf bank_mask:0xf
	v_add_f32_dpp v238, v238, v238 quad_perm:[2,3,0,1] row_mask:0xf bank_mask:0xf
	s_nop 1
	v_add_f32_dpp v236, v236, v236 row_half_mirror row_mask:0xf bank_mask:0xf
	v_add_f32_dpp v238, v238, v238 row_half_mirror row_mask:0xf bank_mask:0xf
	s_nop 1
	v_add_f32_dpp v236, v236, v236 row_mirror row_mask:0xf bank_mask:0xf
	v_add_f32_dpp v238, v238, v238 row_mirror row_mask:0xf bank_mask:0xf
	s_nop 1
	v_add_f32_dpp v236, v236, v236 row_bcast:15 row_mask:0xa bank_mask:0xf
	v_add_f32_dpp v238, v238, v238 row_bcast:15 row_mask:0xa bank_mask:0xf
	s_nop 1
	v_add_f32_dpp v236, v236, v236 row_bcast:31 row_mask:0xc bank_mask:0xf
	v_add_f32_dpp v238, v238, v238 row_bcast:31 row_mask:0xc bank_mask:0xf
	s_nop 1
	v_readlane_b32 s2, v236, 63
	v_readlane_b32 s3, v238, 63
	s_nop 1
	v_mov_b32_e32 v240, s2
	v_mov_b32_e32 v242, s3
	v_fmamk_f32 v240, v240, 0x3a800000, v196
	v_fmamk_f32 v242, v242, 0x3a800000, v196
	v_rsq_f32_e32 v240, v240
	v_rsq_f32_e32 v242, v242
	s_nop 0
	v_pk_mul_f32 v[148:149], v[148:149], v[240:241] op_sel_hi:[1,0]
	v_pk_mul_f32 v[150:151], v[150:151], v[240:241] op_sel_hi:[1,0]
	v_pk_mul_f32 v[152:153], v[152:153], v[240:241] op_sel_hi:[1,0]
	v_pk_mul_f32 v[154:155], v[154:155], v[240:241] op_sel_hi:[1,0]
	v_pk_mul_f32 v[156:157], v[156:157], v[240:241] op_sel_hi:[1,0]
	v_pk_mul_f32 v[158:159], v[158:159], v[240:241] op_sel_hi:[1,0]
	v_pk_mul_f32 v[160:161], v[160:161], v[240:241] op_sel_hi:[1,0]
	v_pk_mul_f32 v[162:163], v[162:163], v[240:241] op_sel_hi:[1,0]
	v_pk_fma_f32 v[148:149], v[148:149], v[180:181], v[60:61]
	v_pk_fma_f32 v[150:151], v[150:151], v[182:183], v[62:63]
	v_pk_fma_f32 v[152:153], v[152:153], v[184:185], v[64:65]
	v_pk_fma_f32 v[154:155], v[154:155], v[186:187], v[66:67]
	v_pk_fma_f32 v[156:157], v[156:157], v[188:189], v[68:69]
	v_pk_fma_f32 v[158:159], v[158:159], v[190:191], v[70:71]
	v_pk_fma_f32 v[160:161], v[160:161], v[192:193], v[72:73]
	v_pk_fma_f32 v[162:163], v[162:163], v[194:195], v[74:75]
	v_pk_mul_f32 v[164:165], v[164:165], v[242:243] op_sel_hi:[1,0]
	v_pk_mul_f32 v[166:167], v[166:167], v[242:243] op_sel_hi:[1,0]
	v_pk_mul_f32 v[168:169], v[168:169], v[242:243] op_sel_hi:[1,0]
	v_pk_mul_f32 v[170:171], v[170:171], v[242:243] op_sel_hi:[1,0]
	v_pk_mul_f32 v[172:173], v[172:173], v[242:243] op_sel_hi:[1,0]
	v_pk_mul_f32 v[174:175], v[174:175], v[242:243] op_sel_hi:[1,0]
	v_pk_mul_f32 v[176:177], v[176:177], v[242:243] op_sel_hi:[1,0]
	v_pk_mul_f32 v[178:179], v[178:179], v[242:243] op_sel_hi:[1,0]
	v_pk_fma_f32 v[164:165], v[164:165], v[180:181], v[84:85]
	v_pk_fma_f32 v[166:167], v[166:167], v[182:183], v[86:87]
	v_pk_fma_f32 v[168:169], v[168:169], v[184:185], v[88:89]
	v_pk_fma_f32 v[170:171], v[170:171], v[186:187], v[90:91]
	v_pk_fma_f32 v[172:173], v[172:173], v[188:189], v[92:93]
	v_pk_fma_f32 v[174:175], v[174:175], v[190:191], v[94:95]
	v_pk_fma_f32 v[176:177], v[176:177], v[192:193], v[96:97]
	v_pk_fma_f32 v[178:179], v[178:179], v[194:195], v[98:99]
	v_pk_mul_f32 v[236:237], v[148:149], v[148:149]
	v_pk_fma_f32 v[236:237], v[150:151], v[150:151], v[236:237]
	v_pk_fma_f32 v[236:237], v[152:153], v[152:153], v[236:237]
	v_pk_fma_f32 v[236:237], v[154:155], v[154:155], v[236:237]
	v_pk_fma_f32 v[236:237], v[156:157], v[156:157], v[236:237]
	v_pk_fma_f32 v[236:237], v[158:159], v[158:159], v[236:237]
	v_pk_fma_f32 v[236:237], v[160:161], v[160:161], v[236:237]
	v_pk_fma_f32 v[236:237], v[162:163], v[162:163], v[236:237]
	v_pk_mul_f32 v[238:239], v[164:165], v[164:165]
	v_pk_fma_f32 v[238:239], v[166:167], v[166:167], v[238:239]
	v_pk_fma_f32 v[238:239], v[168:169], v[168:169], v[238:239]
	v_pk_fma_f32 v[238:239], v[170:171], v[170:171], v[238:239]
	v_pk_fma_f32 v[238:239], v[172:173], v[172:173], v[238:239]
	v_pk_fma_f32 v[238:239], v[174:175], v[174:175], v[238:239]
	v_pk_fma_f32 v[238:239], v[176:177], v[176:177], v[238:239]
	v_pk_fma_f32 v[238:239], v[178:179], v[178:179], v[238:239]
	v_add_f32_e32 v236, v236, v237
	v_add_f32_e32 v238, v238, v239
	s_nop 1
	v_add_f32_dpp v236, v236, v236 quad_perm:[1,0,3,2] row_mask:0xf bank_mask:0xf
	v_add_f32_dpp v238, v238, v238 quad_perm:[1,0,3,2] row_mask:0xf bank_mask:0xf
	s_nop 1
	v_add_f32_dpp v236, v236, v236 quad_perm:[2,3,0,1] row_mask:0xf bank_mask:0xf
	v_add_f32_dpp v238, v238, v238 quad_perm:[2,3,0,1] row_mask:0xf bank_mask:0xf
	s_nop 1
	v_add_f32_dpp v236, v236, v236 row_half_mirror row_mask:0xf bank_mask:0xf
	v_add_f32_dpp v238, v238, v238 row_half_mirror row_mask:0xf bank_mask:0xf
	s_nop 1
	v_add_f32_dpp v236, v236, v236 row_mirror row_mask:0xf bank_mask:0xf
	v_add_f32_dpp v238, v238, v238 row_mirror row_mask:0xf bank_mask:0xf
	s_nop 1
	v_add_f32_dpp v236, v236, v236 row_bcast:15 row_mask:0xa bank_mask:0xf
	v_add_f32_dpp v238, v238, v238 row_bcast:15 row_mask:0xa bank_mask:0xf
	s_nop 1
	v_add_f32_dpp v236, v236, v236 row_bcast:31 row_mask:0xc bank_mask:0xf
	v_add_f32_dpp v238, v238, v238 row_bcast:31 row_mask:0xc bank_mask:0xf
	s_nop 1
	v_readlane_b32 s2, v236, 63
	v_readlane_b32 s3, v238, 63
	s_nop 1
	v_mov_b32_e32 v240, s2
	v_mov_b32_e32 v242, s3
	v_fmamk_f32 v240, v240, 0x3a800000, v196
	v_fmamk_f32 v242, v242, 0x3a800000, v196
	v_rsq_f32_e32 v240, v240
	v_rsq_f32_e32 v242, v242
	s_nop 0
	v_pk_mul_f32 v[148:149], v[148:149], v[240:241] op_sel_hi:[1,0]
	v_pk_mul_f32 v[150:151], v[150:151], v[240:241] op_sel_hi:[1,0]
	v_pk_mul_f32 v[152:153], v[152:153], v[240:241] op_sel_hi:[1,0]
	v_pk_mul_f32 v[154:155], v[154:155], v[240:241] op_sel_hi:[1,0]
	v_pk_mul_f32 v[156:157], v[156:157], v[240:241] op_sel_hi:[1,0]
	v_pk_mul_f32 v[158:159], v[158:159], v[240:241] op_sel_hi:[1,0]
	v_pk_mul_f32 v[160:161], v[160:161], v[240:241] op_sel_hi:[1,0]
	v_pk_mul_f32 v[162:163], v[162:163], v[240:241] op_sel_hi:[1,0]
	v_pk_mul_f32 v[148:149], v[148:149], v[202:203]
	v_pk_mul_f32 v[150:151], v[150:151], v[204:205]
	v_pk_mul_f32 v[152:153], v[152:153], v[206:207]
	v_pk_mul_f32 v[154:155], v[154:155], v[208:209]
	v_pk_mul_f32 v[156:157], v[156:157], v[210:211]
	v_pk_mul_f32 v[158:159], v[158:159], v[212:213]
	v_pk_mul_f32 v[160:161], v[160:161], v[214:215]
	v_pk_mul_f32 v[162:163], v[162:163], v[216:217]
	v_cvt_pk_bf16_f32 v148, v148, v149
	v_cvt_pk_bf16_f32 v149, v150, v151
	v_cvt_pk_bf16_f32 v150, v152, v153
	v_cvt_pk_bf16_f32 v151, v154, v155
	v_cvt_pk_bf16_f32 v152, v156, v157
	v_cvt_pk_bf16_f32 v153, v158, v159
	v_cvt_pk_bf16_f32 v154, v160, v161
	v_cvt_pk_bf16_f32 v155, v162, v163
	s_add_u32 s26, s14, 0x2000000
	s_addc_u32 s27, s15, 0
	global_store_dwordx2 v245, v[148:149], s[26:27] offset:0
	global_store_dwordx2 v245, v[150:151], s[26:27] offset:512
	global_store_dwordx2 v245, v[152:153], s[26:27] offset:1024
	global_store_dwordx2 v245, v[154:155], s[26:27] offset:1536
	v_pk_mul_f32 v[164:165], v[164:165], v[242:243] op_sel_hi:[1,0]
	v_pk_mul_f32 v[166:167], v[166:167], v[242:243] op_sel_hi:[1,0]
	v_pk_mul_f32 v[168:169], v[168:169], v[242:243] op_sel_hi:[1,0]
	v_pk_mul_f32 v[170:171], v[170:171], v[242:243] op_sel_hi:[1,0]
	v_pk_mul_f32 v[172:173], v[172:173], v[242:243] op_sel_hi:[1,0]
	v_pk_mul_f32 v[174:175], v[174:175], v[242:243] op_sel_hi:[1,0]
	v_pk_mul_f32 v[176:177], v[176:177], v[242:243] op_sel_hi:[1,0]
	v_pk_mul_f32 v[178:179], v[178:179], v[242:243] op_sel_hi:[1,0]
	v_pk_mul_f32 v[164:165], v[164:165], v[202:203]
	v_pk_mul_f32 v[166:167], v[166:167], v[204:205]
	v_pk_mul_f32 v[168:169], v[168:169], v[206:207]
	v_pk_mul_f32 v[170:171], v[170:171], v[208:209]
	v_pk_mul_f32 v[172:173], v[172:173], v[210:211]
	v_pk_mul_f32 v[174:175], v[174:175], v[212:213]
	v_pk_mul_f32 v[176:177], v[176:177], v[214:215]
	v_pk_mul_f32 v[178:179], v[178:179], v[216:217]
	v_cvt_pk_bf16_f32 v164, v164, v165
	v_cvt_pk_bf16_f32 v165, v166, v167
	v_cvt_pk_bf16_f32 v166, v168, v169
	v_cvt_pk_bf16_f32 v167, v170, v171
	v_cvt_pk_bf16_f32 v168, v172, v173
	v_cvt_pk_bf16_f32 v169, v174, v175
	v_cvt_pk_bf16_f32 v170, v176, v177
	v_cvt_pk_bf16_f32 v171, v178, v179
	s_add_u32 s26, s14, 0x2400000
	s_addc_u32 s27, s15, 0
	global_store_dwordx2 v245, v[164:165], s[26:27] offset:0
	global_store_dwordx2 v245, v[166:167], s[26:27] offset:512
	global_store_dwordx2 v245, v[168:169], s[26:27] offset:1024
	global_store_dwordx2 v245, v[170:171], s[26:27] offset:1536
	s_add_u32 s22, s10, 0x3800000
	s_addc_u32 s23, s11, 0
	s_add_u32 s24, s12, 0x7000000
	s_addc_u32 s25, s13, 0
	global_load_dwordx2 v[52:53], v245, s[22:23] offset:0 nt
	global_load_dwordx2 v[54:55], v245, s[22:23] offset:512 nt
	global_load_dwordx2 v[56:57], v245, s[22:23] offset:1024 nt
	global_load_dwordx2 v[58:59], v245, s[22:23] offset:1536 nt
	global_load_dwordx4 v[60:63], v244, s[24:25] offset:0 nt
	global_load_dwordx4 v[64:67], v244, s[24:25] offset:1024 nt
	global_load_dwordx4 v[68:71], v244, s[24:25] offset:2048 nt
	global_load_dwordx4 v[72:75], v244, s[24:25] offset:3072 nt
	s_add_u32 s22, s10, 0x3c00000
	s_addc_u32 s23, s11, 0
	s_add_u32 s24, s12, 0x7800000
	s_addc_u32 s25, s13, 0
	global_load_dwordx2 v[76:77], v245, s[22:23] offset:0 nt
	global_load_dwordx2 v[78:79], v245, s[22:23] offset:512 nt
	global_load_dwordx2 v[80:81], v245, s[22:23] offset:1024 nt
	global_load_dwordx2 v[82:83], v245, s[22:23] offset:1536 nt
	global_load_dwordx4 v[84:87], v244, s[24:25] offset:0 nt
	global_load_dwordx4 v[88:91], v244, s[24:25] offset:1024 nt
	global_load_dwordx4 v[92:95], v244, s[24:25] offset:2048 nt
	global_load_dwordx4 v[96:99], v244, s[24:25] offset:3072 nt
	s_waitcnt vmcnt(56)
	v_lshlrev_b32_e32 v148, 16, v100
	v_and_b32_e32 v149, 0xffff0000, v100
	v_lshlrev_b32_e32 v150, 16, v101
	v_and_b32_e32 v151, 0xffff0000, v101
	v_lshlrev_b32_e32 v152, 16, v102
	v_and_b32_e32 v153, 0xffff0000, v102
	v_lshlrev_b32_e32 v154, 16, v103
	v_and_b32_e32 v155, 0xffff0000, v103
	v_lshlrev_b32_e32 v156, 16, v104
	v_and_b32_e32 v157, 0xffff0000, v104
	v_lshlrev_b32_e32 v158, 16, v105
	v_and_b32_e32 v159, 0xffff0000, v105
	v_lshlrev_b32_e32 v160, 16, v106
	v_and_b32_e32 v161, 0xffff0000, v106
	v_lshlrev_b32_e32 v162, 16, v107
	v_and_b32_e32 v163, 0xffff0000, v107
	s_waitcnt vmcnt(48)
	v_lshlrev_b32_e32 v164, 16, v124
	v_and_b32_e32 v165, 0xffff0000, v124
	v_lshlrev_b32_e32 v166, 16, v125
	v_and_b32_e32 v167, 0xffff0000, v125
	v_lshlrev_b32_e32 v168, 16, v126
	v_and_b32_e32 v169, 0xffff0000, v126
	v_lshlrev_b32_e32 v170, 16, v127
	v_and_b32_e32 v171, 0xffff0000, v127
	v_lshlrev_b32_e32 v172, 16, v128
	v_and_b32_e32 v173, 0xffff0000, v128
	v_lshlrev_b32_e32 v174, 16, v129
	v_and_b32_e32 v175, 0xffff0000, v129
	v_lshlrev_b32_e32 v176, 16, v130
	v_and_b32_e32 v177, 0xffff0000, v130
	v_lshlrev_b32_e32 v178, 16, v131
	v_and_b32_e32 v179, 0xffff0000, v131
	v_pk_mul_f32 v[236:237], v[148:149], v[148:149]
	v_pk_fma_f32 v[236:237], v[150:151], v[150:151], v[236:237]
	v_pk_fma_f32 v[236:237], v[152:153], v[152:153], v[236:237]
	v_pk_fma_f32 v[236:237], v[154:155], v[154:155], v[236:237]
	v_pk_fma_f32 v[236:237], v[156:157], v[156:157], v[236:237]
	v_pk_fma_f32 v[236:237], v[158:159], v[158:159], v[236:237]
	v_pk_fma_f32 v[236:237], v[160:161], v[160:161], v[236:237]
	v_pk_fma_f32 v[236:237], v[162:163], v[162:163], v[236:237]
	v_pk_mul_f32 v[238:239], v[164:165], v[164:165]
	v_pk_fma_f32 v[238:239], v[166:167], v[166:167], v[238:239]
	v_pk_fma_f32 v[238:239], v[168:169], v[168:169], v[238:239]
	v_pk_fma_f32 v[238:239], v[170:171], v[170:171], v[238:239]
	v_pk_fma_f32 v[238:239], v[172:173], v[172:173], v[238:239]
	v_pk_fma_f32 v[238:239], v[174:175], v[174:175], v[238:239]
	v_pk_fma_f32 v[238:239], v[176:177], v[176:177], v[238:239]
	v_pk_fma_f32 v[238:239], v[178:179], v[178:179], v[238:239]
	v_add_f32_e32 v236, v236, v237
	v_add_f32_e32 v238, v238, v239
	s_nop 1
	v_add_f32_dpp v236, v236, v236 quad_perm:[1,0,3,2] row_mask:0xf bank_mask:0xf
	v_add_f32_dpp v238, v238, v238 quad_perm:[1,0,3,2] row_mask:0xf bank_mask:0xf
	s_nop 1
	v_add_f32_dpp v236, v236, v236 quad_perm:[2,3,0,1] row_mask:0xf bank_mask:0xf
	v_add_f32_dpp v238, v238, v238 quad_perm:[2,3,0,1] row_mask:0xf bank_mask:0xf
	s_nop 1
	v_add_f32_dpp v236, v236, v236 row_half_mirror row_mask:0xf bank_mask:0xf
	v_add_f32_dpp v238, v238, v238 row_half_mirror row_mask:0xf bank_mask:0xf
	s_nop 1
	v_add_f32_dpp v236, v236, v236 row_mirror row_mask:0xf bank_mask:0xf
	v_add_f32_dpp v238, v238, v238 row_mirror row_mask:0xf bank_mask:0xf
	s_nop 1
	v_add_f32_dpp v236, v236, v236 row_bcast:15 row_mask:0xa bank_mask:0xf
	v_add_f32_dpp v238, v238, v238 row_bcast:15 row_mask:0xa bank_mask:0xf
	s_nop 1
	v_add_f32_dpp v236, v236, v236 row_bcast:31 row_mask:0xc bank_mask:0xf
	v_add_f32_dpp v238, v238, v238 row_bcast:31 row_mask:0xc bank_mask:0xf
	s_nop 1
	v_readlane_b32 s2, v236, 63
	v_readlane_b32 s3, v238, 63
	s_nop 1
	v_mov_b32_e32 v240, s2
	v_mov_b32_e32 v242, s3
	v_fmamk_f32 v240, v240, 0x3a800000, v196
	v_fmamk_f32 v242, v242, 0x3a800000, v196
	v_rsq_f32_e32 v240, v240
	v_rsq_f32_e32 v242, v242
	s_nop 0
	v_pk_mul_f32 v[148:149], v[148:149], v[240:241] op_sel_hi:[1,0]
	v_pk_mul_f32 v[150:151], v[150:151], v[240:241] op_sel_hi:[1,0]
	v_pk_mul_f32 v[152:153], v[152:153], v[240:241] op_sel_hi:[1,0]
	v_pk_mul_f32 v[154:155], v[154:155], v[240:241] op_sel_hi:[1,0]
	v_pk_mul_f32 v[156:157], v[156:157], v[240:241] op_sel_hi:[1,0]
	v_pk_mul_f32 v[158:159], v[158:159], v[240:241] op_sel_hi:[1,0]
	v_pk_mul_f32 v[160:161], v[160:161], v[240:241] op_sel_hi:[1,0]
	v_pk_mul_f32 v[162:163], v[162:163], v[240:241] op_sel_hi:[1,0]
	v_pk_fma_f32 v[148:149], v[148:149], v[180:181], v[108:109]
	v_pk_fma_f32 v[150:151], v[150:151], v[182:183], v[110:111]
	v_pk_fma_f32 v[152:153], v[152:153], v[184:185], v[112:113]
	v_pk_fma_f32 v[154:155], v[154:155], v[186:187], v[114:115]
	v_pk_fma_f32 v[156:157], v[156:157], v[188:189], v[116:117]
	v_pk_fma_f32 v[158:159], v[158:159], v[190:191], v[118:119]
	v_pk_fma_f32 v[160:161], v[160:161], v[192:193], v[120:121]
	v_pk_fma_f32 v[162:163], v[162:163], v[194:195], v[122:123]
	v_pk_mul_f32 v[164:165], v[164:165], v[242:243] op_sel_hi:[1,0]
	v_pk_mul_f32 v[166:167], v[166:167], v[242:243] op_sel_hi:[1,0]
	v_pk_mul_f32 v[168:169], v[168:169], v[242:243] op_sel_hi:[1,0]
	v_pk_mul_f32 v[170:171], v[170:171], v[242:243] op_sel_hi:[1,0]
	v_pk_mul_f32 v[172:173], v[172:173], v[242:243] op_sel_hi:[1,0]
	v_pk_mul_f32 v[174:175], v[174:175], v[242:243] op_sel_hi:[1,0]
	v_pk_mul_f32 v[176:177], v[176:177], v[242:243] op_sel_hi:[1,0]
	v_pk_mul_f32 v[178:179], v[178:179], v[242:243] op_sel_hi:[1,0]
	v_pk_fma_f32 v[164:165], v[164:165], v[180:181], v[132:133]
	v_pk_fma_f32 v[166:167], v[166:167], v[182:183], v[134:135]
	v_pk_fma_f32 v[168:169], v[168:169], v[184:185], v[136:137]
	v_pk_fma_f32 v[170:171], v[170:171], v[186:187], v[138:139]
	v_pk_fma_f32 v[172:173], v[172:173], v[188:189], v[140:141]
	v_pk_fma_f32 v[174:175], v[174:175], v[190:191], v[142:143]
	v_pk_fma_f32 v[176:177], v[176:177], v[192:193], v[144:145]
	v_pk_fma_f32 v[178:179], v[178:179], v[194:195], v[146:147]
	v_pk_mul_f32 v[236:237], v[148:149], v[148:149]
	v_pk_fma_f32 v[236:237], v[150:151], v[150:151], v[236:237]
	v_pk_fma_f32 v[236:237], v[152:153], v[152:153], v[236:237]
	v_pk_fma_f32 v[236:237], v[154:155], v[154:155], v[236:237]
	v_pk_fma_f32 v[236:237], v[156:157], v[156:157], v[236:237]
	v_pk_fma_f32 v[236:237], v[158:159], v[158:159], v[236:237]
	v_pk_fma_f32 v[236:237], v[160:161], v[160:161], v[236:237]
	v_pk_fma_f32 v[236:237], v[162:163], v[162:163], v[236:237]
	v_pk_mul_f32 v[238:239], v[164:165], v[164:165]
	v_pk_fma_f32 v[238:239], v[166:167], v[166:167], v[238:239]
	v_pk_fma_f32 v[238:239], v[168:169], v[168:169], v[238:239]
	v_pk_fma_f32 v[238:239], v[170:171], v[170:171], v[238:239]
	v_pk_fma_f32 v[238:239], v[172:173], v[172:173], v[238:239]
	v_pk_fma_f32 v[238:239], v[174:175], v[174:175], v[238:239]
	v_pk_fma_f32 v[238:239], v[176:177], v[176:177], v[238:239]
	v_pk_fma_f32 v[238:239], v[178:179], v[178:179], v[238:239]
	v_add_f32_e32 v236, v236, v237
	v_add_f32_e32 v238, v238, v239
	s_nop 1
	v_add_f32_dpp v236, v236, v236 quad_perm:[1,0,3,2] row_mask:0xf bank_mask:0xf
	v_add_f32_dpp v238, v238, v238 quad_perm:[1,0,3,2] row_mask:0xf bank_mask:0xf
	s_nop 1
	v_add_f32_dpp v236, v236, v236 quad_perm:[2,3,0,1] row_mask:0xf bank_mask:0xf
	v_add_f32_dpp v238, v238, v238 quad_perm:[2,3,0,1] row_mask:0xf bank_mask:0xf
	s_nop 1
	v_add_f32_dpp v236, v236, v236 row_half_mirror row_mask:0xf bank_mask:0xf
	v_add_f32_dpp v238, v238, v238 row_half_mirror row_mask:0xf bank_mask:0xf
	s_nop 1
	v_add_f32_dpp v236, v236, v236 row_mirror row_mask:0xf bank_mask:0xf
	v_add_f32_dpp v238, v238, v238 row_mirror row_mask:0xf bank_mask:0xf
	s_nop 1
	v_add_f32_dpp v236, v236, v236 row_bcast:15 row_mask:0xa bank_mask:0xf
	v_add_f32_dpp v238, v238, v238 row_bcast:15 row_mask:0xa bank_mask:0xf
	s_nop 1
	v_add_f32_dpp v236, v236, v236 row_bcast:31 row_mask:0xc bank_mask:0xf
	v_add_f32_dpp v238, v238, v238 row_bcast:31 row_mask:0xc bank_mask:0xf
	s_nop 1
	v_readlane_b32 s2, v236, 63
	v_readlane_b32 s3, v238, 63
	s_nop 1
	v_mov_b32_e32 v240, s2
	v_mov_b32_e32 v242, s3
	v_fmamk_f32 v240, v240, 0x3a800000, v196
	v_fmamk_f32 v242, v242, 0x3a800000, v196
	v_rsq_f32_e32 v240, v240
	v_rsq_f32_e32 v242, v242
	s_nop 0
	v_pk_mul_f32 v[148:149], v[148:149], v[240:241] op_sel_hi:[1,0]
	v_pk_mul_f32 v[150:151], v[150:151], v[240:241] op_sel_hi:[1,0]
	v_pk_mul_f32 v[152:153], v[152:153], v[240:241] op_sel_hi:[1,0]
	v_pk_mul_f32 v[154:155], v[154:155], v[240:241] op_sel_hi:[1,0]
	v_pk_mul_f32 v[156:157], v[156:157], v[240:241] op_sel_hi:[1,0]
	v_pk_mul_f32 v[158:159], v[158:159], v[240:241] op_sel_hi:[1,0]
	v_pk_mul_f32 v[160:161], v[160:161], v[240:241] op_sel_hi:[1,0]
	v_pk_mul_f32 v[162:163], v[162:163], v[240:241] op_sel_hi:[1,0]
	v_pk_mul_f32 v[148:149], v[148:149], v[202:203]
	v_pk_mul_f32 v[150:151], v[150:151], v[204:205]
	v_pk_mul_f32 v[152:153], v[152:153], v[206:207]
	v_pk_mul_f32 v[154:155], v[154:155], v[208:209]
	v_pk_mul_f32 v[156:157], v[156:157], v[210:211]
	v_pk_mul_f32 v[158:159], v[158:159], v[212:213]
	v_pk_mul_f32 v[160:161], v[160:161], v[214:215]
	v_pk_mul_f32 v[162:163], v[162:163], v[216:217]
	v_cvt_pk_bf16_f32 v148, v148, v149
	v_cvt_pk_bf16_f32 v149, v150, v151
	v_cvt_pk_bf16_f32 v150, v152, v153
	v_cvt_pk_bf16_f32 v151, v154, v155
	v_cvt_pk_bf16_f32 v152, v156, v157
	v_cvt_pk_bf16_f32 v153, v158, v159
	v_cvt_pk_bf16_f32 v154, v160, v161
	v_cvt_pk_bf16_f32 v155, v162, v163
	s_add_u32 s26, s14, 0x2800000
	s_addc_u32 s27, s15, 0
	global_store_dwordx2 v245, v[148:149], s[26:27] offset:0
	global_store_dwordx2 v245, v[150:151], s[26:27] offset:512
	global_store_dwordx2 v245, v[152:153], s[26:27] offset:1024
	global_store_dwordx2 v245, v[154:155], s[26:27] offset:1536
	v_pk_mul_f32 v[164:165], v[164:165], v[242:243] op_sel_hi:[1,0]
	v_pk_mul_f32 v[166:167], v[166:167], v[242:243] op_sel_hi:[1,0]
	v_pk_mul_f32 v[168:169], v[168:169], v[242:243] op_sel_hi:[1,0]
	v_pk_mul_f32 v[170:171], v[170:171], v[242:243] op_sel_hi:[1,0]
	v_pk_mul_f32 v[172:173], v[172:173], v[242:243] op_sel_hi:[1,0]
	v_pk_mul_f32 v[174:175], v[174:175], v[242:243] op_sel_hi:[1,0]
	v_pk_mul_f32 v[176:177], v[176:177], v[242:243] op_sel_hi:[1,0]
	v_pk_mul_f32 v[178:179], v[178:179], v[242:243] op_sel_hi:[1,0]
	v_pk_mul_f32 v[164:165], v[164:165], v[202:203]
	v_pk_mul_f32 v[166:167], v[166:167], v[204:205]
	v_pk_mul_f32 v[168:169], v[168:169], v[206:207]
	v_pk_mul_f32 v[170:171], v[170:171], v[208:209]
	v_pk_mul_f32 v[172:173], v[172:173], v[210:211]
	v_pk_mul_f32 v[174:175], v[174:175], v[212:213]
	v_pk_mul_f32 v[176:177], v[176:177], v[214:215]
	v_pk_mul_f32 v[178:179], v[178:179], v[216:217]
	v_cvt_pk_bf16_f32 v164, v164, v165
	v_cvt_pk_bf16_f32 v165, v166, v167
	v_cvt_pk_bf16_f32 v166, v168, v169
	v_cvt_pk_bf16_f32 v167, v170, v171
	v_cvt_pk_bf16_f32 v168, v172, v173
	v_cvt_pk_bf16_f32 v169, v174, v175
	v_cvt_pk_bf16_f32 v170, v176, v177
	v_cvt_pk_bf16_f32 v171, v178, v179
	s_add_u32 s26, s14, 0x2c00000
	s_addc_u32 s27, s15, 0
	global_store_dwordx2 v245, v[164:165], s[26:27] offset:0
	global_store_dwordx2 v245, v[166:167], s[26:27] offset:512
	global_store_dwordx2 v245, v[168:169], s[26:27] offset:1024
	global_store_dwordx2 v245, v[170:171], s[26:27] offset:1536
	s_waitcnt vmcnt(40)
	v_lshlrev_b32_e32 v148, 16, v4
	v_and_b32_e32 v149, 0xffff0000, v4
	v_lshlrev_b32_e32 v150, 16, v5
	v_and_b32_e32 v151, 0xffff0000, v5
	v_lshlrev_b32_e32 v152, 16, v6
	v_and_b32_e32 v153, 0xffff0000, v6
	v_lshlrev_b32_e32 v154, 16, v7
	v_and_b32_e32 v155, 0xffff0000, v7
	v_lshlrev_b32_e32 v156, 16, v8
	v_and_b32_e32 v157, 0xffff0000, v8
	v_lshlrev_b32_e32 v158, 16, v9
	v_and_b32_e32 v159, 0xffff0000, v9
	v_lshlrev_b32_e32 v160, 16, v10
	v_and_b32_e32 v161, 0xffff0000, v10
	v_lshlrev_b32_e32 v162, 16, v11
	v_and_b32_e32 v163, 0xffff0000, v11
	s_waitcnt vmcnt(32)
	v_lshlrev_b32_e32 v164, 16, v28
	v_and_b32_e32 v165, 0xffff0000, v28
	v_lshlrev_b32_e32 v166, 16, v29
	v_and_b32_e32 v167, 0xffff0000, v29
	v_lshlrev_b32_e32 v168, 16, v30
	v_and_b32_e32 v169, 0xffff0000, v30
	v_lshlrev_b32_e32 v170, 16, v31
	v_and_b32_e32 v171, 0xffff0000, v31
	v_lshlrev_b32_e32 v172, 16, v32
	v_and_b32_e32 v173, 0xffff0000, v32
	v_lshlrev_b32_e32 v174, 16, v33
	v_and_b32_e32 v175, 0xffff0000, v33
	v_lshlrev_b32_e32 v176, 16, v34
	v_and_b32_e32 v177, 0xffff0000, v34
	v_lshlrev_b32_e32 v178, 16, v35
	v_and_b32_e32 v179, 0xffff0000, v35
	v_pk_mul_f32 v[236:237], v[148:149], v[148:149]
	v_pk_fma_f32 v[236:237], v[150:151], v[150:151], v[236:237]
	v_pk_fma_f32 v[236:237], v[152:153], v[152:153], v[236:237]
	v_pk_fma_f32 v[236:237], v[154:155], v[154:155], v[236:237]
	v_pk_fma_f32 v[236:237], v[156:157], v[156:157], v[236:237]
	v_pk_fma_f32 v[236:237], v[158:159], v[158:159], v[236:237]
	v_pk_fma_f32 v[236:237], v[160:161], v[160:161], v[236:237]
	v_pk_fma_f32 v[236:237], v[162:163], v[162:163], v[236:237]
	v_pk_mul_f32 v[238:239], v[164:165], v[164:165]
	v_pk_fma_f32 v[238:239], v[166:167], v[166:167], v[238:239]
	v_pk_fma_f32 v[238:239], v[168:169], v[168:169], v[238:239]
	v_pk_fma_f32 v[238:239], v[170:171], v[170:171], v[238:239]
	v_pk_fma_f32 v[238:239], v[172:173], v[172:173], v[238:239]
	v_pk_fma_f32 v[238:239], v[174:175], v[174:175], v[238:239]
	v_pk_fma_f32 v[238:239], v[176:177], v[176:177], v[238:239]
	v_pk_fma_f32 v[238:239], v[178:179], v[178:179], v[238:239]
	v_add_f32_e32 v236, v236, v237
	v_add_f32_e32 v238, v238, v239
	s_nop 1
	v_add_f32_dpp v236, v236, v236 quad_perm:[1,0,3,2] row_mask:0xf bank_mask:0xf
	v_add_f32_dpp v238, v238, v238 quad_perm:[1,0,3,2] row_mask:0xf bank_mask:0xf
	s_nop 1
	v_add_f32_dpp v236, v236, v236 quad_perm:[2,3,0,1] row_mask:0xf bank_mask:0xf
	v_add_f32_dpp v238, v238, v238 quad_perm:[2,3,0,1] row_mask:0xf bank_mask:0xf
	s_nop 1
	v_add_f32_dpp v236, v236, v236 row_half_mirror row_mask:0xf bank_mask:0xf
	v_add_f32_dpp v238, v238, v238 row_half_mirror row_mask:0xf bank_mask:0xf
	s_nop 1
	v_add_f32_dpp v236, v236, v236 row_mirror row_mask:0xf bank_mask:0xf
	v_add_f32_dpp v238, v238, v238 row_mirror row_mask:0xf bank_mask:0xf
	s_nop 1
	v_add_f32_dpp v236, v236, v236 row_bcast:15 row_mask:0xa bank_mask:0xf
	v_add_f32_dpp v238, v238, v238 row_bcast:15 row_mask:0xa bank_mask:0xf
	s_nop 1
	v_add_f32_dpp v236, v236, v236 row_bcast:31 row_mask:0xc bank_mask:0xf
	v_add_f32_dpp v238, v238, v238 row_bcast:31 row_mask:0xc bank_mask:0xf
	s_nop 1
	v_readlane_b32 s2, v236, 63
	v_readlane_b32 s3, v238, 63
	s_nop 1
	v_mov_b32_e32 v240, s2
	v_mov_b32_e32 v242, s3
	v_fmamk_f32 v240, v240, 0x3a800000, v196
	v_fmamk_f32 v242, v242, 0x3a800000, v196
	v_rsq_f32_e32 v240, v240
	v_rsq_f32_e32 v242, v242
	s_nop 0
	v_pk_mul_f32 v[148:149], v[148:149], v[240:241] op_sel_hi:[1,0]
	v_pk_mul_f32 v[150:151], v[150:151], v[240:241] op_sel_hi:[1,0]
	v_pk_mul_f32 v[152:153], v[152:153], v[240:241] op_sel_hi:[1,0]
	v_pk_mul_f32 v[154:155], v[154:155], v[240:241] op_sel_hi:[1,0]
	v_pk_mul_f32 v[156:157], v[156:157], v[240:241] op_sel_hi:[1,0]
	v_pk_mul_f32 v[158:159], v[158:159], v[240:241] op_sel_hi:[1,0]
	v_pk_mul_f32 v[160:161], v[160:161], v[240:241] op_sel_hi:[1,0]
	v_pk_mul_f32 v[162:163], v[162:163], v[240:241] op_sel_hi:[1,0]
	v_pk_fma_f32 v[148:149], v[148:149], v[180:181], v[12:13]
	v_pk_fma_f32 v[150:151], v[150:151], v[182:183], v[14:15]
	v_pk_fma_f32 v[152:153], v[152:153], v[184:185], v[16:17]
	v_pk_fma_f32 v[154:155], v[154:155], v[186:187], v[18:19]
	v_pk_fma_f32 v[156:157], v[156:157], v[188:189], v[20:21]
	v_pk_fma_f32 v[158:159], v[158:159], v[190:191], v[22:23]
	v_pk_fma_f32 v[160:161], v[160:161], v[192:193], v[24:25]
	v_pk_fma_f32 v[162:163], v[162:163], v[194:195], v[26:27]
	v_pk_mul_f32 v[164:165], v[164:165], v[242:243] op_sel_hi:[1,0]
	v_pk_mul_f32 v[166:167], v[166:167], v[242:243] op_sel_hi:[1,0]
	v_pk_mul_f32 v[168:169], v[168:169], v[242:243] op_sel_hi:[1,0]
	v_pk_mul_f32 v[170:171], v[170:171], v[242:243] op_sel_hi:[1,0]
	v_pk_mul_f32 v[172:173], v[172:173], v[242:243] op_sel_hi:[1,0]
	v_pk_mul_f32 v[174:175], v[174:175], v[242:243] op_sel_hi:[1,0]
	v_pk_mul_f32 v[176:177], v[176:177], v[242:243] op_sel_hi:[1,0]
	v_pk_mul_f32 v[178:179], v[178:179], v[242:243] op_sel_hi:[1,0]
	v_pk_fma_f32 v[164:165], v[164:165], v[180:181], v[36:37]
	v_pk_fma_f32 v[166:167], v[166:167], v[182:183], v[38:39]
	v_pk_fma_f32 v[168:169], v[168:169], v[184:185], v[40:41]
	v_pk_fma_f32 v[170:171], v[170:171], v[186:187], v[42:43]
	v_pk_fma_f32 v[172:173], v[172:173], v[188:189], v[44:45]
	v_pk_fma_f32 v[174:175], v[174:175], v[190:191], v[46:47]
	v_pk_fma_f32 v[176:177], v[176:177], v[192:193], v[48:49]
	v_pk_fma_f32 v[178:179], v[178:179], v[194:195], v[50:51]
	v_pk_mul_f32 v[236:237], v[148:149], v[148:149]
	v_pk_fma_f32 v[236:237], v[150:151], v[150:151], v[236:237]
	v_pk_fma_f32 v[236:237], v[152:153], v[152:153], v[236:237]
	v_pk_fma_f32 v[236:237], v[154:155], v[154:155], v[236:237]
	v_pk_fma_f32 v[236:237], v[156:157], v[156:157], v[236:237]
	v_pk_fma_f32 v[236:237], v[158:159], v[158:159], v[236:237]
	v_pk_fma_f32 v[236:237], v[160:161], v[160:161], v[236:237]
	v_pk_fma_f32 v[236:237], v[162:163], v[162:163], v[236:237]
	v_pk_mul_f32 v[238:239], v[164:165], v[164:165]
	v_pk_fma_f32 v[238:239], v[166:167], v[166:167], v[238:239]
	v_pk_fma_f32 v[238:239], v[168:169], v[168:169], v[238:239]
	v_pk_fma_f32 v[238:239], v[170:171], v[170:171], v[238:239]
	v_pk_fma_f32 v[238:239], v[172:173], v[172:173], v[238:239]
	v_pk_fma_f32 v[238:239], v[174:175], v[174:175], v[238:239]
	v_pk_fma_f32 v[238:239], v[176:177], v[176:177], v[238:239]
	v_pk_fma_f32 v[238:239], v[178:179], v[178:179], v[238:239]
	v_add_f32_e32 v236, v236, v237
	v_add_f32_e32 v238, v238, v239
	s_nop 1
	v_add_f32_dpp v236, v236, v236 quad_perm:[1,0,3,2] row_mask:0xf bank_mask:0xf
	v_add_f32_dpp v238, v238, v238 quad_perm:[1,0,3,2] row_mask:0xf bank_mask:0xf
	s_nop 1
	v_add_f32_dpp v236, v236, v236 quad_perm:[2,3,0,1] row_mask:0xf bank_mask:0xf
	v_add_f32_dpp v238, v238, v238 quad_perm:[2,3,0,1] row_mask:0xf bank_mask:0xf
	s_nop 1
	v_add_f32_dpp v236, v236, v236 row_half_mirror row_mask:0xf bank_mask:0xf
	v_add_f32_dpp v238, v238, v238 row_half_mirror row_mask:0xf bank_mask:0xf
	s_nop 1
	v_add_f32_dpp v236, v236, v236 row_mirror row_mask:0xf bank_mask:0xf
	v_add_f32_dpp v238, v238, v238 row_mirror row_mask:0xf bank_mask:0xf
	s_nop 1
	v_add_f32_dpp v236, v236, v236 row_bcast:15 row_mask:0xa bank_mask:0xf
	v_add_f32_dpp v238, v238, v238 row_bcast:15 row_mask:0xa bank_mask:0xf
	s_nop 1
	v_add_f32_dpp v236, v236, v236 row_bcast:31 row_mask:0xc bank_mask:0xf
	v_add_f32_dpp v238, v238, v238 row_bcast:31 row_mask:0xc bank_mask:0xf
	s_nop 1
	v_readlane_b32 s2, v236, 63
	v_readlane_b32 s3, v238, 63
	s_nop 1
	v_mov_b32_e32 v240, s2
	v_mov_b32_e32 v242, s3
	v_fmamk_f32 v240, v240, 0x3a800000, v196
	v_fmamk_f32 v242, v242, 0x3a800000, v196
	v_rsq_f32_e32 v240, v240
	v_rsq_f32_e32 v242, v242
	s_nop 0
	v_pk_mul_f32 v[148:149], v[148:149], v[240:241] op_sel_hi:[1,0]
	v_pk_mul_f32 v[150:151], v[150:151], v[240:241] op_sel_hi:[1,0]
	v_pk_mul_f32 v[152:153], v[152:153], v[240:241] op_sel_hi:[1,0]
	v_pk_mul_f32 v[154:155], v[154:155], v[240:241] op_sel_hi:[1,0]
	v_pk_mul_f32 v[156:157], v[156:157], v[240:241] op_sel_hi:[1,0]
	v_pk_mul_f32 v[158:159], v[158:159], v[240:241] op_sel_hi:[1,0]
	v_pk_mul_f32 v[160:161], v[160:161], v[240:241] op_sel_hi:[1,0]
	v_pk_mul_f32 v[162:163], v[162:163], v[240:241] op_sel_hi:[1,0]
	v_pk_mul_f32 v[148:149], v[148:149], v[202:203]
	v_pk_mul_f32 v[150:151], v[150:151], v[204:205]
	v_pk_mul_f32 v[152:153], v[152:153], v[206:207]
	v_pk_mul_f32 v[154:155], v[154:155], v[208:209]
	v_pk_mul_f32 v[156:157], v[156:157], v[210:211]
	v_pk_mul_f32 v[158:159], v[158:159], v[212:213]
	v_pk_mul_f32 v[160:161], v[160:161], v[214:215]
	v_pk_mul_f32 v[162:163], v[162:163], v[216:217]
	v_cvt_pk_bf16_f32 v148, v148, v149
	v_cvt_pk_bf16_f32 v149, v150, v151
	v_cvt_pk_bf16_f32 v150, v152, v153
	v_cvt_pk_bf16_f32 v151, v154, v155
	v_cvt_pk_bf16_f32 v152, v156, v157
	v_cvt_pk_bf16_f32 v153, v158, v159
	v_cvt_pk_bf16_f32 v154, v160, v161
	v_cvt_pk_bf16_f32 v155, v162, v163
	s_add_u32 s26, s14, 0x3000000
	s_addc_u32 s27, s15, 0
	global_store_dwordx2 v245, v[148:149], s[26:27] offset:0
	global_store_dwordx2 v245, v[150:151], s[26:27] offset:512
	global_store_dwordx2 v245, v[152:153], s[26:27] offset:1024
	global_store_dwordx2 v245, v[154:155], s[26:27] offset:1536
	v_pk_mul_f32 v[164:165], v[164:165], v[242:243] op_sel_hi:[1,0]
	v_pk_mul_f32 v[166:167], v[166:167], v[242:243] op_sel_hi:[1,0]
	v_pk_mul_f32 v[168:169], v[168:169], v[242:243] op_sel_hi:[1,0]
	v_pk_mul_f32 v[170:171], v[170:171], v[242:243] op_sel_hi:[1,0]
	v_pk_mul_f32 v[172:173], v[172:173], v[242:243] op_sel_hi:[1,0]
	v_pk_mul_f32 v[174:175], v[174:175], v[242:243] op_sel_hi:[1,0]
	v_pk_mul_f32 v[176:177], v[176:177], v[242:243] op_sel_hi:[1,0]
	v_pk_mul_f32 v[178:179], v[178:179], v[242:243] op_sel_hi:[1,0]
	v_pk_mul_f32 v[164:165], v[164:165], v[202:203]
	v_pk_mul_f32 v[166:167], v[166:167], v[204:205]
	v_pk_mul_f32 v[168:169], v[168:169], v[206:207]
	v_pk_mul_f32 v[170:171], v[170:171], v[208:209]
	v_pk_mul_f32 v[172:173], v[172:173], v[210:211]
	v_pk_mul_f32 v[174:175], v[174:175], v[212:213]
	v_pk_mul_f32 v[176:177], v[176:177], v[214:215]
	v_pk_mul_f32 v[178:179], v[178:179], v[216:217]
	v_cvt_pk_bf16_f32 v164, v164, v165
	v_cvt_pk_bf16_f32 v165, v166, v167
	v_cvt_pk_bf16_f32 v166, v168, v169
	v_cvt_pk_bf16_f32 v167, v170, v171
	v_cvt_pk_bf16_f32 v168, v172, v173
	v_cvt_pk_bf16_f32 v169, v174, v175
	v_cvt_pk_bf16_f32 v170, v176, v177
	v_cvt_pk_bf16_f32 v171, v178, v179
	s_add_u32 s26, s14, 0x3400000
	s_addc_u32 s27, s15, 0
	global_store_dwordx2 v245, v[164:165], s[26:27] offset:0
	global_store_dwordx2 v245, v[166:167], s[26:27] offset:512
	global_store_dwordx2 v245, v[168:169], s[26:27] offset:1024
	global_store_dwordx2 v245, v[170:171], s[26:27] offset:1536
	s_waitcnt vmcnt(24)
	v_lshlrev_b32_e32 v148, 16, v52
	v_and_b32_e32 v149, 0xffff0000, v52
	v_lshlrev_b32_e32 v150, 16, v53
	v_and_b32_e32 v151, 0xffff0000, v53
	v_lshlrev_b32_e32 v152, 16, v54
	v_and_b32_e32 v153, 0xffff0000, v54
	v_lshlrev_b32_e32 v154, 16, v55
	v_and_b32_e32 v155, 0xffff0000, v55
	v_lshlrev_b32_e32 v156, 16, v56
	v_and_b32_e32 v157, 0xffff0000, v56
	v_lshlrev_b32_e32 v158, 16, v57
	v_and_b32_e32 v159, 0xffff0000, v57
	v_lshlrev_b32_e32 v160, 16, v58
	v_and_b32_e32 v161, 0xffff0000, v58
	v_lshlrev_b32_e32 v162, 16, v59
	v_and_b32_e32 v163, 0xffff0000, v59
	s_waitcnt vmcnt(16)
	v_lshlrev_b32_e32 v164, 16, v76
	v_and_b32_e32 v165, 0xffff0000, v76
	v_lshlrev_b32_e32 v166, 16, v77
	v_and_b32_e32 v167, 0xffff0000, v77
	v_lshlrev_b32_e32 v168, 16, v78
	v_and_b32_e32 v169, 0xffff0000, v78
	v_lshlrev_b32_e32 v170, 16, v79
	v_and_b32_e32 v171, 0xffff0000, v79
	v_lshlrev_b32_e32 v172, 16, v80
	v_and_b32_e32 v173, 0xffff0000, v80
	v_lshlrev_b32_e32 v174, 16, v81
	v_and_b32_e32 v175, 0xffff0000, v81
	v_lshlrev_b32_e32 v176, 16, v82
	v_and_b32_e32 v177, 0xffff0000, v82
	v_lshlrev_b32_e32 v178, 16, v83
	v_and_b32_e32 v179, 0xffff0000, v83
	v_pk_mul_f32 v[236:237], v[148:149], v[148:149]
	v_pk_fma_f32 v[236:237], v[150:151], v[150:151], v[236:237]
	v_pk_fma_f32 v[236:237], v[152:153], v[152:153], v[236:237]
	v_pk_fma_f32 v[236:237], v[154:155], v[154:155], v[236:237]
	v_pk_fma_f32 v[236:237], v[156:157], v[156:157], v[236:237]
	v_pk_fma_f32 v[236:237], v[158:159], v[158:159], v[236:237]
	v_pk_fma_f32 v[236:237], v[160:161], v[160:161], v[236:237]
	v_pk_fma_f32 v[236:237], v[162:163], v[162:163], v[236:237]
	v_pk_mul_f32 v[238:239], v[164:165], v[164:165]
	v_pk_fma_f32 v[238:239], v[166:167], v[166:167], v[238:239]
	v_pk_fma_f32 v[238:239], v[168:169], v[168:169], v[238:239]
	v_pk_fma_f32 v[238:239], v[170:171], v[170:171], v[238:239]
	v_pk_fma_f32 v[238:239], v[172:173], v[172:173], v[238:239]
	v_pk_fma_f32 v[238:239], v[174:175], v[174:175], v[238:239]
	v_pk_fma_f32 v[238:239], v[176:177], v[176:177], v[238:239]
	v_pk_fma_f32 v[238:239], v[178:179], v[178:179], v[238:239]
	v_add_f32_e32 v236, v236, v237
	v_add_f32_e32 v238, v238, v239
	s_nop 1
	v_add_f32_dpp v236, v236, v236 quad_perm:[1,0,3,2] row_mask:0xf bank_mask:0xf
	v_add_f32_dpp v238, v238, v238 quad_perm:[1,0,3,2] row_mask:0xf bank_mask:0xf
	s_nop 1
	v_add_f32_dpp v236, v236, v236 quad_perm:[2,3,0,1] row_mask:0xf bank_mask:0xf
	v_add_f32_dpp v238, v238, v238 quad_perm:[2,3,0,1] row_mask:0xf bank_mask:0xf
	s_nop 1
	v_add_f32_dpp v236, v236, v236 row_half_mirror row_mask:0xf bank_mask:0xf
	v_add_f32_dpp v238, v238, v238 row_half_mirror row_mask:0xf bank_mask:0xf
	s_nop 1
	v_add_f32_dpp v236, v236, v236 row_mirror row_mask:0xf bank_mask:0xf
	v_add_f32_dpp v238, v238, v238 row_mirror row_mask:0xf bank_mask:0xf
	s_nop 1
	v_add_f32_dpp v236, v236, v236 row_bcast:15 row_mask:0xa bank_mask:0xf
	v_add_f32_dpp v238, v238, v238 row_bcast:15 row_mask:0xa bank_mask:0xf
	s_nop 1
	v_add_f32_dpp v236, v236, v236 row_bcast:31 row_mask:0xc bank_mask:0xf
	v_add_f32_dpp v238, v238, v238 row_bcast:31 row_mask:0xc bank_mask:0xf
	s_nop 1
	v_readlane_b32 s2, v236, 63
	v_readlane_b32 s3, v238, 63
	s_nop 1
	v_mov_b32_e32 v240, s2
	v_mov_b32_e32 v242, s3
	v_fmamk_f32 v240, v240, 0x3a800000, v196
	v_fmamk_f32 v242, v242, 0x3a800000, v196
	v_rsq_f32_e32 v240, v240
	v_rsq_f32_e32 v242, v242
	s_nop 0
	v_pk_mul_f32 v[148:149], v[148:149], v[240:241] op_sel_hi:[1,0]
	v_pk_mul_f32 v[150:151], v[150:151], v[240:241] op_sel_hi:[1,0]
	v_pk_mul_f32 v[152:153], v[152:153], v[240:241] op_sel_hi:[1,0]
	v_pk_mul_f32 v[154:155], v[154:155], v[240:241] op_sel_hi:[1,0]
	v_pk_mul_f32 v[156:157], v[156:157], v[240:241] op_sel_hi:[1,0]
	v_pk_mul_f32 v[158:159], v[158:159], v[240:241] op_sel_hi:[1,0]
	v_pk_mul_f32 v[160:161], v[160:161], v[240:241] op_sel_hi:[1,0]
	v_pk_mul_f32 v[162:163], v[162:163], v[240:241] op_sel_hi:[1,0]
	v_pk_fma_f32 v[148:149], v[148:149], v[180:181], v[60:61]
	v_pk_fma_f32 v[150:151], v[150:151], v[182:183], v[62:63]
	v_pk_fma_f32 v[152:153], v[152:153], v[184:185], v[64:65]
	v_pk_fma_f32 v[154:155], v[154:155], v[186:187], v[66:67]
	v_pk_fma_f32 v[156:157], v[156:157], v[188:189], v[68:69]
	v_pk_fma_f32 v[158:159], v[158:159], v[190:191], v[70:71]
	v_pk_fma_f32 v[160:161], v[160:161], v[192:193], v[72:73]
	v_pk_fma_f32 v[162:163], v[162:163], v[194:195], v[74:75]
	v_pk_mul_f32 v[164:165], v[164:165], v[242:243] op_sel_hi:[1,0]
	v_pk_mul_f32 v[166:167], v[166:167], v[242:243] op_sel_hi:[1,0]
	v_pk_mul_f32 v[168:169], v[168:169], v[242:243] op_sel_hi:[1,0]
	v_pk_mul_f32 v[170:171], v[170:171], v[242:243] op_sel_hi:[1,0]
	v_pk_mul_f32 v[172:173], v[172:173], v[242:243] op_sel_hi:[1,0]
	v_pk_mul_f32 v[174:175], v[174:175], v[242:243] op_sel_hi:[1,0]
	v_pk_mul_f32 v[176:177], v[176:177], v[242:243] op_sel_hi:[1,0]
	v_pk_mul_f32 v[178:179], v[178:179], v[242:243] op_sel_hi:[1,0]
	v_pk_fma_f32 v[164:165], v[164:165], v[180:181], v[84:85]
	v_pk_fma_f32 v[166:167], v[166:167], v[182:183], v[86:87]
	v_pk_fma_f32 v[168:169], v[168:169], v[184:185], v[88:89]
	v_pk_fma_f32 v[170:171], v[170:171], v[186:187], v[90:91]
	v_pk_fma_f32 v[172:173], v[172:173], v[188:189], v[92:93]
	v_pk_fma_f32 v[174:175], v[174:175], v[190:191], v[94:95]
	v_pk_fma_f32 v[176:177], v[176:177], v[192:193], v[96:97]
	v_pk_fma_f32 v[178:179], v[178:179], v[194:195], v[98:99]
	v_pk_mul_f32 v[236:237], v[148:149], v[148:149]
	v_pk_fma_f32 v[236:237], v[150:151], v[150:151], v[236:237]
	v_pk_fma_f32 v[236:237], v[152:153], v[152:153], v[236:237]
	v_pk_fma_f32 v[236:237], v[154:155], v[154:155], v[236:237]
	v_pk_fma_f32 v[236:237], v[156:157], v[156:157], v[236:237]
	v_pk_fma_f32 v[236:237], v[158:159], v[158:159], v[236:237]
	v_pk_fma_f32 v[236:237], v[160:161], v[160:161], v[236:237]
	v_pk_fma_f32 v[236:237], v[162:163], v[162:163], v[236:237]
	v_pk_mul_f32 v[238:239], v[164:165], v[164:165]
	v_pk_fma_f32 v[238:239], v[166:167], v[166:167], v[238:239]
	v_pk_fma_f32 v[238:239], v[168:169], v[168:169], v[238:239]
	v_pk_fma_f32 v[238:239], v[170:171], v[170:171], v[238:239]
	v_pk_fma_f32 v[238:239], v[172:173], v[172:173], v[238:239]
	v_pk_fma_f32 v[238:239], v[174:175], v[174:175], v[238:239]
	v_pk_fma_f32 v[238:239], v[176:177], v[176:177], v[238:239]
	v_pk_fma_f32 v[238:239], v[178:179], v[178:179], v[238:239]
	v_add_f32_e32 v236, v236, v237
	v_add_f32_e32 v238, v238, v239
	s_nop 1
	v_add_f32_dpp v236, v236, v236 quad_perm:[1,0,3,2] row_mask:0xf bank_mask:0xf
	v_add_f32_dpp v238, v238, v238 quad_perm:[1,0,3,2] row_mask:0xf bank_mask:0xf
	s_nop 1
	v_add_f32_dpp v236, v236, v236 quad_perm:[2,3,0,1] row_mask:0xf bank_mask:0xf
	v_add_f32_dpp v238, v238, v238 quad_perm:[2,3,0,1] row_mask:0xf bank_mask:0xf
	s_nop 1
	v_add_f32_dpp v236, v236, v236 row_half_mirror row_mask:0xf bank_mask:0xf
	v_add_f32_dpp v238, v238, v238 row_half_mirror row_mask:0xf bank_mask:0xf
	s_nop 1
	v_add_f32_dpp v236, v236, v236 row_mirror row_mask:0xf bank_mask:0xf
	v_add_f32_dpp v238, v238, v238 row_mirror row_mask:0xf bank_mask:0xf
	s_nop 1
	v_add_f32_dpp v236, v236, v236 row_bcast:15 row_mask:0xa bank_mask:0xf
	v_add_f32_dpp v238, v238, v238 row_bcast:15 row_mask:0xa bank_mask:0xf
	s_nop 1
	v_add_f32_dpp v236, v236, v236 row_bcast:31 row_mask:0xc bank_mask:0xf
	v_add_f32_dpp v238, v238, v238 row_bcast:31 row_mask:0xc bank_mask:0xf
	s_nop 1
	v_readlane_b32 s2, v236, 63
	v_readlane_b32 s3, v238, 63
	s_nop 1
	v_mov_b32_e32 v240, s2
	v_mov_b32_e32 v242, s3
	v_fmamk_f32 v240, v240, 0x3a800000, v196
	v_fmamk_f32 v242, v242, 0x3a800000, v196
	v_rsq_f32_e32 v240, v240
	v_rsq_f32_e32 v242, v242
	s_nop 0
	v_pk_mul_f32 v[148:149], v[148:149], v[240:241] op_sel_hi:[1,0]
	v_pk_mul_f32 v[150:151], v[150:151], v[240:241] op_sel_hi:[1,0]
	v_pk_mul_f32 v[152:153], v[152:153], v[240:241] op_sel_hi:[1,0]
	v_pk_mul_f32 v[154:155], v[154:155], v[240:241] op_sel_hi:[1,0]
	v_pk_mul_f32 v[156:157], v[156:157], v[240:241] op_sel_hi:[1,0]
	v_pk_mul_f32 v[158:159], v[158:159], v[240:241] op_sel_hi:[1,0]
	v_pk_mul_f32 v[160:161], v[160:161], v[240:241] op_sel_hi:[1,0]
	v_pk_mul_f32 v[162:163], v[162:163], v[240:241] op_sel_hi:[1,0]
	v_pk_mul_f32 v[148:149], v[148:149], v[202:203]
	v_pk_mul_f32 v[150:151], v[150:151], v[204:205]
	v_pk_mul_f32 v[152:153], v[152:153], v[206:207]
	v_pk_mul_f32 v[154:155], v[154:155], v[208:209]
	v_pk_mul_f32 v[156:157], v[156:157], v[210:211]
	v_pk_mul_f32 v[158:159], v[158:159], v[212:213]
	v_pk_mul_f32 v[160:161], v[160:161], v[214:215]
	v_pk_mul_f32 v[162:163], v[162:163], v[216:217]
	v_cvt_pk_bf16_f32 v148, v148, v149
	v_cvt_pk_bf16_f32 v149, v150, v151
	v_cvt_pk_bf16_f32 v150, v152, v153
	v_cvt_pk_bf16_f32 v151, v154, v155
	v_cvt_pk_bf16_f32 v152, v156, v157
	v_cvt_pk_bf16_f32 v153, v158, v159
	v_cvt_pk_bf16_f32 v154, v160, v161
	v_cvt_pk_bf16_f32 v155, v162, v163
	s_add_u32 s26, s14, 0x3800000
	s_addc_u32 s27, s15, 0
	global_store_dwordx2 v245, v[148:149], s[26:27] offset:0
	global_store_dwordx2 v245, v[150:151], s[26:27] offset:512
	global_store_dwordx2 v245, v[152:153], s[26:27] offset:1024
	global_store_dwordx2 v245, v[154:155], s[26:27] offset:1536
	v_pk_mul_f32 v[164:165], v[164:165], v[242:243] op_sel_hi:[1,0]
	v_pk_mul_f32 v[166:167], v[166:167], v[242:243] op_sel_hi:[1,0]
	v_pk_mul_f32 v[168:169], v[168:169], v[242:243] op_sel_hi:[1,0]
	v_pk_mul_f32 v[170:171], v[170:171], v[242:243] op_sel_hi:[1,0]
	v_pk_mul_f32 v[172:173], v[172:173], v[242:243] op_sel_hi:[1,0]
	v_pk_mul_f32 v[174:175], v[174:175], v[242:243] op_sel_hi:[1,0]
	v_pk_mul_f32 v[176:177], v[176:177], v[242:243] op_sel_hi:[1,0]
	v_pk_mul_f32 v[178:179], v[178:179], v[242:243] op_sel_hi:[1,0]
	v_pk_mul_f32 v[164:165], v[164:165], v[202:203]
	v_pk_mul_f32 v[166:167], v[166:167], v[204:205]
	v_pk_mul_f32 v[168:169], v[168:169], v[206:207]
	v_pk_mul_f32 v[170:171], v[170:171], v[208:209]
	v_pk_mul_f32 v[172:173], v[172:173], v[210:211]
	v_pk_mul_f32 v[174:175], v[174:175], v[212:213]
	v_pk_mul_f32 v[176:177], v[176:177], v[214:215]
	v_pk_mul_f32 v[178:179], v[178:179], v[216:217]
	v_cvt_pk_bf16_f32 v164, v164, v165
	v_cvt_pk_bf16_f32 v165, v166, v167
	v_cvt_pk_bf16_f32 v166, v168, v169
	v_cvt_pk_bf16_f32 v167, v170, v171
	v_cvt_pk_bf16_f32 v168, v172, v173
	v_cvt_pk_bf16_f32 v169, v174, v175
	v_cvt_pk_bf16_f32 v170, v176, v177
	v_cvt_pk_bf16_f32 v171, v178, v179
	s_add_u32 s26, s14, 0x3c00000
	s_addc_u32 s27, s15, 0
	global_store_dwordx2 v245, v[164:165], s[26:27] offset:0
	global_store_dwordx2 v245, v[166:167], s[26:27] offset:512
	global_store_dwordx2 v245, v[168:169], s[26:27] offset:1024
	global_store_dwordx2 v245, v[170:171], s[26:27] offset:1536
	s_cmpk_ge_u32 s1, 0x100
	s_cbranch_scc1 .Lrow6_done
	s_cmpk_ge_u32 s1, 16
	s_cbranch_scc1 .Lrow6_zero
	s_mov_b64 s[22:23], s[16:17]
	s_mov_b64 s[24:25], s[18:19]
	global_load_dwordx2 v[4:5], v245, s[22:23] offset:0 nt
	global_load_dwordx2 v[6:7], v245, s[22:23] offset:512 nt
	global_load_dwordx2 v[8:9], v245, s[22:23] offset:1024 nt
	global_load_dwordx2 v[10:11], v245, s[22:23] offset:1536 nt
	global_load_dwordx4 v[12:15], v244, s[24:25] offset:0 nt
	global_load_dwordx4 v[16:19], v244, s[24:25] offset:1024 nt
	global_load_dwordx4 v[20:23], v244, s[24:25] offset:2048 nt
	global_load_dwordx4 v[24:27], v244, s[24:25] offset:3072 nt
	s_waitcnt vmcnt(0)
	v_lshlrev_b32_e32 v148, 16, v4
	v_and_b32_e32 v149, 0xffff0000, v4
	v_lshlrev_b32_e32 v150, 16, v5
	v_and_b32_e32 v151, 0xffff0000, v5
	v_lshlrev_b32_e32 v152, 16, v6
	v_and_b32_e32 v153, 0xffff0000, v6
	v_lshlrev_b32_e32 v154, 16, v7
	v_and_b32_e32 v155, 0xffff0000, v7
	v_lshlrev_b32_e32 v156, 16, v8
	v_and_b32_e32 v157, 0xffff0000, v8
	v_lshlrev_b32_e32 v158, 16, v9
	v_and_b32_e32 v159, 0xffff0000, v9
	v_lshlrev_b32_e32 v160, 16, v10
	v_and_b32_e32 v161, 0xffff0000, v10
	v_lshlrev_b32_e32 v162, 16, v11
	v_and_b32_e32 v163, 0xffff0000, v11
	v_pk_mul_f32 v[236:237], v[148:149], v[148:149]
	v_pk_fma_f32 v[236:237], v[150:151], v[150:151], v[236:237]
	v_pk_fma_f32 v[236:237], v[152:153], v[152:153], v[236:237]
	v_pk_fma_f32 v[236:237], v[154:155], v[154:155], v[236:237]
	v_pk_fma_f32 v[236:237], v[156:157], v[156:157], v[236:237]
	v_pk_fma_f32 v[236:237], v[158:159], v[158:159], v[236:237]
	v_pk_fma_f32 v[236:237], v[160:161], v[160:161], v[236:237]
	v_pk_fma_f32 v[236:237], v[162:163], v[162:163], v[236:237]
	v_add_f32_e32 v236, v236, v237
	s_nop 1
	v_add_f32_dpp v236, v236, v236 quad_perm:[1,0,3,2] row_mask:0xf bank_mask:0xf
	s_nop 1
	v_add_f32_dpp v236, v236, v236 quad_perm:[2,3,0,1] row_mask:0xf bank_mask:0xf
	s_nop 1
	v_add_f32_dpp v236, v236, v236 row_half_mirror row_mask:0xf bank_mask:0xf
	s_nop 1
	v_add_f32_dpp v236, v236, v236 row_mirror row_mask:0xf bank_mask:0xf
	s_nop 1
	v_add_f32_dpp v236, v236, v236 row_bcast:15 row_mask:0xa bank_mask:0xf
	s_nop 1
	v_add_f32_dpp v236, v236, v236 row_bcast:31 row_mask:0xc bank_mask:0xf
	s_nop 1
	v_readlane_b32 s2, v236, 63
	s_nop 1
	v_mov_b32_e32 v240, s2
	v_fmamk_f32 v240, v240, 0x3a800000, v196
	v_rsq_f32_e32 v240, v240
	s_nop 0
	v_pk_mul_f32 v[148:149], v[148:149], v[240:241] op_sel_hi:[1,0]
	v_pk_mul_f32 v[150:151], v[150:151], v[240:241] op_sel_hi:[1,0]
	v_pk_mul_f32 v[152:153], v[152:153], v[240:241] op_sel_hi:[1,0]
	v_pk_mul_f32 v[154:155], v[154:155], v[240:241] op_sel_hi:[1,0]
	v_pk_mul_f32 v[156:157], v[156:157], v[240:241] op_sel_hi:[1,0]
	v_pk_mul_f32 v[158:159], v[158:159], v[240:241] op_sel_hi:[1,0]
	v_pk_mul_f32 v[160:161], v[160:161], v[240:241] op_sel_hi:[1,0]
	v_pk_mul_f32 v[162:163], v[162:163], v[240:241] op_sel_hi:[1,0]
	v_pk_fma_f32 v[148:149], v[148:149], v[180:181], v[12:13]
	v_pk_fma_f32 v[150:151], v[150:151], v[182:183], v[14:15]
	v_pk_fma_f32 v[152:153], v[152:153], v[184:185], v[16:17]
	v_pk_fma_f32 v[154:155], v[154:155], v[186:187], v[18:19]
	v_pk_fma_f32 v[156:157], v[156:157], v[188:189], v[20:21]
	v_pk_fma_f32 v[158:159], v[158:159], v[190:191], v[22:23]
	v_pk_fma_f32 v[160:161], v[160:161], v[192:193], v[24:25]
	v_pk_fma_f32 v[162:163], v[162:163], v[194:195], v[26:27]
	v_pk_mul_f32 v[236:237], v[148:149], v[148:149]
	v_pk_fma_f32 v[236:237], v[150:151], v[150:151], v[236:237]
	v_pk_fma_f32 v[236:237], v[152:153], v[152:153], v[236:237]
	v_pk_fma_f32 v[236:237], v[154:155], v[154:155], v[236:237]
	v_pk_fma_f32 v[236:237], v[156:157], v[156:157], v[236:237]
	v_pk_fma_f32 v[236:237], v[158:159], v[158:159], v[236:237]
	v_pk_fma_f32 v[236:237], v[160:161], v[160:161], v[236:237]
	v_pk_fma_f32 v[236:237], v[162:163], v[162:163], v[236:237]
	v_add_f32_e32 v236, v236, v237
	s_nop 1
	v_add_f32_dpp v236, v236, v236 quad_perm:[1,0,3,2] row_mask:0xf bank_mask:0xf
	s_nop 1
	v_add_f32_dpp v236, v236, v236 quad_perm:[2,3,0,1] row_mask:0xf bank_mask:0xf
	s_nop 1
	v_add_f32_dpp v236, v236, v236 row_half_mirror row_mask:0xf bank_mask:0xf
	s_nop 1
	v_add_f32_dpp v236, v236, v236 row_mirror row_mask:0xf bank_mask:0xf
	s_nop 1
	v_add_f32_dpp v236, v236, v236 row_bcast:15 row_mask:0xa bank_mask:0xf
	s_nop 1
	v_add_f32_dpp v236, v236, v236 row_bcast:31 row_mask:0xc bank_mask:0xf
	s_nop 1
	v_readlane_b32 s2, v236, 63
	s_nop 1
	v_mov_b32_e32 v240, s2
	v_fmamk_f32 v240, v240, 0x3a800000, v196
	v_rsq_f32_e32 v240, v240
	s_nop 0
	v_pk_mul_f32 v[148:149], v[148:149], v[240:241] op_sel_hi:[1,0]
	v_pk_mul_f32 v[150:151], v[150:151], v[240:241] op_sel_hi:[1,0]
	v_pk_mul_f32 v[152:153], v[152:153], v[240:241] op_sel_hi:[1,0]
	v_pk_mul_f32 v[154:155], v[154:155], v[240:241] op_sel_hi:[1,0]
	v_pk_mul_f32 v[156:157], v[156:157], v[240:241] op_sel_hi:[1,0]
	v_pk_mul_f32 v[158:159], v[158:159], v[240:241] op_sel_hi:[1,0]
	v_pk_mul_f32 v[160:161], v[160:161], v[240:241] op_sel_hi:[1,0]
	v_pk_mul_f32 v[162:163], v[162:163], v[240:241] op_sel_hi:[1,0]
	v_pk_mul_f32 v[148:149], v[148:149], v[202:203]
	v_pk_mul_f32 v[150:151], v[150:151], v[204:205]
	v_pk_mul_f32 v[152:153], v[152:153], v[206:207]
	v_pk_mul_f32 v[154:155], v[154:155], v[208:209]
	v_pk_mul_f32 v[156:157], v[156:157], v[210:211]
	v_pk_mul_f32 v[158:159], v[158:159], v[212:213]
	v_pk_mul_f32 v[160:161], v[160:161], v[214:215]
	v_pk_mul_f32 v[162:163], v[162:163], v[216:217]
	v_cvt_pk_bf16_f32 v148, v148, v149
	v_cvt_pk_bf16_f32 v149, v150, v151
	v_cvt_pk_bf16_f32 v150, v152, v153
	v_cvt_pk_bf16_f32 v151, v154, v155
	v_cvt_pk_bf16_f32 v152, v156, v157
	v_cvt_pk_bf16_f32 v153, v158, v159
	v_cvt_pk_bf16_f32 v154, v160, v161
	v_cvt_pk_bf16_f32 v155, v162, v163
	s_mov_b64 s[26:27], s[20:21]
	global_store_dwordx2 v245, v[148:149], s[26:27] offset:0
	global_store_dwordx2 v245, v[150:151], s[26:27] offset:512
	global_store_dwordx2 v245, v[152:153], s[26:27] offset:1024
	global_store_dwordx2 v245, v[154:155], s[26:27] offset:1536
	s_branch .Lrow6_done
.Lrow6_zero:
	v_mov_b32_e32 v4, 0
	v_mov_b32_e32 v5, 0
	global_store_dwordx2 v245, v[4:5], s[20:21] offset:0
	global_store_dwordx2 v245, v[4:5], s[20:21] offset:512
	global_store_dwordx2 v245, v[4:5], s[20:21] offset:1024
	global_store_dwordx2 v245, v[4:5], s[20:21] offset:1536
.Lrow6_done:
	s_mov_b64 s[2:3], exec
	s_branch .LBB0_112
.Lrow6_generic:
	s_waitcnt vmcnt(0)
	v_mov_b32_e32 v37, v197
	s_mov_b32 s0, s70
	s_lshl_b32 s0, s0, 3
	v_ashrrev_i32_e32 v36, 6, v37
	v_add_u32_e32 v138, s0, v36
	s_mov_b32 s1, 0x8100
	v_cmp_gt_i32_e32 vcc, s1, v138
	s_and_saveexec_b64 s[2:3], vcc
	s_cbranch_execz .LBB0_112
	v_lshlrev_b32_e32 v0, 2, v37
	v_and_b32_e32 v38, 0xfc, v0
	v_readlane_b32 s36, v252, 56
	v_lshlrev_b32_e32 v0, 2, v38
	v_readlane_b32 s50, v253, 6
	v_readlane_b32 s51, v253, 7
	v_readlane_b32 s48, v253, 4
	v_readlane_b32 s49, v253, 5
	s_nop 2
	global_load_dwordx4 v[4:7], v0, s[50:51] offset:3072
	s_nop 0
	global_load_dwordx4 v[8:11], v0, s[48:49] offset:3072
	global_load_dwordx4 v[12:15], v0, s[50:51] offset:2048
	global_load_dwordx4 v[16:19], v0, s[48:49] offset:2048
	global_load_dwordx4 v[20:23], v0, s[50:51] offset:1024
	global_load_dwordx4 v[24:27], v0, s[48:49] offset:1024
	global_load_dwordx4 v[28:31], v0, s[50:51]
	global_load_dwordx4 v[32:35], v0, s[48:49]
	v_cmp_lt_i32_e32 vcc, v224, v220
	s_load_dword s36, s[80:81], 0x0
	v_readlane_b32 s20, v252, 12
	v_cndmask_b32_e32 v0, v218, v224, vcc
	v_cmp_lt_i32_e32 vcc, v219, v220
	v_lshlrev_b32_e32 v139, 2, v0
	v_lshlrev_b32_e32 v2, 1, v38
	v_cndmask_b32_e32 v0, v218, v219, vcc
	v_cmp_lt_i32_e32 vcc, v235, v220
	v_lshlrev_b32_e32 v140, 2, v0
	v_readlane_b32 s21, v252, 13
	v_cndmask_b32_e32 v0, v218, v235, vcc
	v_lshlrev_b32_e32 v141, 2, v0
	v_xor_b32_e32 v0, 8, v218
	v_cmp_lt_i32_e32 vcc, v0, v220
	s_waitcnt lgkmcnt(0)
	s_lshl_b32 s30, s36, 3
	v_readlane_b32 s46, v253, 2
	v_cndmask_b32_e32 v0, v218, v0, vcc
	v_cmp_lt_i32_e32 vcc, v225, v220
	v_lshlrev_b32_e32 v142, 2, v0
	v_add_u32_e32 v40, s30, v138
	v_cndmask_b32_e32 v0, v218, v225, vcc
	v_cmp_lt_i32_e32 vcc, v226, v220
	v_lshlrev_b32_e32 v143, 2, v0
	s_ashr_i32 s1, s0, 31
	v_cndmask_b32_e32 v0, v218, v226, vcc
	v_lshlrev_b32_e32 v144, 2, v0
	v_lshl_add_u64 v[0:1], s[20:21], 0, v[2:3]
	v_readlane_b32 s20, v252, 10
	v_readlane_b32 s21, v252, 11
	v_readlane_b32 s47, v253, 3
	s_lshl_b32 s46, s36, 5
	v_lshl_add_u64 v[84:85], s[20:21], 0, v[2:3]
	v_and_b32_e32 v2, 63, v37
	v_ashrrev_i32_e32 v37, 31, v36
	v_ashrrev_i32_e32 v41, 31, v40
	v_lshl_add_u64 v[36:37], v[36:37], 0, s[0:1]
	v_readlane_b32 s0, v254, 24
	v_lshlrev_b64 v[40:41], 11, v[40:41]
	s_ashr_i32 s47, s46, 31
	v_lshlrev_b64 v[36:37], 11, v[36:37]
	v_readlane_b32 s1, v254, 25
	v_lshlrev_b32_e32 v86, 3, v2
	v_mov_b32_e32 v87, v3
	v_lshl_add_u64 v[88:89], s[92:93], 0, v[40:41]
	s_lshl_b64 s[48:49], s[46:47], 11
	v_lshl_add_u64 v[90:91], s[0:1], 0, v[36:37]
	s_lshl_b32 s31, s36, 4
	s_mul_i32 s36, s36, 24
	s_mov_b64 s[50:51], 0
	v_lshlrev_b32_e32 v92, 2, v38
	v_readlane_b32 s37, v252, 57
	v_readlane_b32 s38, v252, 58
	v_readlane_b32 s39, v252, 59
	v_readlane_b32 s40, v252, 60
	v_readlane_b32 s41, v252, 61
	v_readlane_b32 s42, v252, 62
	v_readlane_b32 s43, v252, 63
	v_readlane_b32 s44, v253, 0
	v_readlane_b32 s45, v253, 1
	s_branch .LBB0_99

.LBB0_427:
	s_add_u32 s23, s0, 0xfffc0080
	s_addc_u32 s24, s1, -1
	s_add_i32 s25, 0, 0x10000
	v_add_u32_e32 v2, s25, v187
	ds_read_b128 v[132:135], v2
	ds_read_b128 v[136:139], v2 offset:1024
	ds_read_b128 v[140:143], v2 offset:2048
	ds_read_b128 v[144:147], v2 offset:3072
	s_cmp_eq_u32 s22, 12
	s_cselect_b32 s47, s57, s24
	s_cselect_b32 s46, s56, s23
	s_cselect_b32 s45, s59, s21
	s_cselect_b32 s44, s58, s20
	v_lshl_add_u64 v[208:209], s[0:1], 0, v[194:195]
	s_add_i32 m0, s74, 0xc000
	ds_read_b128 v[148:151], v240
	ds_read_b128 v[152:155], v240 offset:1024
	ds_read_b128 v[156:159], v240 offset:2048
	ds_read_b128 v[160:163], v240 offset:3072
	ds_read_b128 v[164:167], v240 offset:4096
	ds_read_b128 v[168:171], v240 offset:5120
	ds_read_b128 v[172:175], v240 offset:6144
	ds_read_b128 v[204:207], v240 offset:7168
	global_load_lds_dwordx4 v[208:209], off
	v_lshl_add_u64 v[208:209], s[0:1], 0, v[202:203]
	s_add_i32 m0, s74, 0xe000
	s_nop 0
	global_load_lds_dwordx4 v[208:209], off
	s_waitcnt lgkmcnt(8)
	s_barrier
	s_waitcnt lgkmcnt(0)
	s_setprio 1
	s_waitcnt lgkmcnt(0)
	v_mfma_f32_16x16x32_bf16 v[128:131], v[132:135], v[148:151], v[128:131]
	v_mfma_f32_16x16x32_bf16 v[124:127], v[140:143], v[148:151], v[124:127]
	v_mfma_f32_16x16x32_bf16 v[120:123], v[132:135], v[156:159], v[120:123]
	v_mfma_f32_16x16x32_bf16 v[116:119], v[140:143], v[156:159], v[116:119]
	v_mfma_f32_16x16x32_bf16 v[112:115], v[132:135], v[164:167], v[112:115]
	v_mfma_f32_16x16x32_bf16 v[108:111], v[140:143], v[164:167], v[108:111]
	v_mfma_f32_16x16x32_bf16 v[104:107], v[132:135], v[172:175], v[104:107]
	v_mfma_f32_16x16x32_bf16 v[100:103], v[140:143], v[172:175], v[100:103]
	v_mfma_f32_16x16x32_bf16 v[128:131], v[136:139], v[152:155], v[128:131]
	v_mfma_f32_16x16x32_bf16 v[124:127], v[144:147], v[152:155], v[124:127]
	v_mfma_f32_16x16x32_bf16 v[120:123], v[136:139], v[160:163], v[120:123]
	v_mfma_f32_16x16x32_bf16 v[116:119], v[144:147], v[160:163], v[116:119]
	v_mfma_f32_16x16x32_bf16 v[112:115], v[136:139], v[168:171], v[112:115]
	v_mfma_f32_16x16x32_bf16 v[108:111], v[144:147], v[168:171], v[108:111]
	v_mfma_f32_16x16x32_bf16 v[104:107], v[136:139], v[204:207], v[104:107]
	v_mfma_f32_16x16x32_bf16 v[100:103], v[144:147], v[204:207], v[100:103]
	s_setprio 0
	s_barrier
	s_add_i32 s23, 0, 0x14000
	s_add_i32 s24, s25, s67
	v_add_u32_e32 v2, s23, v187
	v_lshl_add_u64 v[250:251], s[44:45], 0, v[176:177]
	s_mov_b32 m0, s24
	ds_read_b128 v[208:211], v2
	ds_read_b128 v[212:215], v2 offset:1024
	ds_read_b128 v[242:245], v2 offset:2048
	ds_read_b128 v[246:249], v2 offset:3072
	global_load_lds_dwordx4 v[250:251], off
	v_lshl_add_u64 v[222:223], s[44:45], 0, v[180:181]
	s_add_i32 m0, s24, 0x2000
	s_nop 0
	global_load_lds_dwordx4 v[222:223], off
	s_barrier
	s_waitcnt lgkmcnt(0)
	s_setprio 1
	s_waitcnt lgkmcnt(0)
	v_mfma_f32_16x16x32_bf16 v[64:67], v[208:211], v[148:151], v[64:67]
	v_mfma_f32_16x16x32_bf16 v[60:63], v[242:245], v[148:151], v[60:63]
	v_mfma_f32_16x16x32_bf16 v[56:59], v[208:211], v[156:159], v[56:59]
	v_mfma_f32_16x16x32_bf16 v[52:55], v[242:245], v[156:159], v[52:55]
	v_mfma_f32_16x16x32_bf16 v[48:51], v[208:211], v[164:167], v[48:51]
	v_mfma_f32_16x16x32_bf16 v[44:47], v[242:245], v[164:167], v[44:47]
	v_mfma_f32_16x16x32_bf16 v[40:43], v[208:211], v[172:175], v[40:43]
	v_mfma_f32_16x16x32_bf16 v[36:39], v[242:245], v[172:175], v[36:39]
	v_mfma_f32_16x16x32_bf16 v[64:67], v[212:215], v[152:155], v[64:67]
	v_mfma_f32_16x16x32_bf16 v[60:63], v[246:249], v[152:155], v[60:63]
	v_mfma_f32_16x16x32_bf16 v[56:59], v[212:215], v[160:163], v[56:59]
	v_mfma_f32_16x16x32_bf16 v[52:55], v[246:249], v[160:163], v[52:55]
	v_mfma_f32_16x16x32_bf16 v[48:51], v[212:215], v[168:171], v[48:51]
	v_mfma_f32_16x16x32_bf16 v[44:47], v[246:249], v[168:171], v[44:47]
	v_mfma_f32_16x16x32_bf16 v[40:43], v[212:215], v[204:207], v[40:43]
	v_mfma_f32_16x16x32_bf16 v[36:39], v[246:249], v[204:207], v[36:39]
	s_setprio 0
	s_mov_b32 m0, s74
	v_lshl_add_u64 v[216:217], s[46:47], 0, v[0:1]
	s_barrier
	ds_read_b128 v[148:151], v240 offset:16384
	ds_read_b128 v[152:155], v240 offset:17408
	ds_read_b128 v[156:159], v240 offset:18432
	ds_read_b128 v[160:163], v240 offset:19456
	ds_read_b128 v[164:167], v240 offset:20480
	ds_read_b128 v[168:171], v240 offset:21504
	ds_read_b128 v[172:175], v240 offset:22528
	ds_read_b128 v[204:207], v240 offset:23552
	global_load_lds_dwordx4 v[216:217], off
	v_lshl_add_u64 v[236:237], s[46:47], 0, v[178:179]
	s_mov_b32 m0, s75
	s_nop 0
	global_load_lds_dwordx4 v[236:237], off
	s_barrier
	s_waitcnt lgkmcnt(0)
	s_setprio 1
	s_waitcnt lgkmcnt(0)
	v_mfma_f32_16x16x32_bf16 v[96:99], v[132:135], v[148:151], v[96:99]
	v_mfma_f32_16x16x32_bf16 v[92:95], v[140:143], v[148:151], v[92:95]
	v_mfma_f32_16x16x32_bf16 v[88:91], v[132:135], v[156:159], v[88:91]
	v_mfma_f32_16x16x32_bf16 v[84:87], v[140:143], v[156:159], v[84:87]
	v_mfma_f32_16x16x32_bf16 v[80:83], v[132:135], v[164:167], v[80:83]
	v_mfma_f32_16x16x32_bf16 v[76:79], v[140:143], v[164:167], v[76:79]
	v_mfma_f32_16x16x32_bf16 v[72:75], v[132:135], v[172:175], v[72:75]
	v_mfma_f32_16x16x32_bf16 v[68:71], v[140:143], v[172:175], v[68:71]
	v_mfma_f32_16x16x32_bf16 v[96:99], v[136:139], v[152:155], v[96:99]
	v_mfma_f32_16x16x32_bf16 v[92:95], v[144:147], v[152:155], v[92:95]
	v_mfma_f32_16x16x32_bf16 v[88:91], v[136:139], v[160:163], v[88:91]
	v_mfma_f32_16x16x32_bf16 v[84:87], v[144:147], v[160:163], v[84:87]
	v_mfma_f32_16x16x32_bf16 v[80:83], v[136:139], v[168:171], v[80:83]
	v_mfma_f32_16x16x32_bf16 v[76:79], v[144:147], v[168:171], v[76:79]
	v_mfma_f32_16x16x32_bf16 v[72:75], v[136:139], v[204:207], v[72:75]
	v_mfma_f32_16x16x32_bf16 v[68:71], v[144:147], v[204:207], v[68:71]
	s_setprio 0
	s_barrier
	s_add_u32 s24, s44, 0x40000
	s_addc_u32 s25, s45, 0
	s_add_i32 s23, s23, s67
	v_lshl_add_u64 v[132:133], s[24:25], 0, v[176:177]
	s_mov_b32 m0, s23
	s_nop 0
	global_load_lds_dwordx4 v[132:133], off
	v_lshl_add_u64 v[132:133], s[24:25], 0, v[180:181]
	s_add_i32 m0, s23, 0x2000
	s_nop 0
	global_load_lds_dwordx4 v[132:133], off
	s_waitcnt vmcnt(6)
	s_barrier
	s_setprio 1
	v_mfma_f32_16x16x32_bf16 v[32:35], v[208:211], v[148:151], v[32:35]
	v_mfma_f32_16x16x32_bf16 v[28:31], v[242:245], v[148:151], v[28:31]
	v_mfma_f32_16x16x32_bf16 v[24:27], v[208:211], v[156:159], v[24:27]
	v_mfma_f32_16x16x32_bf16 v[20:23], v[242:245], v[156:159], v[20:23]
	v_mfma_f32_16x16x32_bf16 v[16:19], v[208:211], v[164:167], v[16:19]
	v_mfma_f32_16x16x32_bf16 v[12:15], v[242:245], v[164:167], v[12:15]
	v_mfma_f32_16x16x32_bf16 v[8:11], v[208:211], v[172:175], v[8:11]
	v_mfma_f32_16x16x32_bf16 v[4:7], v[242:245], v[172:175], v[4:7]
	v_mfma_f32_16x16x32_bf16 v[32:35], v[212:215], v[152:155], v[32:35]
	v_mfma_f32_16x16x32_bf16 v[28:31], v[246:249], v[152:155], v[28:31]
	v_mfma_f32_16x16x32_bf16 v[24:27], v[212:215], v[160:163], v[24:27]
	v_mfma_f32_16x16x32_bf16 v[20:23], v[246:249], v[160:163], v[20:23]
	v_mfma_f32_16x16x32_bf16 v[16:19], v[212:215], v[168:171], v[16:19]
	v_mfma_f32_16x16x32_bf16 v[12:15], v[246:249], v[168:171], v[12:15]
	v_mfma_f32_16x16x32_bf16 v[8:11], v[212:215], v[204:207], v[8:11]
	v_mfma_f32_16x16x32_bf16 v[4:7], v[246:249], v[204:207], v[4:7]
	s_setprio 0
	s_add_i32 s23, 0, 0x18000
	v_add_u32_e32 v2, s23, v187
	s_barrier
	ds_read_b128 v[132:135], v2
	ds_read_b128 v[136:139], v2 offset:1024
	ds_read_b128 v[140:143], v2 offset:2048
	ds_read_b128 v[144:147], v2 offset:3072
	s_add_u32 s24, s46, 0x40000
	s_addc_u32 s25, s47, 0
	s_mov_b32 m0, s82
	v_lshl_add_u64 v[208:209], s[24:25], 0, v[0:1]
	ds_read_b128 v[148:151], v240 offset:32768
	ds_read_b128 v[152:155], v240 offset:33792
	ds_read_b128 v[156:159], v240 offset:34816
	ds_read_b128 v[160:163], v240 offset:35840
	ds_read_b128 v[164:167], v240 offset:36864
	ds_read_b128 v[168:171], v240 offset:37888
	ds_read_b128 v[172:175], v240 offset:38912
	ds_read_b128 v[204:207], v240 offset:39936
	global_load_lds_dwordx4 v[208:209], off
	v_lshl_add_u64 v[208:209], s[24:25], 0, v[178:179]
	s_mov_b32 m0, s83
	s_nop 0
	global_load_lds_dwordx4 v[208:209], off
	s_waitcnt lgkmcnt(8)
	s_barrier
	s_waitcnt lgkmcnt(0)
	s_setprio 1
	s_waitcnt lgkmcnt(0)
	v_mfma_f32_16x16x32_bf16 v[128:131], v[132:135], v[148:151], v[128:131]
	v_mfma_f32_16x16x32_bf16 v[124:127], v[140:143], v[148:151], v[124:127]
	v_mfma_f32_16x16x32_bf16 v[120:123], v[132:135], v[156:159], v[120:123]
	v_mfma_f32_16x16x32_bf16 v[116:119], v[140:143], v[156:159], v[116:119]
	v_mfma_f32_16x16x32_bf16 v[112:115], v[132:135], v[164:167], v[112:115]
	v_mfma_f32_16x16x32_bf16 v[108:111], v[140:143], v[164:167], v[108:111]
	v_mfma_f32_16x16x32_bf16 v[104:107], v[132:135], v[172:175], v[104:107]
	v_mfma_f32_16x16x32_bf16 v[100:103], v[140:143], v[172:175], v[100:103]
	v_mfma_f32_16x16x32_bf16 v[128:131], v[136:139], v[152:155], v[128:131]
	v_mfma_f32_16x16x32_bf16 v[124:127], v[144:147], v[152:155], v[124:127]
	v_mfma_f32_16x16x32_bf16 v[120:123], v[136:139], v[160:163], v[120:123]
	v_mfma_f32_16x16x32_bf16 v[116:119], v[144:147], v[160:163], v[116:119]
	v_mfma_f32_16x16x32_bf16 v[112:115], v[136:139], v[168:171], v[112:115]
	v_mfma_f32_16x16x32_bf16 v[108:111], v[144:147], v[168:171], v[108:111]
	v_mfma_f32_16x16x32_bf16 v[104:107], v[136:139], v[204:207], v[104:107]
	v_mfma_f32_16x16x32_bf16 v[100:103], v[144:147], v[204:207], v[100:103]
	s_setprio 0
	s_barrier
	s_add_i32 s26, 0, 0x1c000
	s_add_i32 s23, s23, s67
	v_add_u32_e32 v2, s26, v187
	v_lshl_add_u64 v[250:251], v[250:251], 0, s[76:77]
	s_mov_b32 m0, s23
	ds_read_b128 v[208:211], v2
	ds_read_b128 v[212:215], v2 offset:1024
	ds_read_b128 v[242:245], v2 offset:2048
	ds_read_b128 v[246:249], v2 offset:3072
	global_load_lds_dwordx4 v[250:251], off
	v_lshl_add_u64 v[222:223], v[222:223], 0, s[76:77]
	s_add_i32 m0, s23, 0x2000
	s_nop 0
	global_load_lds_dwordx4 v[222:223], off
	s_barrier
	s_waitcnt lgkmcnt(0)
	s_setprio 1
	s_waitcnt lgkmcnt(0)
	v_mfma_f32_16x16x32_bf16 v[64:67], v[208:211], v[148:151], v[64:67]
	v_mfma_f32_16x16x32_bf16 v[60:63], v[242:245], v[148:151], v[60:63]
	v_mfma_f32_16x16x32_bf16 v[56:59], v[208:211], v[156:159], v[56:59]
	v_mfma_f32_16x16x32_bf16 v[52:55], v[242:245], v[156:159], v[52:55]
	v_mfma_f32_16x16x32_bf16 v[48:51], v[208:211], v[164:167], v[48:51]
	v_mfma_f32_16x16x32_bf16 v[44:47], v[242:245], v[164:167], v[44:47]
	v_mfma_f32_16x16x32_bf16 v[40:43], v[208:211], v[172:175], v[40:43]
	v_mfma_f32_16x16x32_bf16 v[36:39], v[242:245], v[172:175], v[36:39]
	v_mfma_f32_16x16x32_bf16 v[64:67], v[212:215], v[152:155], v[64:67]
	v_mfma_f32_16x16x32_bf16 v[60:63], v[246:249], v[152:155], v[60:63]
	v_mfma_f32_16x16x32_bf16 v[56:59], v[212:215], v[160:163], v[56:59]
	v_mfma_f32_16x16x32_bf16 v[52:55], v[246:249], v[160:163], v[52:55]
	v_mfma_f32_16x16x32_bf16 v[48:51], v[212:215], v[168:171], v[48:51]
	v_mfma_f32_16x16x32_bf16 v[44:47], v[246:249], v[168:171], v[44:47]
	v_mfma_f32_16x16x32_bf16 v[40:43], v[212:215], v[204:207], v[40:43]
	v_mfma_f32_16x16x32_bf16 v[36:39], v[246:249], v[204:207], v[36:39]
	s_setprio 0
	s_mov_b32 m0, s48
	v_lshl_add_u64 v[216:217], v[216:217], 0, s[76:77]
	s_barrier
	ds_read_b128 v[148:151], v240 offset:49152
	ds_read_b128 v[152:155], v240 offset:50176
	ds_read_b128 v[156:159], v240 offset:51200
	ds_read_b128 v[160:163], v240 offset:52224
	ds_read_b128 v[164:167], v240 offset:53248
	ds_read_b128 v[168:171], v240 offset:54272
	ds_read_b128 v[172:175], v240 offset:55296
	ds_read_b128 v[204:207], v240 offset:56320
	global_load_lds_dwordx4 v[216:217], off
	v_lshl_add_u64 v[216:217], v[236:237], 0, s[76:77]
	s_mov_b32 m0, s50
	s_nop 0
	global_load_lds_dwordx4 v[216:217], off
	s_barrier
	s_waitcnt lgkmcnt(0)
	s_setprio 1
	s_waitcnt lgkmcnt(0)
	v_mfma_f32_16x16x32_bf16 v[96:99], v[132:135], v[148:151], v[96:99]
	v_mfma_f32_16x16x32_bf16 v[92:95], v[140:143], v[148:151], v[92:95]
	v_mfma_f32_16x16x32_bf16 v[88:91], v[132:135], v[156:159], v[88:91]
	v_mfma_f32_16x16x32_bf16 v[84:87], v[140:143], v[156:159], v[84:87]
	v_mfma_f32_16x16x32_bf16 v[80:83], v[132:135], v[164:167], v[80:83]
	v_mfma_f32_16x16x32_bf16 v[76:79], v[140:143], v[164:167], v[76:79]
	v_mfma_f32_16x16x32_bf16 v[72:75], v[132:135], v[172:175], v[72:75]
	v_mfma_f32_16x16x32_bf16 v[68:71], v[140:143], v[172:175], v[68:71]
	v_mfma_f32_16x16x32_bf16 v[96:99], v[136:139], v[152:155], v[96:99]
	v_mfma_f32_16x16x32_bf16 v[92:95], v[144:147], v[152:155], v[92:95]
	v_mfma_f32_16x16x32_bf16 v[88:91], v[136:139], v[160:163], v[88:91]
	v_mfma_f32_16x16x32_bf16 v[84:87], v[144:147], v[160:163], v[84:87]
	v_mfma_f32_16x16x32_bf16 v[80:83], v[136:139], v[168:171], v[80:83]
	v_mfma_f32_16x16x32_bf16 v[76:79], v[144:147], v[168:171], v[76:79]
	v_mfma_f32_16x16x32_bf16 v[72:75], v[136:139], v[204:207], v[72:75]
	v_mfma_f32_16x16x32_bf16 v[68:71], v[144:147], v[204:207], v[68:71]
	s_setprio 0
	s_barrier
	s_add_u32 s24, s44, 0x40080
	s_addc_u32 s25, s45, 0
	s_add_i32 s23, s26, s67
	v_lshl_add_u64 v[132:133], s[24:25], 0, v[176:177]
	s_mov_b32 m0, s23
	s_nop 0
	global_load_lds_dwordx4 v[132:133], off
	v_lshl_add_u64 v[132:133], s[24:25], 0, v[180:181]
	s_add_i32 m0, s23, 0x2000
	s_nop 0
	global_load_lds_dwordx4 v[132:133], off
	s_waitcnt vmcnt(6)
	s_barrier
	s_setprio 1
	v_mfma_f32_16x16x32_bf16 v[32:35], v[208:211], v[148:151], v[32:35]
	v_mfma_f32_16x16x32_bf16 v[28:31], v[242:245], v[148:151], v[28:31]
	v_mfma_f32_16x16x32_bf16 v[24:27], v[208:211], v[156:159], v[24:27]
	v_mfma_f32_16x16x32_bf16 v[20:23], v[242:245], v[156:159], v[20:23]
	v_mfma_f32_16x16x32_bf16 v[16:19], v[208:211], v[164:167], v[16:19]
	v_mfma_f32_16x16x32_bf16 v[12:15], v[242:245], v[164:167], v[12:15]
	v_mfma_f32_16x16x32_bf16 v[8:11], v[208:211], v[172:175], v[8:11]
	v_mfma_f32_16x16x32_bf16 v[4:7], v[242:245], v[172:175], v[4:7]
	v_mfma_f32_16x16x32_bf16 v[32:35], v[212:215], v[152:155], v[32:35]
	v_mfma_f32_16x16x32_bf16 v[28:31], v[246:249], v[152:155], v[28:31]
	v_mfma_f32_16x16x32_bf16 v[24:27], v[212:215], v[160:163], v[24:27]
	v_mfma_f32_16x16x32_bf16 v[20:23], v[246:249], v[160:163], v[20:23]
	v_mfma_f32_16x16x32_bf16 v[16:19], v[212:215], v[168:171], v[16:19]
	v_mfma_f32_16x16x32_bf16 v[12:15], v[246:249], v[168:171], v[12:15]
	v_mfma_f32_16x16x32_bf16 v[8:11], v[212:215], v[204:207], v[8:11]
	v_mfma_f32_16x16x32_bf16 v[4:7], v[246:249], v[204:207], v[4:7]
	s_setprio 0
	s_add_i32 s22, s22, 2
	s_add_u32 s0, s0, 0x100
	s_addc_u32 s1, s1, 0
	s_add_u32 s20, s20, 0x100
	s_addc_u32 s21, s21, 0
	s_cmp_gt_u32 s22, 13
	s_barrier
	s_cbranch_scc0 .LBB0_427
	s_add_i32 s0, s61, -8
	s_cmp_lt_u32 s0, 12
	s_mov_b64 s[0:1], -1
	s_cbranch_scc1 .LBB0_451
	s_cmp_gt_i32 s61, 33
	s_cselect_b64 s[64:65], -1, 0
	s_lshl_b32 s0, s61, 8
	s_lshl_b32 s53, s60, 8
	s_add_i32 s1, s0, 0xffffee00
	s_cmp_lt_i32 s61, 26
	v_cndmask_b32_e64 v2, 0, 1, s[36:37]
	s_cselect_b32 s62, s0, s1
	s_mov_b64 s[0:1], -1
	s_and_b64 vcc, exec, s[64:65]
	v_cmp_ne_u32_e64 s[44:45], 1, v2
	s_cbranch_vccz .LBB0_433
	s_and_b64 vcc, exec, s[44:45]
	s_cbranch_vccnz .LBB0_432
	v_add_u32_e32 v132, s53, v185
	v_ashrrev_i32_e32 v133, 31, v132
	v_lshlrev_b64 v[140:141], 7, v[132:133]
	global_load_dwordx4 v[204:207], v[188:189], off offset:16
	global_load_dwordx4 v[208:211], v[188:189], off
	s_mov_b32 s3, 0xbfb8aa3b
	s_mov_b32 s2, 0x800000
	s_mov_b32 s4, 0x3f317217
	s_mov_b32 s5, 0x7f800000
	s_waitcnt vmcnt(0)
	v_mov_b32_e32 v132, v204
	v_mov_b32_e32 v133, v205
	v_mov_b32_e32 v134, v206
	v_mov_b32_e32 v135, v207
	v_mov_b32_e32 v136, v208
	v_mov_b32_e32 v137, v209
	v_mov_b32_e32 v138, v210
	v_mov_b32_e32 v139, v211
	v_add_f32_e32 v147, v126, v134
	v_add_f32_e32 v2, v128, v136
	v_max_f32_e32 v142, 0, v2
	v_mul_f32_e64 v2, |v2|, s3
	v_exp_f32_e32 v2, v2
	v_add_f32_e32 v136, v124, v132
	v_add_f32_e32 v149, v127, v135
	v_add_f32_e32 v2, 1.0, v2
	v_cmp_gt_f32_e32 vcc, s2, v2
	s_nop 1
	v_cndmask_b32_e64 v132, 0, 32, vcc
	v_ldexp_f32 v2, v2, v132
	v_log_f32_e32 v2, v2
	s_nop 0
	v_mul_f32_e32 v132, 0x3f317217, v2
	v_fma_f32 v132, v2, s4, -v132
	v_fmac_f32_e32 v132, 0x3377d1cf, v2
	v_fmac_f32_e32 v132, 0x3f317217, v2
	v_cmp_lt_f32_e64 s[0:1], |v2|, s5
	s_nop 1
	v_cndmask_b32_e64 v2, v2, v132, s[0:1]
	v_cndmask_b32_e32 v132, 0, v228, vcc
	v_sub_f32_e32 v144, v2, v132
	v_mul_f32_e64 v2, |v136|, s3
	v_exp_f32_e32 v2, v2
	v_max_f32_e32 v132, 0, v136
	v_add_f32_e32 v2, 1.0, v2
	v_cmp_gt_f32_e32 vcc, s2, v2
	s_nop 1
	v_cndmask_b32_e64 v136, 0, 32, vcc
	v_ldexp_f32 v2, v2, v136
	v_log_f32_e32 v2, v2
	s_nop 0
	v_mul_f32_e32 v136, 0x3f317217, v2
	v_fma_f32 v136, v2, s4, -v136
	v_fmac_f32_e32 v136, 0x3377d1cf, v2
	v_fmac_f32_e32 v136, 0x3f317217, v2
	v_cmp_lt_f32_e64 s[0:1], |v2|, s5
	s_nop 1
	v_cndmask_b32_e64 v2, v2, v136, s[0:1]
	v_cndmask_b32_e32 v136, 0, v228, vcc
	v_sub_f32_e32 v136, v2, v136
	v_add_f32_e32 v2, v129, v137
	v_max_f32_e32 v143, 0, v2
	v_mul_f32_e64 v2, |v2|, s3
	v_exp_f32_e32 v2, v2
	v_add_f32_e32 v137, v125, v133
	v_add_f32_e32 v2, 1.0, v2
	v_cmp_gt_f32_e32 vcc, s2, v2
	s_nop 1
	v_cndmask_b32_e64 v133, 0, 32, vcc
	v_ldexp_f32 v2, v2, v133
	v_log_f32_e32 v2, v2
	s_nop 0
	v_mul_f32_e32 v133, 0x3f317217, v2
	v_fma_f32 v133, v2, s4, -v133
	v_fmac_f32_e32 v133, 0x3377d1cf, v2
	v_fmac_f32_e32 v133, 0x3f317217, v2
	v_cmp_lt_f32_e64 s[0:1], |v2|, s5
	s_nop 1
	v_cndmask_b32_e64 v2, v2, v133, s[0:1]
	v_cndmask_b32_e32 v133, 0, v228, vcc
	v_sub_f32_e32 v145, v2, v133
	v_mul_f32_e64 v2, |v137|, s3
	v_exp_f32_e32 v2, v2
	v_max_f32_e32 v133, 0, v137
	v_pk_add_f32 v[142:143], v[142:143], v[144:145]
	v_add_f32_e32 v2, 1.0, v2
	v_cmp_gt_f32_e32 vcc, s2, v2
	s_nop 1
	v_cndmask_b32_e64 v137, 0, 32, vcc
	v_ldexp_f32 v2, v2, v137
	v_log_f32_e32 v2, v2
	s_nop 0
	v_mul_f32_e32 v137, 0x3f317217, v2
	v_fma_f32 v137, v2, s4, -v137
	v_fmac_f32_e32 v137, 0x3377d1cf, v2
	v_fmac_f32_e32 v137, 0x3f317217, v2
	v_cmp_lt_f32_e64 s[0:1], |v2|, s5
	s_nop 1
	v_cndmask_b32_e64 v2, v2, v137, s[0:1]
	v_cndmask_b32_e32 v137, 0, v228, vcc
	v_sub_f32_e32 v137, v2, v137
	v_add_f32_e32 v2, v130, v138
	v_max_f32_e32 v138, 0, v2
	v_mul_f32_e64 v2, |v2|, s3
	v_exp_f32_e32 v2, v2
	v_pk_add_f32 v[132:133], v[132:133], v[136:137]
	v_lshl_add_u64 v[136:137], v[190:191], 0, v[140:141]
	v_add_f32_e32 v2, 1.0, v2
	v_cmp_gt_f32_e32 vcc, s2, v2
	s_nop 1
	v_cndmask_b32_e64 v134, 0, 32, vcc
	v_ldexp_f32 v2, v2, v134
	v_log_f32_e32 v2, v2
	s_nop 0
	v_mul_f32_e32 v134, 0x3f317217, v2
	v_fma_f32 v134, v2, s4, -v134
	v_fmac_f32_e32 v134, 0x3377d1cf, v2
	v_fmac_f32_e32 v134, 0x3f317217, v2
	v_cmp_lt_f32_e64 s[0:1], |v2|, s5
	s_nop 1
	v_cndmask_b32_e64 v2, v2, v134, s[0:1]
	v_cndmask_b32_e32 v134, 0, v228, vcc
	v_sub_f32_e32 v146, v2, v134
	v_mul_f32_e64 v2, |v147|, s3
	v_exp_f32_e32 v2, v2
	v_max_f32_e32 v134, 0, v147
	v_add_f32_e32 v2, 1.0, v2
	v_cmp_gt_f32_e32 vcc, s2, v2
	s_nop 1
	v_cndmask_b32_e64 v147, 0, 32, vcc
	v_ldexp_f32 v2, v2, v147
	v_log_f32_e32 v2, v2
	s_nop 0
	v_mul_f32_e32 v147, 0x3f317217, v2
	v_fma_f32 v147, v2, s4, -v147
	v_fmac_f32_e32 v147, 0x3377d1cf, v2
	v_fmac_f32_e32 v147, 0x3f317217, v2
	v_cmp_lt_f32_e64 s[0:1], |v2|, s5
	s_nop 1
	v_cndmask_b32_e64 v2, v2, v147, s[0:1]
	v_cndmask_b32_e32 v147, 0, v228, vcc
	v_sub_f32_e32 v148, v2, v147
	v_add_f32_e32 v2, v131, v139
	v_max_f32_e32 v139, 0, v2
	v_mul_f32_e64 v2, |v2|, s3
	v_exp_f32_e32 v2, v2
	s_nop 0
	v_add_f32_e32 v2, 1.0, v2
	v_cmp_gt_f32_e32 vcc, s2, v2
	s_nop 1
	v_cndmask_b32_e64 v135, 0, 32, vcc
	v_ldexp_f32 v2, v2, v135
	v_log_f32_e32 v2, v2
	s_nop 0
	v_mul_f32_e32 v135, 0x3f317217, v2
	v_fma_f32 v135, v2, s4, -v135
	v_fmac_f32_e32 v135, 0x3377d1cf, v2
	v_fmac_f32_e32 v135, 0x3f317217, v2
	v_cmp_lt_f32_e64 s[0:1], |v2|, s5
	s_nop 1
	v_cndmask_b32_e64 v2, v2, v135, s[0:1]
	v_cndmask_b32_e32 v135, 0, v228, vcc
	v_sub_f32_e32 v147, v2, v135
	v_mul_f32_e64 v2, |v149|, s3
	v_exp_f32_e32 v2, v2
	v_pk_add_f32 v[144:145], v[138:139], v[146:147]
	v_max_f32_e32 v135, 0, v149
	v_add_f32_e32 v2, 1.0, v2
	v_cmp_gt_f32_e32 vcc, s2, v2
	s_nop 1
	v_cndmask_b32_e64 v138, 0, 32, vcc
	v_ldexp_f32 v2, v2, v138
	v_log_f32_e32 v2, v2
	s_nop 0
	v_mul_f32_e32 v138, 0x3f317217, v2
	v_fma_f32 v138, v2, s4, -v138
	v_fmac_f32_e32 v138, 0x3377d1cf, v2
	v_fmac_f32_e32 v138, 0x3f317217, v2
	v_cmp_lt_f32_e64 s[0:1], |v2|, s5
	s_nop 1
	v_cndmask_b32_e64 v2, v2, v138, s[0:1]
	v_cndmask_b32_e32 v138, 0, v228, vcc
	v_sub_f32_e32 v149, v2, v138
	v_pk_add_f32 v[134:135], v[134:135], v[148:149]
	global_store_dwordx4 v[136:137], v[142:145], off
	global_store_dwordx4 v[136:137], v[132:135], off offset:16

.LBB0_474:
	v_add_u32_e32 v132, s53, v241
	v_ashrrev_i32_e32 v133, 31, v132
	v_lshlrev_b64 v[140:141], 7, v[132:133]
	v_mov_b32_e32 v132, v204
	v_mov_b32_e32 v133, v205
	v_mov_b32_e32 v134, v206
	v_mov_b32_e32 v135, v207
	v_mov_b32_e32 v136, v208
	v_mov_b32_e32 v137, v209
	v_mov_b32_e32 v138, v210
	v_mov_b32_e32 v139, v211
	s_mov_b32 s3, 0xbfb8aa3b
	s_mov_b32 s2, 0x800000
	s_mov_b32 s4, 0x3f317217
	s_mov_b32 s5, 0x7f800000
	s_nop 0
	v_add_f32_e32 v143, v116, v132
	v_add_f32_e32 v136, v120, v136
	v_mul_f32_e64 v132, |v136|, s3
	v_exp_f32_e32 v132, v132
	v_max_f32_e32 v142, 0, v136
	v_add_f32_e32 v137, v121, v137
	v_add_f32_e32 v146, v117, v133
	v_add_f32_e32 v132, 1.0, v132
	v_cmp_gt_f32_e32 vcc, s2, v132
	v_mul_f32_e64 v133, |v137|, s3
	v_exp_f32_e32 v133, v133
	v_cndmask_b32_e64 v136, 0, 32, vcc
	v_ldexp_f32 v132, v132, v136
	v_log_f32_e32 v132, v132
	v_add_f32_e32 v133, 1.0, v133
	v_add_f32_e32 v147, v118, v134
	v_add_f32_e32 v149, v119, v135
	v_mul_f32_e32 v136, 0x3f317217, v132
	v_fma_f32 v136, v132, s4, -v136
	v_fmac_f32_e32 v136, 0x3377d1cf, v132
	v_fmac_f32_e32 v136, 0x3f317217, v132
	v_cmp_lt_f32_e64 s[0:1], |v132|, s5
	s_nop 1
	v_cndmask_b32_e64 v132, v132, v136, s[0:1]
	v_cndmask_b32_e32 v136, 0, v228, vcc
	v_sub_f32_e32 v144, v132, v136
	v_mul_f32_e64 v136, |v143|, s3
	v_exp_f32_e32 v136, v136
	v_max_f32_e32 v132, 0, v143
	v_add_f32_e32 v136, 1.0, v136
	v_cmp_gt_f32_e32 vcc, s2, v136
	s_nop 1
	v_cndmask_b32_e64 v143, 0, 32, vcc
	v_ldexp_f32 v136, v136, v143
	v_log_f32_e32 v136, v136
	s_nop 0
	v_mul_f32_e32 v143, 0x3f317217, v136
	v_fma_f32 v143, v136, s4, -v143
	v_fmac_f32_e32 v143, 0x3377d1cf, v136
	v_fmac_f32_e32 v143, 0x3f317217, v136
	v_cmp_lt_f32_e64 s[0:1], |v136|, s5
	s_nop 1
	v_cndmask_b32_e64 v136, v136, v143, s[0:1]
	v_cndmask_b32_e32 v143, 0, v228, vcc
	v_cmp_gt_f32_e32 vcc, s2, v133
	v_sub_f32_e32 v136, v136, v143
	v_max_f32_e32 v143, 0, v137
	v_cndmask_b32_e64 v137, 0, 32, vcc
	v_ldexp_f32 v133, v133, v137
	v_log_f32_e32 v133, v133
	s_nop 0
	v_mul_f32_e32 v137, 0x3f317217, v133
	v_fma_f32 v137, v133, s4, -v137
	v_fmac_f32_e32 v137, 0x3377d1cf, v133
	v_fmac_f32_e32 v137, 0x3f317217, v133
	v_cmp_lt_f32_e64 s[0:1], |v133|, s5
	s_nop 1
	v_cndmask_b32_e64 v133, v133, v137, s[0:1]
	v_cndmask_b32_e32 v137, 0, v228, vcc
	v_sub_f32_e32 v145, v133, v137
	v_mul_f32_e64 v137, |v146|, s3
	v_exp_f32_e32 v137, v137
	v_max_f32_e32 v133, 0, v146
	v_pk_add_f32 v[142:143], v[142:143], v[144:145]
	v_add_f32_e32 v137, 1.0, v137
	v_cmp_gt_f32_e32 vcc, s2, v137
	s_nop 1
	v_cndmask_b32_e64 v146, 0, 32, vcc
	v_ldexp_f32 v137, v137, v146
	v_log_f32_e32 v137, v137
	s_nop 0
	v_mul_f32_e32 v146, 0x3f317217, v137
	v_fma_f32 v146, v137, s4, -v146
	v_fmac_f32_e32 v146, 0x3377d1cf, v137
	v_fmac_f32_e32 v146, 0x3f317217, v137
	v_cmp_lt_f32_e64 s[0:1], |v137|, s5
	s_nop 1
	v_cndmask_b32_e64 v137, v137, v146, s[0:1]
	v_cndmask_b32_e32 v146, 0, v228, vcc
	v_sub_f32_e32 v137, v137, v146
	v_add_f32_e32 v146, v122, v138
	v_mul_f32_e64 v134, |v146|, s3
	v_exp_f32_e32 v134, v134
	v_max_f32_e32 v138, 0, v146
	v_pk_add_f32 v[132:133], v[132:133], v[136:137]
	v_lshl_add_u64 v[136:137], v[190:191], 0, v[140:141]
	v_add_f32_e32 v134, 1.0, v134
	v_cmp_gt_f32_e32 vcc, s2, v134
	s_nop 1
	v_cndmask_b32_e64 v146, 0, 32, vcc
	v_ldexp_f32 v134, v134, v146
	v_log_f32_e32 v134, v134
	s_nop 0
	v_mul_f32_e32 v146, 0x3f317217, v134
	v_fma_f32 v146, v134, s4, -v146
	v_fmac_f32_e32 v146, 0x3377d1cf, v134
	v_fmac_f32_e32 v146, 0x3f317217, v134
	v_cmp_lt_f32_e64 s[0:1], |v134|, s5
	s_nop 1
	v_cndmask_b32_e64 v134, v134, v146, s[0:1]
	v_cndmask_b32_e32 v146, 0, v228, vcc
	v_sub_f32_e32 v146, v134, v146
	v_max_f32_e32 v134, 0, v147
	v_mul_f32_e64 v147, |v147|, s3
	v_exp_f32_e32 v147, v147
	s_nop 0
	v_add_f32_e32 v147, 1.0, v147
	v_cmp_gt_f32_e32 vcc, s2, v147
	s_nop 1
	v_cndmask_b32_e64 v148, 0, 32, vcc
	v_ldexp_f32 v147, v147, v148
	v_log_f32_e32 v147, v147
	s_nop 0
	v_mul_f32_e32 v148, 0x3f317217, v147
	v_fma_f32 v148, v147, s4, -v148
	v_fmac_f32_e32 v148, 0x3377d1cf, v147
	v_fmac_f32_e32 v148, 0x3f317217, v147
	v_cmp_lt_f32_e64 s[0:1], |v147|, s5
	s_nop 1
	v_cndmask_b32_e64 v147, v147, v148, s[0:1]
	v_cndmask_b32_e32 v148, 0, v228, vcc
	v_sub_f32_e32 v148, v147, v148
	v_add_f32_e32 v147, v123, v139
	v_mul_f32_e64 v135, |v147|, s3
	v_exp_f32_e32 v135, v135
	v_max_f32_e32 v139, 0, v147
	v_add_f32_e32 v135, 1.0, v135
	v_cmp_gt_f32_e32 vcc, s2, v135
	s_nop 1
	v_cndmask_b32_e64 v147, 0, 32, vcc
	v_ldexp_f32 v135, v135, v147
	v_log_f32_e32 v135, v135
	s_nop 0
	v_mul_f32_e32 v147, 0x3f317217, v135
	v_fma_f32 v147, v135, s4, -v147
	v_fmac_f32_e32 v147, 0x3377d1cf, v135
	v_fmac_f32_e32 v147, 0x3f317217, v135
	v_cmp_lt_f32_e64 s[0:1], |v135|, s5
	s_nop 1
	v_cndmask_b32_e64 v135, v135, v147, s[0:1]
	v_cndmask_b32_e32 v147, 0, v228, vcc
	v_sub_f32_e32 v147, v135, v147
	v_pk_add_f32 v[144:145], v[138:139], v[146:147]
	v_mul_f32_e64 v138, |v149|, s3
	v_exp_f32_e32 v138, v138
	v_max_f32_e32 v135, 0, v149
	v_add_f32_e32 v138, 1.0, v138
	v_cmp_gt_f32_e32 vcc, s2, v138
	s_nop 1
	v_cndmask_b32_e64 v139, 0, 32, vcc
	v_ldexp_f32 v138, v138, v139
	v_log_f32_e32 v138, v138
	s_nop 0
	v_mul_f32_e32 v139, 0x3f317217, v138
	v_fma_f32 v139, v138, s4, -v139
	v_fmac_f32_e32 v139, 0x3377d1cf, v138
	v_fmac_f32_e32 v139, 0x3f317217, v138
	v_cmp_lt_f32_e64 s[0:1], |v138|, s5
	s_nop 1
	v_cndmask_b32_e64 v138, v138, v139, s[0:1]
	v_cndmask_b32_e32 v139, 0, v228, vcc
	v_sub_f32_e32 v149, v138, v139
	v_pk_add_f32 v[134:135], v[134:135], v[148:149]
	global_store_dwordx4 v[136:137], v[142:145], off
	global_store_dwordx4 v[136:137], v[132:135], off offset:16
	s_cbranch_execnz .LBB0_437

.LBB0_478:
	v_add_u32_e32 v132, s53, v219
	v_ashrrev_i32_e32 v133, 31, v132
	v_lshlrev_b64 v[140:141], 7, v[132:133]
	v_mov_b32_e32 v132, v204
	v_mov_b32_e32 v133, v205
	v_mov_b32_e32 v134, v206
	v_mov_b32_e32 v135, v207
	v_mov_b32_e32 v136, v208
	v_mov_b32_e32 v137, v209
	v_mov_b32_e32 v138, v210
	v_mov_b32_e32 v139, v211
	s_mov_b32 s3, 0xbfb8aa3b
	s_mov_b32 s2, 0x800000
	s_mov_b32 s4, 0x3f317217
	s_mov_b32 s5, 0x7f800000
	s_nop 0
	v_add_f32_e32 v143, v108, v132
	v_add_f32_e32 v136, v112, v136
	v_mul_f32_e64 v132, |v136|, s3
	v_exp_f32_e32 v132, v132
	v_max_f32_e32 v142, 0, v136
	v_add_f32_e32 v137, v113, v137
	v_add_f32_e32 v146, v109, v133
	v_add_f32_e32 v132, 1.0, v132
	v_cmp_gt_f32_e32 vcc, s2, v132
	v_mul_f32_e64 v133, |v137|, s3
	v_exp_f32_e32 v133, v133
	v_cndmask_b32_e64 v136, 0, 32, vcc
	v_ldexp_f32 v132, v132, v136
	v_log_f32_e32 v132, v132
	v_add_f32_e32 v133, 1.0, v133
	v_add_f32_e32 v147, v110, v134
	v_add_f32_e32 v149, v111, v135
	v_mul_f32_e32 v136, 0x3f317217, v132
	v_fma_f32 v136, v132, s4, -v136
	v_fmac_f32_e32 v136, 0x3377d1cf, v132
	v_fmac_f32_e32 v136, 0x3f317217, v132
	v_cmp_lt_f32_e64 s[0:1], |v132|, s5
	s_nop 1
	v_cndmask_b32_e64 v132, v132, v136, s[0:1]
	v_cndmask_b32_e32 v136, 0, v228, vcc
	v_sub_f32_e32 v144, v132, v136
	v_mul_f32_e64 v136, |v143|, s3
	v_exp_f32_e32 v136, v136
	v_max_f32_e32 v132, 0, v143
	v_add_f32_e32 v136, 1.0, v136
	v_cmp_gt_f32_e32 vcc, s2, v136
	s_nop 1
	v_cndmask_b32_e64 v143, 0, 32, vcc
	v_ldexp_f32 v136, v136, v143
	v_log_f32_e32 v136, v136
	s_nop 0
	v_mul_f32_e32 v143, 0x3f317217, v136
	v_fma_f32 v143, v136, s4, -v143
	v_fmac_f32_e32 v143, 0x3377d1cf, v136
	v_fmac_f32_e32 v143, 0x3f317217, v136
	v_cmp_lt_f32_e64 s[0:1], |v136|, s5
	s_nop 1
	v_cndmask_b32_e64 v136, v136, v143, s[0:1]
	v_cndmask_b32_e32 v143, 0, v228, vcc
	v_cmp_gt_f32_e32 vcc, s2, v133
	v_sub_f32_e32 v136, v136, v143
	v_max_f32_e32 v143, 0, v137
	v_cndmask_b32_e64 v137, 0, 32, vcc
	v_ldexp_f32 v133, v133, v137
	v_log_f32_e32 v133, v133
	s_nop 0
	v_mul_f32_e32 v137, 0x3f317217, v133
	v_fma_f32 v137, v133, s4, -v137
	v_fmac_f32_e32 v137, 0x3377d1cf, v133
	v_fmac_f32_e32 v137, 0x3f317217, v133
	v_cmp_lt_f32_e64 s[0:1], |v133|, s5
	s_nop 1
	v_cndmask_b32_e64 v133, v133, v137, s[0:1]
	v_cndmask_b32_e32 v137, 0, v228, vcc
	v_sub_f32_e32 v145, v133, v137
	v_mul_f32_e64 v137, |v146|, s3
	v_exp_f32_e32 v137, v137
	v_max_f32_e32 v133, 0, v146
	v_pk_add_f32 v[142:143], v[142:143], v[144:145]
	v_add_f32_e32 v137, 1.0, v137
	v_cmp_gt_f32_e32 vcc, s2, v137
	s_nop 1
	v_cndmask_b32_e64 v146, 0, 32, vcc
	v_ldexp_f32 v137, v137, v146
	v_log_f32_e32 v137, v137
	s_nop 0
	v_mul_f32_e32 v146, 0x3f317217, v137
	v_fma_f32 v146, v137, s4, -v146
	v_fmac_f32_e32 v146, 0x3377d1cf, v137
	v_fmac_f32_e32 v146, 0x3f317217, v137
	v_cmp_lt_f32_e64 s[0:1], |v137|, s5
	s_nop 1
	v_cndmask_b32_e64 v137, v137, v146, s[0:1]
	v_cndmask_b32_e32 v146, 0, v228, vcc
	v_sub_f32_e32 v137, v137, v146
	v_add_f32_e32 v146, v114, v138
	v_mul_f32_e64 v134, |v146|, s3
	v_exp_f32_e32 v134, v134
	v_max_f32_e32 v138, 0, v146
	v_pk_add_f32 v[132:133], v[132:133], v[136:137]
	v_lshl_add_u64 v[136:137], v[190:191], 0, v[140:141]
	v_add_f32_e32 v134, 1.0, v134
	v_cmp_gt_f32_e32 vcc, s2, v134
	s_nop 1
	v_cndmask_b32_e64 v146, 0, 32, vcc
	v_ldexp_f32 v134, v134, v146
	v_log_f32_e32 v134, v134
	s_nop 0
	v_mul_f32_e32 v146, 0x3f317217, v134
	v_fma_f32 v146, v134, s4, -v146
	v_fmac_f32_e32 v146, 0x3377d1cf, v134
	v_fmac_f32_e32 v146, 0x3f317217, v134
	v_cmp_lt_f32_e64 s[0:1], |v134|, s5
	s_nop 1
	v_cndmask_b32_e64 v134, v134, v146, s[0:1]
	v_cndmask_b32_e32 v146, 0, v228, vcc
	v_sub_f32_e32 v146, v134, v146
	v_max_f32_e32 v134, 0, v147
	v_mul_f32_e64 v147, |v147|, s3
	v_exp_f32_e32 v147, v147
	s_nop 0
	v_add_f32_e32 v147, 1.0, v147
	v_cmp_gt_f32_e32 vcc, s2, v147
	s_nop 1
	v_cndmask_b32_e64 v148, 0, 32, vcc
	v_ldexp_f32 v147, v147, v148
	v_log_f32_e32 v147, v147
	s_nop 0
	v_mul_f32_e32 v148, 0x3f317217, v147
	v_fma_f32 v148, v147, s4, -v148
	v_fmac_f32_e32 v148, 0x3377d1cf, v147
	v_fmac_f32_e32 v148, 0x3f317217, v147
	v_cmp_lt_f32_e64 s[0:1], |v147|, s5
	s_nop 1
	v_cndmask_b32_e64 v147, v147, v148, s[0:1]
	v_cndmask_b32_e32 v148, 0, v228, vcc
	v_sub_f32_e32 v148, v147, v148
	v_add_f32_e32 v147, v115, v139
	v_mul_f32_e64 v135, |v147|, s3
	v_exp_f32_e32 v135, v135
	v_max_f32_e32 v139, 0, v147
	v_add_f32_e32 v135, 1.0, v135
	v_cmp_gt_f32_e32 vcc, s2, v135
	s_nop 1
	v_cndmask_b32_e64 v147, 0, 32, vcc
	v_ldexp_f32 v135, v135, v147
	v_log_f32_e32 v135, v135
	s_nop 0
	v_mul_f32_e32 v147, 0x3f317217, v135
	v_fma_f32 v147, v135, s4, -v147
	v_fmac_f32_e32 v147, 0x3377d1cf, v135
	v_fmac_f32_e32 v147, 0x3f317217, v135
	v_cmp_lt_f32_e64 s[0:1], |v135|, s5
	s_nop 1
	v_cndmask_b32_e64 v135, v135, v147, s[0:1]
	v_cndmask_b32_e32 v147, 0, v228, vcc
	v_sub_f32_e32 v147, v135, v147
	v_pk_add_f32 v[144:145], v[138:139], v[146:147]
	v_mul_f32_e64 v138, |v149|, s3
	v_exp_f32_e32 v138, v138
	v_max_f32_e32 v135, 0, v149
	v_add_f32_e32 v138, 1.0, v138
	v_cmp_gt_f32_e32 vcc, s2, v138
	s_nop 1
	v_cndmask_b32_e64 v139, 0, 32, vcc
	v_ldexp_f32 v138, v138, v139
	v_log_f32_e32 v138, v138
	s_nop 0
	v_mul_f32_e32 v139, 0x3f317217, v138
	v_fma_f32 v139, v138, s4, -v139
	v_fmac_f32_e32 v139, 0x3377d1cf, v138
	v_fmac_f32_e32 v139, 0x3f317217, v138
	v_cmp_lt_f32_e64 s[0:1], |v138|, s5
	s_nop 1
	v_cndmask_b32_e64 v138, v138, v139, s[0:1]
	v_cndmask_b32_e32 v139, 0, v228, vcc
	v_sub_f32_e32 v149, v138, v139
	v_pk_add_f32 v[134:135], v[134:135], v[148:149]
	global_store_dwordx4 v[136:137], v[142:145], off
	global_store_dwordx4 v[136:137], v[132:135], off offset:16
	s_cbranch_execnz .LBB0_439

.LBB0_482:
	v_add_u32_e32 v132, s53, v235
	v_ashrrev_i32_e32 v133, 31, v132
	v_lshlrev_b64 v[140:141], 7, v[132:133]
	v_mov_b32_e32 v132, v204
	v_mov_b32_e32 v133, v205
	v_mov_b32_e32 v134, v206
	v_mov_b32_e32 v135, v207
	v_mov_b32_e32 v136, v208
	v_mov_b32_e32 v137, v209
	v_mov_b32_e32 v138, v210
	v_mov_b32_e32 v139, v211
	s_mov_b32 s3, 0xbfb8aa3b
	s_mov_b32 s2, 0x800000
	s_mov_b32 s4, 0x3f317217
	s_mov_b32 s5, 0x7f800000
	s_nop 0
	v_add_f32_e32 v143, v100, v132
	v_add_f32_e32 v136, v104, v136
	v_mul_f32_e64 v132, |v136|, s3
	v_exp_f32_e32 v132, v132
	v_max_f32_e32 v142, 0, v136
	v_add_f32_e32 v137, v105, v137
	v_add_f32_e32 v146, v101, v133
	v_add_f32_e32 v132, 1.0, v132
	v_cmp_gt_f32_e32 vcc, s2, v132
	v_mul_f32_e64 v133, |v137|, s3
	v_exp_f32_e32 v133, v133
	v_cndmask_b32_e64 v136, 0, 32, vcc
	v_ldexp_f32 v132, v132, v136
	v_log_f32_e32 v132, v132
	v_add_f32_e32 v133, 1.0, v133
	v_add_f32_e32 v147, v102, v134
	v_add_f32_e32 v149, v103, v135
	v_mul_f32_e32 v136, 0x3f317217, v132
	v_fma_f32 v136, v132, s4, -v136
	v_fmac_f32_e32 v136, 0x3377d1cf, v132
	v_fmac_f32_e32 v136, 0x3f317217, v132
	v_cmp_lt_f32_e64 s[0:1], |v132|, s5
	s_nop 1
	v_cndmask_b32_e64 v132, v132, v136, s[0:1]
	v_cndmask_b32_e32 v136, 0, v228, vcc
	v_sub_f32_e32 v144, v132, v136
	v_mul_f32_e64 v136, |v143|, s3
	v_exp_f32_e32 v136, v136
	v_max_f32_e32 v132, 0, v143
	v_add_f32_e32 v136, 1.0, v136
	v_cmp_gt_f32_e32 vcc, s2, v136
	s_nop 1
	v_cndmask_b32_e64 v143, 0, 32, vcc
	v_ldexp_f32 v136, v136, v143
	v_log_f32_e32 v136, v136
	s_nop 0
	v_mul_f32_e32 v143, 0x3f317217, v136
	v_fma_f32 v143, v136, s4, -v143
	v_fmac_f32_e32 v143, 0x3377d1cf, v136
	v_fmac_f32_e32 v143, 0x3f317217, v136
	v_cmp_lt_f32_e64 s[0:1], |v136|, s5
	s_nop 1
	v_cndmask_b32_e64 v136, v136, v143, s[0:1]
	v_cndmask_b32_e32 v143, 0, v228, vcc
	v_cmp_gt_f32_e32 vcc, s2, v133
	v_sub_f32_e32 v136, v136, v143
	v_max_f32_e32 v143, 0, v137
	v_cndmask_b32_e64 v137, 0, 32, vcc
	v_ldexp_f32 v133, v133, v137
	v_log_f32_e32 v133, v133
	s_nop 0
	v_mul_f32_e32 v137, 0x3f317217, v133
	v_fma_f32 v137, v133, s4, -v137
	v_fmac_f32_e32 v137, 0x3377d1cf, v133
	v_fmac_f32_e32 v137, 0x3f317217, v133
	v_cmp_lt_f32_e64 s[0:1], |v133|, s5
	s_nop 1
	v_cndmask_b32_e64 v133, v133, v137, s[0:1]
	v_cndmask_b32_e32 v137, 0, v228, vcc
	v_sub_f32_e32 v145, v133, v137
	v_mul_f32_e64 v137, |v146|, s3
	v_exp_f32_e32 v137, v137
	v_max_f32_e32 v133, 0, v146
	v_pk_add_f32 v[142:143], v[142:143], v[144:145]
	v_add_f32_e32 v137, 1.0, v137
	v_cmp_gt_f32_e32 vcc, s2, v137
	s_nop 1
	v_cndmask_b32_e64 v146, 0, 32, vcc
	v_ldexp_f32 v137, v137, v146
	v_log_f32_e32 v137, v137
	s_nop 0
	v_mul_f32_e32 v146, 0x3f317217, v137
	v_fma_f32 v146, v137, s4, -v146
	v_fmac_f32_e32 v146, 0x3377d1cf, v137
	v_fmac_f32_e32 v146, 0x3f317217, v137
	v_cmp_lt_f32_e64 s[0:1], |v137|, s5
	s_nop 1
	v_cndmask_b32_e64 v137, v137, v146, s[0:1]
	v_cndmask_b32_e32 v146, 0, v228, vcc
	v_sub_f32_e32 v137, v137, v146
	v_add_f32_e32 v146, v106, v138
	v_mul_f32_e64 v134, |v146|, s3
	v_exp_f32_e32 v134, v134
	v_max_f32_e32 v138, 0, v146
	v_pk_add_f32 v[132:133], v[132:133], v[136:137]
	v_lshl_add_u64 v[136:137], v[190:191], 0, v[140:141]
	v_add_f32_e32 v134, 1.0, v134
	v_cmp_gt_f32_e32 vcc, s2, v134
	s_nop 1
	v_cndmask_b32_e64 v146, 0, 32, vcc
	v_ldexp_f32 v134, v134, v146
	v_log_f32_e32 v134, v134
	s_nop 0
	v_mul_f32_e32 v146, 0x3f317217, v134
	v_fma_f32 v146, v134, s4, -v146
	v_fmac_f32_e32 v146, 0x3377d1cf, v134
	v_fmac_f32_e32 v146, 0x3f317217, v134
	v_cmp_lt_f32_e64 s[0:1], |v134|, s5
	s_nop 1
	v_cndmask_b32_e64 v134, v134, v146, s[0:1]
	v_cndmask_b32_e32 v146, 0, v228, vcc
	v_sub_f32_e32 v146, v134, v146
	v_max_f32_e32 v134, 0, v147
	v_mul_f32_e64 v147, |v147|, s3
	v_exp_f32_e32 v147, v147
	s_nop 0
	v_add_f32_e32 v147, 1.0, v147
	v_cmp_gt_f32_e32 vcc, s2, v147
	s_nop 1
	v_cndmask_b32_e64 v148, 0, 32, vcc
	v_ldexp_f32 v147, v147, v148
	v_log_f32_e32 v147, v147
	s_nop 0
	v_mul_f32_e32 v148, 0x3f317217, v147
	v_fma_f32 v148, v147, s4, -v148
	v_fmac_f32_e32 v148, 0x3377d1cf, v147
	v_fmac_f32_e32 v148, 0x3f317217, v147
	v_cmp_lt_f32_e64 s[0:1], |v147|, s5
	s_nop 1
	v_cndmask_b32_e64 v147, v147, v148, s[0:1]
	v_cndmask_b32_e32 v148, 0, v228, vcc
	v_sub_f32_e32 v148, v147, v148
	v_add_f32_e32 v147, v107, v139
	v_mul_f32_e64 v135, |v147|, s3
	v_exp_f32_e32 v135, v135
	v_max_f32_e32 v139, 0, v147
	v_add_f32_e32 v135, 1.0, v135
	v_cmp_gt_f32_e32 vcc, s2, v135
	s_nop 1
	v_cndmask_b32_e64 v147, 0, 32, vcc
	v_ldexp_f32 v135, v135, v147
	v_log_f32_e32 v135, v135
	s_nop 0
	v_mul_f32_e32 v147, 0x3f317217, v135
	v_fma_f32 v147, v135, s4, -v147
	v_fmac_f32_e32 v147, 0x3377d1cf, v135
	v_fmac_f32_e32 v147, 0x3f317217, v135
	v_cmp_lt_f32_e64 s[0:1], |v135|, s5
	s_nop 1
	v_cndmask_b32_e64 v135, v135, v147, s[0:1]
	v_cndmask_b32_e32 v147, 0, v228, vcc
	v_sub_f32_e32 v147, v135, v147
	v_pk_add_f32 v[144:145], v[138:139], v[146:147]
	v_mul_f32_e64 v138, |v149|, s3
	v_exp_f32_e32 v138, v138
	v_max_f32_e32 v135, 0, v149
	v_add_f32_e32 v138, 1.0, v138
	v_cmp_gt_f32_e32 vcc, s2, v138
	s_nop 1
	v_cndmask_b32_e64 v139, 0, 32, vcc
	v_ldexp_f32 v138, v138, v139
	v_log_f32_e32 v138, v138
	s_nop 0
	v_mul_f32_e32 v139, 0x3f317217, v138
	v_fma_f32 v139, v138, s4, -v139
	v_fmac_f32_e32 v139, 0x3377d1cf, v138
	v_fmac_f32_e32 v139, 0x3f317217, v138
	v_cmp_lt_f32_e64 s[0:1], |v138|, s5
	s_nop 1
	v_cndmask_b32_e64 v138, v138, v139, s[0:1]
	v_cndmask_b32_e32 v139, 0, v228, vcc
	v_sub_f32_e32 v149, v138, v139
	v_pk_add_f32 v[134:135], v[134:135], v[148:149]
	global_store_dwordx4 v[136:137], v[142:145], off
	global_store_dwordx4 v[136:137], v[132:135], off offset:16
	s_cbranch_execnz .LBB0_441

.LBB0_486:
	v_add_u32_e32 v132, s53, v221
	v_ashrrev_i32_e32 v133, 31, v132
	v_lshlrev_b64 v[140:141], 7, v[132:133]
	v_mov_b32_e32 v132, v204
	v_mov_b32_e32 v133, v205
	v_mov_b32_e32 v134, v206
	v_mov_b32_e32 v135, v207
	v_mov_b32_e32 v136, v208
	v_mov_b32_e32 v137, v209
	v_mov_b32_e32 v138, v210
	v_mov_b32_e32 v139, v211
	s_mov_b32 s3, 0xbfb8aa3b
	s_mov_b32 s2, 0x800000
	s_mov_b32 s4, 0x3f317217
	s_mov_b32 s5, 0x7f800000
	s_nop 0
	v_add_f32_e32 v143, v92, v132
	v_add_f32_e32 v136, v96, v136
	v_mul_f32_e64 v132, |v136|, s3
	v_exp_f32_e32 v132, v132
	v_max_f32_e32 v142, 0, v136
	v_add_f32_e32 v137, v97, v137
	v_add_f32_e32 v146, v93, v133
	v_add_f32_e32 v132, 1.0, v132
	v_cmp_gt_f32_e32 vcc, s2, v132
	v_mul_f32_e64 v133, |v137|, s3
	v_exp_f32_e32 v133, v133
	v_cndmask_b32_e64 v136, 0, 32, vcc
	v_ldexp_f32 v132, v132, v136
	v_log_f32_e32 v132, v132
	v_add_f32_e32 v133, 1.0, v133
	v_add_f32_e32 v147, v94, v134
	v_add_f32_e32 v149, v95, v135
	v_mul_f32_e32 v136, 0x3f317217, v132
	v_fma_f32 v136, v132, s4, -v136
	v_fmac_f32_e32 v136, 0x3377d1cf, v132
	v_fmac_f32_e32 v136, 0x3f317217, v132
	v_cmp_lt_f32_e64 s[0:1], |v132|, s5
	s_nop 1
	v_cndmask_b32_e64 v132, v132, v136, s[0:1]
	v_cndmask_b32_e32 v136, 0, v228, vcc
	v_sub_f32_e32 v144, v132, v136
	v_mul_f32_e64 v136, |v143|, s3
	v_exp_f32_e32 v136, v136
	v_max_f32_e32 v132, 0, v143
	v_add_f32_e32 v136, 1.0, v136
	v_cmp_gt_f32_e32 vcc, s2, v136
	s_nop 1
	v_cndmask_b32_e64 v143, 0, 32, vcc
	v_ldexp_f32 v136, v136, v143
	v_log_f32_e32 v136, v136
	s_nop 0
	v_mul_f32_e32 v143, 0x3f317217, v136
	v_fma_f32 v143, v136, s4, -v143
	v_fmac_f32_e32 v143, 0x3377d1cf, v136
	v_fmac_f32_e32 v143, 0x3f317217, v136
	v_cmp_lt_f32_e64 s[0:1], |v136|, s5
	s_nop 1
	v_cndmask_b32_e64 v136, v136, v143, s[0:1]
	v_cndmask_b32_e32 v143, 0, v228, vcc
	v_cmp_gt_f32_e32 vcc, s2, v133
	v_sub_f32_e32 v136, v136, v143
	v_max_f32_e32 v143, 0, v137
	v_cndmask_b32_e64 v137, 0, 32, vcc
	v_ldexp_f32 v133, v133, v137
	v_log_f32_e32 v133, v133
	s_nop 0
	v_mul_f32_e32 v137, 0x3f317217, v133
	v_fma_f32 v137, v133, s4, -v137
	v_fmac_f32_e32 v137, 0x3377d1cf, v133
	v_fmac_f32_e32 v137, 0x3f317217, v133
	v_cmp_lt_f32_e64 s[0:1], |v133|, s5
	s_nop 1
	v_cndmask_b32_e64 v133, v133, v137, s[0:1]
	v_cndmask_b32_e32 v137, 0, v228, vcc
	v_sub_f32_e32 v145, v133, v137
	v_mul_f32_e64 v137, |v146|, s3
	v_exp_f32_e32 v137, v137
	v_max_f32_e32 v133, 0, v146
	v_pk_add_f32 v[142:143], v[142:143], v[144:145]
	v_add_f32_e32 v137, 1.0, v137
	v_cmp_gt_f32_e32 vcc, s2, v137
	s_nop 1
	v_cndmask_b32_e64 v146, 0, 32, vcc
	v_ldexp_f32 v137, v137, v146
	v_log_f32_e32 v137, v137
	s_nop 0
	v_mul_f32_e32 v146, 0x3f317217, v137
	v_fma_f32 v146, v137, s4, -v146
	v_fmac_f32_e32 v146, 0x3377d1cf, v137
	v_fmac_f32_e32 v146, 0x3f317217, v137
	v_cmp_lt_f32_e64 s[0:1], |v137|, s5
	s_nop 1
	v_cndmask_b32_e64 v137, v137, v146, s[0:1]
	v_cndmask_b32_e32 v146, 0, v228, vcc
	v_sub_f32_e32 v137, v137, v146
	v_add_f32_e32 v146, v98, v138
	v_mul_f32_e64 v134, |v146|, s3
	v_exp_f32_e32 v134, v134
	v_max_f32_e32 v138, 0, v146
	v_pk_add_f32 v[132:133], v[132:133], v[136:137]
	v_lshl_add_u64 v[136:137], v[190:191], 0, v[140:141]
	v_add_f32_e32 v134, 1.0, v134
	v_cmp_gt_f32_e32 vcc, s2, v134
	s_nop 1
	v_cndmask_b32_e64 v146, 0, 32, vcc
	v_ldexp_f32 v134, v134, v146
	v_log_f32_e32 v134, v134
	s_nop 0
	v_mul_f32_e32 v146, 0x3f317217, v134
	v_fma_f32 v146, v134, s4, -v146
	v_fmac_f32_e32 v146, 0x3377d1cf, v134
	v_fmac_f32_e32 v146, 0x3f317217, v134
	v_cmp_lt_f32_e64 s[0:1], |v134|, s5
	s_nop 1
	v_cndmask_b32_e64 v134, v134, v146, s[0:1]
	v_cndmask_b32_e32 v146, 0, v228, vcc
	v_sub_f32_e32 v146, v134, v146
	v_max_f32_e32 v134, 0, v147
	v_mul_f32_e64 v147, |v147|, s3
	v_exp_f32_e32 v147, v147
	s_nop 0
	v_add_f32_e32 v147, 1.0, v147
	v_cmp_gt_f32_e32 vcc, s2, v147
	s_nop 1
	v_cndmask_b32_e64 v148, 0, 32, vcc
	v_ldexp_f32 v147, v147, v148
	v_log_f32_e32 v147, v147
	s_nop 0
	v_mul_f32_e32 v148, 0x3f317217, v147
	v_fma_f32 v148, v147, s4, -v148
	v_fmac_f32_e32 v148, 0x3377d1cf, v147
	v_fmac_f32_e32 v148, 0x3f317217, v147
	v_cmp_lt_f32_e64 s[0:1], |v147|, s5
	s_nop 1
	v_cndmask_b32_e64 v147, v147, v148, s[0:1]
	v_cndmask_b32_e32 v148, 0, v228, vcc
	v_sub_f32_e32 v148, v147, v148
	v_add_f32_e32 v147, v99, v139
	v_mul_f32_e64 v135, |v147|, s3
	v_exp_f32_e32 v135, v135
	v_max_f32_e32 v139, 0, v147
	v_add_f32_e32 v135, 1.0, v135
	v_cmp_gt_f32_e32 vcc, s2, v135
	s_nop 1
	v_cndmask_b32_e64 v147, 0, 32, vcc
	v_ldexp_f32 v135, v135, v147
	v_log_f32_e32 v135, v135
	s_nop 0
	v_mul_f32_e32 v147, 0x3f317217, v135
	v_fma_f32 v147, v135, s4, -v147
	v_fmac_f32_e32 v147, 0x3377d1cf, v135
	v_fmac_f32_e32 v147, 0x3f317217, v135
	v_cmp_lt_f32_e64 s[0:1], |v135|, s5
	s_nop 1
	v_cndmask_b32_e64 v135, v135, v147, s[0:1]
	v_cndmask_b32_e32 v147, 0, v228, vcc
	v_sub_f32_e32 v147, v135, v147
	v_pk_add_f32 v[144:145], v[138:139], v[146:147]
	v_mul_f32_e64 v138, |v149|, s3
	v_exp_f32_e32 v138, v138
	v_max_f32_e32 v135, 0, v149
	v_add_f32_e32 v138, 1.0, v138
	v_cmp_gt_f32_e32 vcc, s2, v138
	s_nop 1
	v_cndmask_b32_e64 v139, 0, 32, vcc
	v_ldexp_f32 v138, v138, v139
	v_log_f32_e32 v138, v138
	s_nop 0
	v_mul_f32_e32 v139, 0x3f317217, v138
	v_fma_f32 v139, v138, s4, -v139
	v_fmac_f32_e32 v139, 0x3377d1cf, v138
	v_fmac_f32_e32 v139, 0x3f317217, v138
	v_cmp_lt_f32_e64 s[0:1], |v138|, s5
	s_nop 1
	v_cndmask_b32_e64 v138, v138, v139, s[0:1]
	v_cndmask_b32_e32 v139, 0, v228, vcc
	v_sub_f32_e32 v149, v138, v139
	v_pk_add_f32 v[134:135], v[134:135], v[148:149]
	global_store_dwordx4 v[136:137], v[142:145], off
	global_store_dwordx4 v[136:137], v[132:135], off offset:16
	s_cbranch_execnz .LBB0_443

.LBB0_490:
	v_add_u32_e32 v132, s53, v224
	v_ashrrev_i32_e32 v133, 31, v132
	v_lshlrev_b64 v[140:141], 7, v[132:133]
	v_mov_b32_e32 v132, v204
	v_mov_b32_e32 v133, v205
	v_mov_b32_e32 v134, v206
	v_mov_b32_e32 v135, v207
	v_mov_b32_e32 v136, v208
	v_mov_b32_e32 v137, v209
	v_mov_b32_e32 v138, v210
	v_mov_b32_e32 v139, v211
	s_mov_b32 s3, 0xbfb8aa3b
	s_mov_b32 s2, 0x800000
	s_mov_b32 s4, 0x3f317217
	s_mov_b32 s5, 0x7f800000
	s_nop 0
	v_add_f32_e32 v143, v84, v132
	v_add_f32_e32 v136, v88, v136
	v_mul_f32_e64 v132, |v136|, s3
	v_exp_f32_e32 v132, v132
	v_max_f32_e32 v142, 0, v136
	v_add_f32_e32 v137, v89, v137
	v_add_f32_e32 v146, v85, v133
	v_add_f32_e32 v132, 1.0, v132
	v_cmp_gt_f32_e32 vcc, s2, v132
	v_mul_f32_e64 v133, |v137|, s3
	v_exp_f32_e32 v133, v133
	v_cndmask_b32_e64 v136, 0, 32, vcc
	v_ldexp_f32 v132, v132, v136
	v_log_f32_e32 v132, v132
	v_add_f32_e32 v133, 1.0, v133
	v_add_f32_e32 v147, v86, v134
	v_add_f32_e32 v149, v87, v135
	v_mul_f32_e32 v136, 0x3f317217, v132
	v_fma_f32 v136, v132, s4, -v136
	v_fmac_f32_e32 v136, 0x3377d1cf, v132
	v_fmac_f32_e32 v136, 0x3f317217, v132
	v_cmp_lt_f32_e64 s[0:1], |v132|, s5
	s_nop 1
	v_cndmask_b32_e64 v132, v132, v136, s[0:1]
	v_cndmask_b32_e32 v136, 0, v228, vcc
	v_sub_f32_e32 v144, v132, v136
	v_mul_f32_e64 v136, |v143|, s3
	v_exp_f32_e32 v136, v136
	v_max_f32_e32 v132, 0, v143
	v_add_f32_e32 v136, 1.0, v136
	v_cmp_gt_f32_e32 vcc, s2, v136
	s_nop 1
	v_cndmask_b32_e64 v143, 0, 32, vcc
	v_ldexp_f32 v136, v136, v143
	v_log_f32_e32 v136, v136
	s_nop 0
	v_mul_f32_e32 v143, 0x3f317217, v136
	v_fma_f32 v143, v136, s4, -v143
	v_fmac_f32_e32 v143, 0x3377d1cf, v136
	v_fmac_f32_e32 v143, 0x3f317217, v136
	v_cmp_lt_f32_e64 s[0:1], |v136|, s5
	s_nop 1
	v_cndmask_b32_e64 v136, v136, v143, s[0:1]
	v_cndmask_b32_e32 v143, 0, v228, vcc
	v_cmp_gt_f32_e32 vcc, s2, v133
	v_sub_f32_e32 v136, v136, v143
	v_max_f32_e32 v143, 0, v137
	v_cndmask_b32_e64 v137, 0, 32, vcc
	v_ldexp_f32 v133, v133, v137
	v_log_f32_e32 v133, v133
	s_nop 0
	v_mul_f32_e32 v137, 0x3f317217, v133
	v_fma_f32 v137, v133, s4, -v137
	v_fmac_f32_e32 v137, 0x3377d1cf, v133
	v_fmac_f32_e32 v137, 0x3f317217, v133
	v_cmp_lt_f32_e64 s[0:1], |v133|, s5
	s_nop 1
	v_cndmask_b32_e64 v133, v133, v137, s[0:1]
	v_cndmask_b32_e32 v137, 0, v228, vcc
	v_sub_f32_e32 v145, v133, v137
	v_mul_f32_e64 v137, |v146|, s3
	v_exp_f32_e32 v137, v137
	v_max_f32_e32 v133, 0, v146
	v_pk_add_f32 v[142:143], v[142:143], v[144:145]
	v_add_f32_e32 v137, 1.0, v137
	v_cmp_gt_f32_e32 vcc, s2, v137
	s_nop 1
	v_cndmask_b32_e64 v146, 0, 32, vcc
	v_ldexp_f32 v137, v137, v146
	v_log_f32_e32 v137, v137
	s_nop 0
	v_mul_f32_e32 v146, 0x3f317217, v137
	v_fma_f32 v146, v137, s4, -v146
	v_fmac_f32_e32 v146, 0x3377d1cf, v137
	v_fmac_f32_e32 v146, 0x3f317217, v137
	v_cmp_lt_f32_e64 s[0:1], |v137|, s5
	s_nop 1
	v_cndmask_b32_e64 v137, v137, v146, s[0:1]
	v_cndmask_b32_e32 v146, 0, v228, vcc
	v_sub_f32_e32 v137, v137, v146
	v_add_f32_e32 v146, v90, v138
	v_mul_f32_e64 v134, |v146|, s3
	v_exp_f32_e32 v134, v134
	v_max_f32_e32 v138, 0, v146
	v_pk_add_f32 v[132:133], v[132:133], v[136:137]
	v_lshl_add_u64 v[136:137], v[190:191], 0, v[140:141]
	v_add_f32_e32 v134, 1.0, v134
	v_cmp_gt_f32_e32 vcc, s2, v134
	s_nop 1
	v_cndmask_b32_e64 v146, 0, 32, vcc
	v_ldexp_f32 v134, v134, v146
	v_log_f32_e32 v134, v134
	s_nop 0
	v_mul_f32_e32 v146, 0x3f317217, v134
	v_fma_f32 v146, v134, s4, -v146
	v_fmac_f32_e32 v146, 0x3377d1cf, v134
	v_fmac_f32_e32 v146, 0x3f317217, v134
	v_cmp_lt_f32_e64 s[0:1], |v134|, s5
	s_nop 1
	v_cndmask_b32_e64 v134, v134, v146, s[0:1]
	v_cndmask_b32_e32 v146, 0, v228, vcc
	v_sub_f32_e32 v146, v134, v146
	v_max_f32_e32 v134, 0, v147
	v_mul_f32_e64 v147, |v147|, s3
	v_exp_f32_e32 v147, v147
	s_nop 0
	v_add_f32_e32 v147, 1.0, v147
	v_cmp_gt_f32_e32 vcc, s2, v147
	s_nop 1
	v_cndmask_b32_e64 v148, 0, 32, vcc
	v_ldexp_f32 v147, v147, v148
	v_log_f32_e32 v147, v147
	s_nop 0
	v_mul_f32_e32 v148, 0x3f317217, v147
	v_fma_f32 v148, v147, s4, -v148
	v_fmac_f32_e32 v148, 0x3377d1cf, v147
	v_fmac_f32_e32 v148, 0x3f317217, v147
	v_cmp_lt_f32_e64 s[0:1], |v147|, s5
	s_nop 1
	v_cndmask_b32_e64 v147, v147, v148, s[0:1]
	v_cndmask_b32_e32 v148, 0, v228, vcc
	v_sub_f32_e32 v148, v147, v148
	v_add_f32_e32 v147, v91, v139
	v_mul_f32_e64 v135, |v147|, s3
	v_exp_f32_e32 v135, v135
	v_max_f32_e32 v139, 0, v147
	v_add_f32_e32 v135, 1.0, v135
	v_cmp_gt_f32_e32 vcc, s2, v135
	s_nop 1
	v_cndmask_b32_e64 v147, 0, 32, vcc
	v_ldexp_f32 v135, v135, v147
	v_log_f32_e32 v135, v135
	s_nop 0
	v_mul_f32_e32 v147, 0x3f317217, v135
	v_fma_f32 v147, v135, s4, -v147
	v_fmac_f32_e32 v147, 0x3377d1cf, v135
	v_fmac_f32_e32 v147, 0x3f317217, v135
	v_cmp_lt_f32_e64 s[0:1], |v135|, s5
	s_nop 1
	v_cndmask_b32_e64 v135, v135, v147, s[0:1]
	v_cndmask_b32_e32 v147, 0, v228, vcc
	v_sub_f32_e32 v147, v135, v147
	v_pk_add_f32 v[144:145], v[138:139], v[146:147]
	v_mul_f32_e64 v138, |v149|, s3
	v_exp_f32_e32 v138, v138
	v_max_f32_e32 v135, 0, v149
	v_add_f32_e32 v138, 1.0, v138
	v_cmp_gt_f32_e32 vcc, s2, v138
	s_nop 1
	v_cndmask_b32_e64 v139, 0, 32, vcc
	v_ldexp_f32 v138, v138, v139
	v_log_f32_e32 v138, v138
	s_nop 0
	v_mul_f32_e32 v139, 0x3f317217, v138
	v_fma_f32 v139, v138, s4, -v139
	v_fmac_f32_e32 v139, 0x3377d1cf, v138
	v_fmac_f32_e32 v139, 0x3f317217, v138
	v_cmp_lt_f32_e64 s[0:1], |v138|, s5
	s_nop 1
	v_cndmask_b32_e64 v138, v138, v139, s[0:1]
	v_cndmask_b32_e32 v139, 0, v228, vcc
	v_sub_f32_e32 v149, v138, v139
	v_pk_add_f32 v[134:135], v[134:135], v[148:149]
	global_store_dwordx4 v[136:137], v[142:145], off
	global_store_dwordx4 v[136:137], v[132:135], off offset:16
	s_cbranch_execnz .LBB0_445

.LBB0_494:
	v_add_u32_e32 v132, s53, v238
	v_ashrrev_i32_e32 v133, 31, v132
	v_lshlrev_b64 v[140:141], 7, v[132:133]
	v_mov_b32_e32 v132, v204
	v_mov_b32_e32 v133, v205
	v_mov_b32_e32 v134, v206
	v_mov_b32_e32 v135, v207
	v_mov_b32_e32 v136, v208
	v_mov_b32_e32 v137, v209
	v_mov_b32_e32 v138, v210
	v_mov_b32_e32 v139, v211
	s_mov_b32 s3, 0xbfb8aa3b
	s_mov_b32 s2, 0x800000
	s_mov_b32 s4, 0x3f317217
	s_mov_b32 s5, 0x7f800000
	s_nop 0
	v_add_f32_e32 v143, v76, v132
	v_add_f32_e32 v136, v80, v136
	v_mul_f32_e64 v132, |v136|, s3
	v_exp_f32_e32 v132, v132
	v_max_f32_e32 v142, 0, v136
	v_add_f32_e32 v137, v81, v137
	v_add_f32_e32 v146, v77, v133
	v_add_f32_e32 v132, 1.0, v132
	v_cmp_gt_f32_e32 vcc, s2, v132
	v_mul_f32_e64 v133, |v137|, s3
	v_exp_f32_e32 v133, v133
	v_cndmask_b32_e64 v136, 0, 32, vcc
	v_ldexp_f32 v132, v132, v136
	v_log_f32_e32 v132, v132
	v_add_f32_e32 v133, 1.0, v133
	v_add_f32_e32 v147, v78, v134
	v_add_f32_e32 v149, v79, v135
	v_mul_f32_e32 v136, 0x3f317217, v132
	v_fma_f32 v136, v132, s4, -v136
	v_fmac_f32_e32 v136, 0x3377d1cf, v132
	v_fmac_f32_e32 v136, 0x3f317217, v132
	v_cmp_lt_f32_e64 s[0:1], |v132|, s5
	s_nop 1
	v_cndmask_b32_e64 v132, v132, v136, s[0:1]
	v_cndmask_b32_e32 v136, 0, v228, vcc
	v_sub_f32_e32 v144, v132, v136
	v_mul_f32_e64 v136, |v143|, s3
	v_exp_f32_e32 v136, v136
	v_max_f32_e32 v132, 0, v143
	v_add_f32_e32 v136, 1.0, v136
	v_cmp_gt_f32_e32 vcc, s2, v136
	s_nop 1
	v_cndmask_b32_e64 v143, 0, 32, vcc
	v_ldexp_f32 v136, v136, v143
	v_log_f32_e32 v136, v136
	s_nop 0
	v_mul_f32_e32 v143, 0x3f317217, v136
	v_fma_f32 v143, v136, s4, -v143
	v_fmac_f32_e32 v143, 0x3377d1cf, v136
	v_fmac_f32_e32 v143, 0x3f317217, v136
	v_cmp_lt_f32_e64 s[0:1], |v136|, s5
	s_nop 1
	v_cndmask_b32_e64 v136, v136, v143, s[0:1]
	v_cndmask_b32_e32 v143, 0, v228, vcc
	v_cmp_gt_f32_e32 vcc, s2, v133
	v_sub_f32_e32 v136, v136, v143
	v_max_f32_e32 v143, 0, v137
	v_cndmask_b32_e64 v137, 0, 32, vcc
	v_ldexp_f32 v133, v133, v137
	v_log_f32_e32 v133, v133
	s_nop 0
	v_mul_f32_e32 v137, 0x3f317217, v133
	v_fma_f32 v137, v133, s4, -v137
	v_fmac_f32_e32 v137, 0x3377d1cf, v133
	v_fmac_f32_e32 v137, 0x3f317217, v133
	v_cmp_lt_f32_e64 s[0:1], |v133|, s5
	s_nop 1
	v_cndmask_b32_e64 v133, v133, v137, s[0:1]
	v_cndmask_b32_e32 v137, 0, v228, vcc
	v_sub_f32_e32 v145, v133, v137
	v_mul_f32_e64 v137, |v146|, s3
	v_exp_f32_e32 v137, v137
	v_max_f32_e32 v133, 0, v146
	v_pk_add_f32 v[142:143], v[142:143], v[144:145]
	v_add_f32_e32 v137, 1.0, v137
	v_cmp_gt_f32_e32 vcc, s2, v137
	s_nop 1
	v_cndmask_b32_e64 v146, 0, 32, vcc
	v_ldexp_f32 v137, v137, v146
	v_log_f32_e32 v137, v137
	s_nop 0
	v_mul_f32_e32 v146, 0x3f317217, v137
	v_fma_f32 v146, v137, s4, -v146
	v_fmac_f32_e32 v146, 0x3377d1cf, v137
	v_fmac_f32_e32 v146, 0x3f317217, v137
	v_cmp_lt_f32_e64 s[0:1], |v137|, s5
	s_nop 1
	v_cndmask_b32_e64 v137, v137, v146, s[0:1]
	v_cndmask_b32_e32 v146, 0, v228, vcc
	v_sub_f32_e32 v137, v137, v146
	v_add_f32_e32 v146, v82, v138
	v_mul_f32_e64 v134, |v146|, s3
	v_exp_f32_e32 v134, v134
	v_max_f32_e32 v138, 0, v146
	v_pk_add_f32 v[132:133], v[132:133], v[136:137]
	v_lshl_add_u64 v[136:137], v[190:191], 0, v[140:141]
	v_add_f32_e32 v134, 1.0, v134
	v_cmp_gt_f32_e32 vcc, s2, v134
	s_nop 1
	v_cndmask_b32_e64 v146, 0, 32, vcc
	v_ldexp_f32 v134, v134, v146
	v_log_f32_e32 v134, v134
	s_nop 0
	v_mul_f32_e32 v146, 0x3f317217, v134
	v_fma_f32 v146, v134, s4, -v146
	v_fmac_f32_e32 v146, 0x3377d1cf, v134
	v_fmac_f32_e32 v146, 0x3f317217, v134
	v_cmp_lt_f32_e64 s[0:1], |v134|, s5
	s_nop 1
	v_cndmask_b32_e64 v134, v134, v146, s[0:1]
	v_cndmask_b32_e32 v146, 0, v228, vcc
	v_sub_f32_e32 v146, v134, v146
	v_max_f32_e32 v134, 0, v147
	v_mul_f32_e64 v147, |v147|, s3
	v_exp_f32_e32 v147, v147
	s_nop 0
	v_add_f32_e32 v147, 1.0, v147
	v_cmp_gt_f32_e32 vcc, s2, v147
	s_nop 1
	v_cndmask_b32_e64 v148, 0, 32, vcc
	v_ldexp_f32 v147, v147, v148
	v_log_f32_e32 v147, v147
	s_nop 0
	v_mul_f32_e32 v148, 0x3f317217, v147
	v_fma_f32 v148, v147, s4, -v148
	v_fmac_f32_e32 v148, 0x3377d1cf, v147
	v_fmac_f32_e32 v148, 0x3f317217, v147
	v_cmp_lt_f32_e64 s[0:1], |v147|, s5
	s_nop 1
	v_cndmask_b32_e64 v147, v147, v148, s[0:1]
	v_cndmask_b32_e32 v148, 0, v228, vcc
	v_sub_f32_e32 v148, v147, v148
	v_add_f32_e32 v147, v83, v139
	v_mul_f32_e64 v135, |v147|, s3
	v_exp_f32_e32 v135, v135
	v_max_f32_e32 v139, 0, v147
	v_add_f32_e32 v135, 1.0, v135
	v_cmp_gt_f32_e32 vcc, s2, v135
	s_nop 1
	v_cndmask_b32_e64 v147, 0, 32, vcc
	v_ldexp_f32 v135, v135, v147
	v_log_f32_e32 v135, v135
	s_nop 0
	v_mul_f32_e32 v147, 0x3f317217, v135
	v_fma_f32 v147, v135, s4, -v147
	v_fmac_f32_e32 v147, 0x3377d1cf, v135
	v_fmac_f32_e32 v147, 0x3f317217, v135
	v_cmp_lt_f32_e64 s[0:1], |v135|, s5
	s_nop 1
	v_cndmask_b32_e64 v135, v135, v147, s[0:1]
	v_cndmask_b32_e32 v147, 0, v228, vcc
	v_sub_f32_e32 v147, v135, v147
	v_pk_add_f32 v[144:145], v[138:139], v[146:147]
	v_mul_f32_e64 v138, |v149|, s3
	v_exp_f32_e32 v138, v138
	v_max_f32_e32 v135, 0, v149
	v_add_f32_e32 v138, 1.0, v138
	v_cmp_gt_f32_e32 vcc, s2, v138
	s_nop 1
	v_cndmask_b32_e64 v139, 0, 32, vcc
	v_ldexp_f32 v138, v138, v139
	v_log_f32_e32 v138, v138
	s_nop 0
	v_mul_f32_e32 v139, 0x3f317217, v138
	v_fma_f32 v139, v138, s4, -v139
	v_fmac_f32_e32 v139, 0x3377d1cf, v138
	v_fmac_f32_e32 v139, 0x3f317217, v138
	v_cmp_lt_f32_e64 s[0:1], |v138|, s5
	s_nop 1
	v_cndmask_b32_e64 v138, v138, v139, s[0:1]
	v_cndmask_b32_e32 v139, 0, v228, vcc
	v_sub_f32_e32 v149, v138, v139
	v_pk_add_f32 v[134:135], v[134:135], v[148:149]
	global_store_dwordx4 v[136:137], v[142:145], off
	global_store_dwordx4 v[136:137], v[132:135], off offset:16
	s_cbranch_execnz .LBB0_447

.LBB0_498:
	v_add_u32_e32 v132, s53, v239
	v_ashrrev_i32_e32 v133, 31, v132
	v_lshlrev_b64 v[140:141], 7, v[132:133]
	v_mov_b32_e32 v132, v204
	v_mov_b32_e32 v133, v205
	v_mov_b32_e32 v134, v206
	v_mov_b32_e32 v135, v207
	v_mov_b32_e32 v136, v208
	v_mov_b32_e32 v137, v209
	v_mov_b32_e32 v138, v210
	v_mov_b32_e32 v139, v211
	s_mov_b32 s3, 0xbfb8aa3b
	s_mov_b32 s2, 0x800000
	s_mov_b32 s4, 0x3f317217
	s_mov_b32 s5, 0x7f800000
	s_nop 0
	v_add_f32_e32 v143, v68, v132
	v_add_f32_e32 v136, v72, v136
	v_mul_f32_e64 v132, |v136|, s3
	v_exp_f32_e32 v132, v132
	v_max_f32_e32 v142, 0, v136
	v_add_f32_e32 v137, v73, v137
	v_add_f32_e32 v146, v69, v133
	v_add_f32_e32 v132, 1.0, v132
	v_cmp_gt_f32_e32 vcc, s2, v132
	v_mul_f32_e64 v133, |v137|, s3
	v_exp_f32_e32 v133, v133
	v_cndmask_b32_e64 v136, 0, 32, vcc
	v_ldexp_f32 v132, v132, v136
	v_log_f32_e32 v132, v132
	v_add_f32_e32 v133, 1.0, v133
	v_add_f32_e32 v147, v70, v134
	v_add_f32_e32 v149, v71, v135
	v_mul_f32_e32 v136, 0x3f317217, v132
	v_fma_f32 v136, v132, s4, -v136
	v_fmac_f32_e32 v136, 0x3377d1cf, v132
	v_fmac_f32_e32 v136, 0x3f317217, v132
	v_cmp_lt_f32_e64 s[0:1], |v132|, s5
	s_nop 1
	v_cndmask_b32_e64 v132, v132, v136, s[0:1]
	v_cndmask_b32_e32 v136, 0, v228, vcc
	v_sub_f32_e32 v144, v132, v136
	v_mul_f32_e64 v136, |v143|, s3
	v_exp_f32_e32 v136, v136
	v_max_f32_e32 v132, 0, v143
	v_add_f32_e32 v136, 1.0, v136
	v_cmp_gt_f32_e32 vcc, s2, v136
	s_nop 1
	v_cndmask_b32_e64 v143, 0, 32, vcc
	v_ldexp_f32 v136, v136, v143
	v_log_f32_e32 v136, v136
	s_nop 0
	v_mul_f32_e32 v143, 0x3f317217, v136
	v_fma_f32 v143, v136, s4, -v143
	v_fmac_f32_e32 v143, 0x3377d1cf, v136
	v_fmac_f32_e32 v143, 0x3f317217, v136
	v_cmp_lt_f32_e64 s[0:1], |v136|, s5
	s_nop 1
	v_cndmask_b32_e64 v136, v136, v143, s[0:1]
	v_cndmask_b32_e32 v143, 0, v228, vcc
	v_cmp_gt_f32_e32 vcc, s2, v133
	v_sub_f32_e32 v136, v136, v143
	v_max_f32_e32 v143, 0, v137
	v_cndmask_b32_e64 v137, 0, 32, vcc
	v_ldexp_f32 v133, v133, v137
	v_log_f32_e32 v133, v133
	s_nop 0
	v_mul_f32_e32 v137, 0x3f317217, v133
	v_fma_f32 v137, v133, s4, -v137
	v_fmac_f32_e32 v137, 0x3377d1cf, v133
	v_fmac_f32_e32 v137, 0x3f317217, v133
	v_cmp_lt_f32_e64 s[0:1], |v133|, s5
	s_nop 1
	v_cndmask_b32_e64 v133, v133, v137, s[0:1]
	v_cndmask_b32_e32 v137, 0, v228, vcc
	v_sub_f32_e32 v145, v133, v137
	v_mul_f32_e64 v137, |v146|, s3
	v_exp_f32_e32 v137, v137
	v_max_f32_e32 v133, 0, v146
	v_pk_add_f32 v[142:143], v[142:143], v[144:145]
	v_add_f32_e32 v137, 1.0, v137
	v_cmp_gt_f32_e32 vcc, s2, v137
	s_nop 1
	v_cndmask_b32_e64 v146, 0, 32, vcc
	v_ldexp_f32 v137, v137, v146
	v_log_f32_e32 v137, v137
	s_nop 0
	v_mul_f32_e32 v146, 0x3f317217, v137
	v_fma_f32 v146, v137, s4, -v146
	v_fmac_f32_e32 v146, 0x3377d1cf, v137
	v_fmac_f32_e32 v146, 0x3f317217, v137
	v_cmp_lt_f32_e64 s[0:1], |v137|, s5
	s_nop 1
	v_cndmask_b32_e64 v137, v137, v146, s[0:1]
	v_cndmask_b32_e32 v146, 0, v228, vcc
	v_sub_f32_e32 v137, v137, v146
	v_add_f32_e32 v146, v74, v138
	v_mul_f32_e64 v134, |v146|, s3
	v_exp_f32_e32 v134, v134
	v_max_f32_e32 v138, 0, v146
	v_pk_add_f32 v[132:133], v[132:133], v[136:137]
	v_lshl_add_u64 v[136:137], v[190:191], 0, v[140:141]
	v_add_f32_e32 v134, 1.0, v134
	v_cmp_gt_f32_e32 vcc, s2, v134
	s_nop 1
	v_cndmask_b32_e64 v146, 0, 32, vcc
	v_ldexp_f32 v134, v134, v146
	v_log_f32_e32 v134, v134
	s_nop 0
	v_mul_f32_e32 v146, 0x3f317217, v134
	v_fma_f32 v146, v134, s4, -v146
	v_fmac_f32_e32 v146, 0x3377d1cf, v134
	v_fmac_f32_e32 v146, 0x3f317217, v134
	v_cmp_lt_f32_e64 s[0:1], |v134|, s5
	s_nop 1
	v_cndmask_b32_e64 v134, v134, v146, s[0:1]
	v_cndmask_b32_e32 v146, 0, v228, vcc
	v_sub_f32_e32 v146, v134, v146
	v_max_f32_e32 v134, 0, v147
	v_mul_f32_e64 v147, |v147|, s3
	v_exp_f32_e32 v147, v147
	s_nop 0
	v_add_f32_e32 v147, 1.0, v147
	v_cmp_gt_f32_e32 vcc, s2, v147
	s_nop 1
	v_cndmask_b32_e64 v148, 0, 32, vcc
	v_ldexp_f32 v147, v147, v148
	v_log_f32_e32 v147, v147
	s_nop 0
	v_mul_f32_e32 v148, 0x3f317217, v147
	v_fma_f32 v148, v147, s4, -v148
	v_fmac_f32_e32 v148, 0x3377d1cf, v147
	v_fmac_f32_e32 v148, 0x3f317217, v147
	v_cmp_lt_f32_e64 s[0:1], |v147|, s5
	s_nop 1
	v_cndmask_b32_e64 v147, v147, v148, s[0:1]
	v_cndmask_b32_e32 v148, 0, v228, vcc
	v_sub_f32_e32 v148, v147, v148
	v_add_f32_e32 v147, v75, v139
	v_mul_f32_e64 v135, |v147|, s3
	v_exp_f32_e32 v135, v135
	v_max_f32_e32 v139, 0, v147
	v_add_f32_e32 v135, 1.0, v135
	v_cmp_gt_f32_e32 vcc, s2, v135
	s_nop 1
	v_cndmask_b32_e64 v147, 0, 32, vcc
	v_ldexp_f32 v135, v135, v147
	v_log_f32_e32 v135, v135
	s_nop 0
	v_mul_f32_e32 v147, 0x3f317217, v135
	v_fma_f32 v147, v135, s4, -v147
	v_fmac_f32_e32 v147, 0x3377d1cf, v135
	v_fmac_f32_e32 v147, 0x3f317217, v135
	v_cmp_lt_f32_e64 s[0:1], |v135|, s5
	s_nop 1
	v_cndmask_b32_e64 v135, v135, v147, s[0:1]
	v_cndmask_b32_e32 v147, 0, v228, vcc
	v_sub_f32_e32 v147, v135, v147
	v_pk_add_f32 v[144:145], v[138:139], v[146:147]
	v_mul_f32_e64 v138, |v149|, s3
	v_exp_f32_e32 v138, v138
	v_max_f32_e32 v135, 0, v149
	v_add_f32_e32 v138, 1.0, v138
	v_cmp_gt_f32_e32 vcc, s2, v138
	s_nop 1
	v_cndmask_b32_e64 v139, 0, 32, vcc
	v_ldexp_f32 v138, v138, v139
	v_log_f32_e32 v138, v138
	s_nop 0
	v_mul_f32_e32 v139, 0x3f317217, v138
	v_fma_f32 v139, v138, s4, -v139
	v_fmac_f32_e32 v139, 0x3377d1cf, v138
	v_fmac_f32_e32 v139, 0x3f317217, v138
	v_cmp_lt_f32_e64 s[0:1], |v138|, s5
	s_nop 1
	v_cndmask_b32_e64 v138, v138, v139, s[0:1]
	v_cndmask_b32_e32 v139, 0, v228, vcc
	v_sub_f32_e32 v149, v138, v139
	v_pk_add_f32 v[134:135], v[134:135], v[148:149]
	global_store_dwordx4 v[136:137], v[142:145], off
	global_store_dwordx4 v[136:137], v[132:135], off offset:16
	s_cbranch_execz .LBB0_449
	s_branch .LBB0_450
